# bundle25 + within every K-loop load segment all ds_reads are issued first, before the scalar pointer arithmetic and LDS-DMA loads
# baseline (speedup 1.0000x reference)
.LBB0_292:
	s_ashr_i32 s13, s12, 31
	s_lshl_b64 s[14:15], s[12:13], 20
	s_add_u32 s14, s19, s14
	s_addc_u32 s15, s22, s15
	s_and_b64 s[16:17], s[2:3], exec
	s_cselect_b32 s13, s15, s41
	s_cselect_b32 s74, s14, s40
	s_ashr_i32 s11, s10, 31
	s_lshl_b64 s[16:17], s[10:11], 20
	s_add_u32 s16, s23, s16
	s_addc_u32 s17, s28, s17
	s_and_b64 s[54:55], s[2:3], exec
	s_cselect_b32 s11, s17, s43
	s_cselect_b32 s75, s16, s42
	s_add_u32 s40, s40, 0x80080
	s_addc_u32 s41, s41, 0
	s_add_u32 s76, s42, 0x100
	s_addc_u32 s77, s43, 0
	s_mov_b32 s78, -2
	s_add_u32 s42, s40, 0xfff80080
	s_addc_u32 s43, s41, -1
	s_cmp_eq_u32 s78, 28
	s_cselect_b32 s55, s13, s43
	s_cselect_b32 s54, s74, s42
	s_cselect_b32 s43, s11, s77
	s_cselect_b32 s42, s75, s76
	s_add_i32 m0, s35, 0xc000
	s_nop 0
	global_load_lds_dwordx4 v138, s[40:41]
	s_add_i32 m0, s35, 0xe000
	s_nop 0
	global_load_lds_dwordx4 v140, s[40:41]
	s_waitcnt vmcnt(8)
	s_waitcnt lgkmcnt(0)
	s_setprio 1
	s_barrier
	v_mfma_f32_16x16x32_bf16 v[126:129], v[146:149], v[188:191], 0
	v_mfma_f32_16x16x32_bf16 v[118:121], v[160:163], v[188:191], 0
	v_mfma_f32_16x16x32_bf16 v[110:113], v[146:149], v[196:199], 0
	v_mfma_f32_16x16x32_bf16 v[102:105], v[160:163], v[196:199], 0
	v_mfma_f32_16x16x32_bf16 v[94:97], v[146:149], v[204:207], 0
	v_mfma_f32_16x16x32_bf16 v[86:89], v[160:163], v[204:207], 0
	v_mfma_f32_16x16x32_bf16 v[78:81], v[146:149], v[212:215], 0
	v_mfma_f32_16x16x32_bf16 v[70:73], v[160:163], v[212:215], 0
	v_mfma_f32_16x16x32_bf16 v[126:129], v[156:159], v[192:195], v[126:129]
	v_mfma_f32_16x16x32_bf16 v[118:121], v[164:167], v[192:195], v[118:121]
	v_mfma_f32_16x16x32_bf16 v[110:113], v[156:159], v[200:203], v[110:113]
	v_mfma_f32_16x16x32_bf16 v[102:105], v[164:167], v[200:203], v[102:105]
	v_mfma_f32_16x16x32_bf16 v[94:97], v[156:159], v[208:211], v[94:97]
	v_mfma_f32_16x16x32_bf16 v[86:89], v[164:167], v[208:211], v[86:89]
	v_mfma_f32_16x16x32_bf16 v[78:81], v[156:159], v[216:219], v[78:81]
	v_mfma_f32_16x16x32_bf16 v[70:73], v[164:167], v[216:219], v[70:73]
	s_setprio 0
	s_setprio 1
	v_mfma_f32_16x16x32_bf16 v[122:125], v[168:171], v[188:191], 0
	v_mfma_f32_16x16x32_bf16 v[114:117], v[180:183], v[188:191], 0
	v_mfma_f32_16x16x32_bf16 v[106:109], v[168:171], v[196:199], 0
	v_mfma_f32_16x16x32_bf16 v[98:101], v[180:183], v[196:199], 0
	v_mfma_f32_16x16x32_bf16 v[90:93], v[168:171], v[204:207], 0
	v_mfma_f32_16x16x32_bf16 v[82:85], v[180:183], v[204:207], 0
	v_mfma_f32_16x16x32_bf16 v[74:77], v[168:171], v[212:215], 0
	v_mfma_f32_16x16x32_bf16 v[66:69], v[180:183], v[212:215], 0
	v_mfma_f32_16x16x32_bf16 v[122:125], v[172:175], v[192:195], v[122:125]
	v_mfma_f32_16x16x32_bf16 v[114:117], v[184:187], v[192:195], v[114:117]
	v_mfma_f32_16x16x32_bf16 v[106:109], v[172:175], v[200:203], v[106:109]
	v_mfma_f32_16x16x32_bf16 v[98:101], v[184:187], v[200:203], v[98:101]
	v_mfma_f32_16x16x32_bf16 v[90:93], v[172:175], v[208:211], v[90:93]
	v_mfma_f32_16x16x32_bf16 v[82:85], v[184:187], v[208:211], v[82:85]
	v_mfma_f32_16x16x32_bf16 v[74:77], v[172:175], v[216:219], v[74:77]
	v_mfma_f32_16x16x32_bf16 v[66:69], v[184:187], v[216:219], v[66:69]
	s_barrier
	s_setprio 0
	ds_read_b128 v[188:191], v155 offset:16384
	ds_read_b128 v[192:195], v155 offset:17408
	ds_read_b128 v[196:199], v155 offset:18432
	ds_read_b128 v[200:203], v155 offset:19456
	ds_read_b128 v[204:207], v155 offset:20480
	ds_read_b128 v[208:211], v155 offset:21504
	ds_read_b128 v[212:215], v155 offset:22528
	ds_read_b128 v[216:219], v155 offset:23552
	s_add_i32 s79, s70, s29
	s_add_u32 s98, s42, 0x80
	s_addc_u32 s99, s43, 0
	s_mov_b32 m0, s79
	s_nop 0
	global_load_lds_dwordx4 v134, s[42:43]
	s_add_i32 m0, s79, 0x2000
	s_add_u32 s80, s42, 0x80000
	s_addc_u32 s81, s43, 0
	s_add_i32 s79, s71, s29
	global_load_lds_dwordx4 v130, s[42:43]
	s_mov_b32 m0, s79
	s_nop 0
	global_load_lds_dwordx4 v134, s[80:81]
	s_add_i32 m0, s79, 0x2000
	s_nop 0
	global_load_lds_dwordx4 v130, s[80:81]
	s_add_u32 s100, s54, 0x80
	s_addc_u32 s101, s55, 0
	s_mov_b32 m0, s35
	s_nop 0
	global_load_lds_dwordx4 v136, s[54:55]
	s_mov_b32 m0, s57
	s_nop 0
	global_load_lds_dwordx4 v132, s[54:55]
	s_waitcnt vmcnt(8)
	s_waitcnt lgkmcnt(0)
	s_setprio 1
	s_barrier
	v_mfma_f32_16x16x32_bf16 v[62:65], v[146:149], v[188:191], 0
	v_mfma_f32_16x16x32_bf16 v[54:57], v[160:163], v[188:191], 0
	v_mfma_f32_16x16x32_bf16 v[46:49], v[146:149], v[196:199], 0
	v_mfma_f32_16x16x32_bf16 v[38:41], v[160:163], v[196:199], 0
	v_mfma_f32_16x16x32_bf16 v[30:33], v[146:149], v[204:207], 0
	v_mfma_f32_16x16x32_bf16 v[22:25], v[160:163], v[204:207], 0
	v_mfma_f32_16x16x32_bf16 v[14:17], v[146:149], v[212:215], 0
	v_mfma_f32_16x16x32_bf16 v[6:9], v[160:163], v[212:215], 0
	v_mfma_f32_16x16x32_bf16 v[62:65], v[156:159], v[192:195], v[62:65]
	v_mfma_f32_16x16x32_bf16 v[54:57], v[164:167], v[192:195], v[54:57]
	v_mfma_f32_16x16x32_bf16 v[46:49], v[156:159], v[200:203], v[46:49]
	v_mfma_f32_16x16x32_bf16 v[38:41], v[164:167], v[200:203], v[38:41]
	v_mfma_f32_16x16x32_bf16 v[30:33], v[156:159], v[208:211], v[30:33]
	v_mfma_f32_16x16x32_bf16 v[22:25], v[164:167], v[208:211], v[22:25]
	v_mfma_f32_16x16x32_bf16 v[14:17], v[156:159], v[216:219], v[14:17]
	v_mfma_f32_16x16x32_bf16 v[6:9], v[164:167], v[216:219], v[6:9]
	s_setprio 0
	s_setprio 1
	v_mfma_f32_16x16x32_bf16 v[58:61], v[168:171], v[188:191], 0
	v_mfma_f32_16x16x32_bf16 v[50:53], v[180:183], v[188:191], 0
	v_mfma_f32_16x16x32_bf16 v[42:45], v[168:171], v[196:199], 0
	v_mfma_f32_16x16x32_bf16 v[34:37], v[180:183], v[196:199], 0
	v_mfma_f32_16x16x32_bf16 v[26:29], v[168:171], v[204:207], 0
	v_mfma_f32_16x16x32_bf16 v[18:21], v[180:183], v[204:207], 0
	v_mfma_f32_16x16x32_bf16 v[10:13], v[168:171], v[212:215], 0
	v_mfma_f32_16x16x32_bf16 v[2:5], v[180:183], v[212:215], 0
	v_mfma_f32_16x16x32_bf16 v[58:61], v[172:175], v[192:195], v[58:61]
	v_mfma_f32_16x16x32_bf16 v[50:53], v[184:187], v[192:195], v[50:53]
	v_mfma_f32_16x16x32_bf16 v[42:45], v[172:175], v[200:203], v[42:45]
	v_mfma_f32_16x16x32_bf16 v[34:37], v[184:187], v[200:203], v[34:37]
	v_mfma_f32_16x16x32_bf16 v[26:29], v[172:175], v[208:211], v[26:29]
	v_mfma_f32_16x16x32_bf16 v[18:21], v[184:187], v[208:211], v[18:21]
	v_mfma_f32_16x16x32_bf16 v[10:13], v[172:175], v[216:219], v[10:13]
	v_mfma_f32_16x16x32_bf16 v[2:5], v[184:187], v[216:219], v[2:5]
	s_barrier
	s_setprio 0
	ds_read_b128 v[146:149], v153 offset:32768
	ds_read_b128 v[156:159], v153 offset:33792
	ds_read_b128 v[160:163], v153 offset:34816
	ds_read_b128 v[164:167], v153 offset:35840
	ds_read_b128 v[168:171], v154 offset:32768
	ds_read_b128 v[172:175], v154 offset:33792
	ds_read_b128 v[180:183], v154 offset:34816
	ds_read_b128 v[184:187], v154 offset:35840
	ds_read_b128 v[188:191], v155 offset:32768
	ds_read_b128 v[192:195], v155 offset:33792
	ds_read_b128 v[196:199], v155 offset:34816
	ds_read_b128 v[200:203], v155 offset:35840
	ds_read_b128 v[204:207], v155 offset:36864
	ds_read_b128 v[208:211], v155 offset:37888
	ds_read_b128 v[212:215], v155 offset:38912
	ds_read_b128 v[216:219], v155 offset:39936
	s_add_i32 s79, 0, 0x18000
	s_add_i32 s80, 0, 0x1c000
	s_add_u32 s54, s54, 0x80000
	s_addc_u32 s55, s55, 0
	s_mov_b32 m0, s58
	s_nop 0
	global_load_lds_dwordx4 v136, s[54:55]
	s_mov_b32 m0, s59
	s_nop 0
	global_load_lds_dwordx4 v132, s[54:55]
	s_waitcnt vmcnt(8)
	s_waitcnt lgkmcnt(0)
	s_setprio 1
	s_barrier
	v_mfma_f32_16x16x32_bf16 v[126:129], v[146:149], v[188:191], v[126:129]
	v_mfma_f32_16x16x32_bf16 v[118:121], v[160:163], v[188:191], v[118:121]
	v_mfma_f32_16x16x32_bf16 v[110:113], v[146:149], v[196:199], v[110:113]
	v_mfma_f32_16x16x32_bf16 v[102:105], v[160:163], v[196:199], v[102:105]
	v_mfma_f32_16x16x32_bf16 v[94:97], v[146:149], v[204:207], v[94:97]
	v_mfma_f32_16x16x32_bf16 v[86:89], v[160:163], v[204:207], v[86:89]
	v_mfma_f32_16x16x32_bf16 v[78:81], v[146:149], v[212:215], v[78:81]
	v_mfma_f32_16x16x32_bf16 v[70:73], v[160:163], v[212:215], v[70:73]
	v_mfma_f32_16x16x32_bf16 v[126:129], v[156:159], v[192:195], v[126:129]
	v_mfma_f32_16x16x32_bf16 v[118:121], v[164:167], v[192:195], v[118:121]
	v_mfma_f32_16x16x32_bf16 v[110:113], v[156:159], v[200:203], v[110:113]
	v_mfma_f32_16x16x32_bf16 v[102:105], v[164:167], v[200:203], v[102:105]
	v_mfma_f32_16x16x32_bf16 v[94:97], v[156:159], v[208:211], v[94:97]
	v_mfma_f32_16x16x32_bf16 v[86:89], v[164:167], v[208:211], v[86:89]
	v_mfma_f32_16x16x32_bf16 v[78:81], v[156:159], v[216:219], v[78:81]
	v_mfma_f32_16x16x32_bf16 v[70:73], v[164:167], v[216:219], v[70:73]
	s_setprio 0
	s_setprio 1
	v_mfma_f32_16x16x32_bf16 v[122:125], v[168:171], v[188:191], v[122:125]
	v_mfma_f32_16x16x32_bf16 v[114:117], v[180:183], v[188:191], v[114:117]
	v_mfma_f32_16x16x32_bf16 v[106:109], v[168:171], v[196:199], v[106:109]
	v_mfma_f32_16x16x32_bf16 v[98:101], v[180:183], v[196:199], v[98:101]
	v_mfma_f32_16x16x32_bf16 v[90:93], v[168:171], v[204:207], v[90:93]
	v_mfma_f32_16x16x32_bf16 v[82:85], v[180:183], v[204:207], v[82:85]
	v_mfma_f32_16x16x32_bf16 v[74:77], v[168:171], v[212:215], v[74:77]
	v_mfma_f32_16x16x32_bf16 v[66:69], v[180:183], v[212:215], v[66:69]
	v_mfma_f32_16x16x32_bf16 v[122:125], v[172:175], v[192:195], v[122:125]
	v_mfma_f32_16x16x32_bf16 v[114:117], v[184:187], v[192:195], v[114:117]
	v_mfma_f32_16x16x32_bf16 v[106:109], v[172:175], v[200:203], v[106:109]
	v_mfma_f32_16x16x32_bf16 v[98:101], v[184:187], v[200:203], v[98:101]
	v_mfma_f32_16x16x32_bf16 v[90:93], v[172:175], v[208:211], v[90:93]
	v_mfma_f32_16x16x32_bf16 v[82:85], v[184:187], v[208:211], v[82:85]
	v_mfma_f32_16x16x32_bf16 v[74:77], v[172:175], v[216:219], v[74:77]
	v_mfma_f32_16x16x32_bf16 v[66:69], v[184:187], v[216:219], v[66:69]
	s_barrier
	s_setprio 0
	ds_read_b128 v[188:191], v155 offset:49152
	ds_read_b128 v[192:195], v155 offset:50176
	ds_read_b128 v[196:199], v155 offset:51200
	ds_read_b128 v[200:203], v155 offset:52224
	ds_read_b128 v[204:207], v155 offset:53248
	ds_read_b128 v[208:211], v155 offset:54272
	ds_read_b128 v[212:215], v155 offset:55296
	ds_read_b128 v[216:219], v155 offset:56320
	s_add_i32 s54, s79, s29
	s_mov_b32 m0, s54
	s_nop 0
	global_load_lds_dwordx4 v134, s[98:99]
	s_add_i32 m0, s54, 0x2000
	s_add_u32 s42, s42, 0x80080
	s_addc_u32 s43, s43, 0
	s_add_i32 s54, s80, s29
	global_load_lds_dwordx4 v130, s[98:99]
	s_mov_b32 m0, s54
	s_nop 0
	global_load_lds_dwordx4 v134, s[42:43]
	s_add_i32 m0, s54, 0x2000
	s_nop 0
	global_load_lds_dwordx4 v130, s[42:43]
	s_mov_b32 m0, s64
	s_nop 0
	global_load_lds_dwordx4 v136, s[100:101]
	s_mov_b32 m0, s65
	s_nop 0
	global_load_lds_dwordx4 v132, s[100:101]
	s_waitcnt vmcnt(8)
	s_waitcnt lgkmcnt(0)
	s_setprio 1
	s_barrier
	v_mfma_f32_16x16x32_bf16 v[62:65], v[146:149], v[188:191], v[62:65]
	v_mfma_f32_16x16x32_bf16 v[54:57], v[160:163], v[188:191], v[54:57]
	v_mfma_f32_16x16x32_bf16 v[46:49], v[146:149], v[196:199], v[46:49]
	v_mfma_f32_16x16x32_bf16 v[38:41], v[160:163], v[196:199], v[38:41]
	v_mfma_f32_16x16x32_bf16 v[30:33], v[146:149], v[204:207], v[30:33]
	v_mfma_f32_16x16x32_bf16 v[22:25], v[160:163], v[204:207], v[22:25]
	v_mfma_f32_16x16x32_bf16 v[14:17], v[146:149], v[212:215], v[14:17]
	v_mfma_f32_16x16x32_bf16 v[6:9], v[160:163], v[212:215], v[6:9]
	v_mfma_f32_16x16x32_bf16 v[62:65], v[156:159], v[192:195], v[62:65]
	v_mfma_f32_16x16x32_bf16 v[54:57], v[164:167], v[192:195], v[54:57]
	v_mfma_f32_16x16x32_bf16 v[46:49], v[156:159], v[200:203], v[46:49]
	v_mfma_f32_16x16x32_bf16 v[38:41], v[164:167], v[200:203], v[38:41]
	v_mfma_f32_16x16x32_bf16 v[30:33], v[156:159], v[208:211], v[30:33]
	v_mfma_f32_16x16x32_bf16 v[22:25], v[164:167], v[208:211], v[22:25]
	v_mfma_f32_16x16x32_bf16 v[14:17], v[156:159], v[216:219], v[14:17]
	v_mfma_f32_16x16x32_bf16 v[6:9], v[164:167], v[216:219], v[6:9]
	s_setprio 0
	s_setprio 1
	v_mfma_f32_16x16x32_bf16 v[58:61], v[168:171], v[188:191], v[58:61]
	v_mfma_f32_16x16x32_bf16 v[50:53], v[180:183], v[188:191], v[50:53]
	v_mfma_f32_16x16x32_bf16 v[42:45], v[168:171], v[196:199], v[42:45]
	v_mfma_f32_16x16x32_bf16 v[34:37], v[180:183], v[196:199], v[34:37]
	v_mfma_f32_16x16x32_bf16 v[26:29], v[168:171], v[204:207], v[26:29]
	v_mfma_f32_16x16x32_bf16 v[18:21], v[180:183], v[204:207], v[18:21]
	v_mfma_f32_16x16x32_bf16 v[10:13], v[168:171], v[212:215], v[10:13]
	v_mfma_f32_16x16x32_bf16 v[2:5], v[180:183], v[212:215], v[2:5]
	v_mfma_f32_16x16x32_bf16 v[58:61], v[172:175], v[192:195], v[58:61]
	v_mfma_f32_16x16x32_bf16 v[50:53], v[184:187], v[192:195], v[50:53]
	v_mfma_f32_16x16x32_bf16 v[42:45], v[172:175], v[200:203], v[42:45]
	v_mfma_f32_16x16x32_bf16 v[34:37], v[184:187], v[200:203], v[34:37]
	v_mfma_f32_16x16x32_bf16 v[26:29], v[172:175], v[208:211], v[26:29]
	v_mfma_f32_16x16x32_bf16 v[18:21], v[184:187], v[208:211], v[18:21]
	v_mfma_f32_16x16x32_bf16 v[10:13], v[172:175], v[216:219], v[10:13]
	v_mfma_f32_16x16x32_bf16 v[2:5], v[184:187], v[216:219], v[2:5]
	s_barrier
	s_setprio 0
	s_add_i32 s78, s78, 2
	s_add_u32 s40, s40, 0x100
	s_addc_u32 s41, s41, 0
	s_add_u32 s76, s76, 0x100
	s_addc_u32 s77, s77, 0
	s_cmp_gt_u32 s78, 29
.LBB0_293:
	ds_read_b128 v[146:149], v153
	ds_read_b128 v[156:159], v153 offset:1024
	ds_read_b128 v[160:163], v153 offset:2048
	ds_read_b128 v[164:167], v153 offset:3072
	ds_read_b128 v[168:171], v154
	ds_read_b128 v[172:175], v154 offset:1024
	ds_read_b128 v[180:183], v154 offset:2048
	ds_read_b128 v[184:187], v154 offset:3072
	ds_read_b128 v[188:191], v155
	ds_read_b128 v[192:195], v155 offset:1024
	ds_read_b128 v[196:199], v155 offset:2048
	ds_read_b128 v[200:203], v155 offset:3072
	ds_read_b128 v[204:207], v155 offset:4096
	ds_read_b128 v[208:211], v155 offset:5120
	ds_read_b128 v[212:215], v155 offset:6144
	ds_read_b128 v[216:219], v155 offset:7168
	s_add_u32 s42, s40, 0xfff80080
	s_addc_u32 s43, s41, -1
	s_cmp_eq_u32 s78, 28
	s_cselect_b32 s55, s13, s43
	s_cselect_b32 s54, s74, s42
	s_cselect_b32 s43, s11, s77
	s_cselect_b32 s42, s75, s76
	s_add_i32 m0, s35, 0xc000
	s_nop 0
	global_load_lds_dwordx4 v138, s[40:41]
	s_add_i32 m0, s35, 0xe000
	s_nop 0
	global_load_lds_dwordx4 v140, s[40:41]
	s_waitcnt vmcnt(8)
	s_waitcnt lgkmcnt(0)
	s_setprio 1
	s_barrier
	v_mfma_f32_16x16x32_bf16 v[126:129], v[146:149], v[188:191], v[126:129]
	v_mfma_f32_16x16x32_bf16 v[118:121], v[160:163], v[188:191], v[118:121]
	v_mfma_f32_16x16x32_bf16 v[110:113], v[146:149], v[196:199], v[110:113]
	v_mfma_f32_16x16x32_bf16 v[102:105], v[160:163], v[196:199], v[102:105]
	v_mfma_f32_16x16x32_bf16 v[94:97], v[146:149], v[204:207], v[94:97]
	v_mfma_f32_16x16x32_bf16 v[86:89], v[160:163], v[204:207], v[86:89]
	v_mfma_f32_16x16x32_bf16 v[78:81], v[146:149], v[212:215], v[78:81]
	v_mfma_f32_16x16x32_bf16 v[70:73], v[160:163], v[212:215], v[70:73]
	v_mfma_f32_16x16x32_bf16 v[126:129], v[156:159], v[192:195], v[126:129]
	v_mfma_f32_16x16x32_bf16 v[118:121], v[164:167], v[192:195], v[118:121]
	v_mfma_f32_16x16x32_bf16 v[110:113], v[156:159], v[200:203], v[110:113]
	v_mfma_f32_16x16x32_bf16 v[102:105], v[164:167], v[200:203], v[102:105]
	v_mfma_f32_16x16x32_bf16 v[94:97], v[156:159], v[208:211], v[94:97]
	v_mfma_f32_16x16x32_bf16 v[86:89], v[164:167], v[208:211], v[86:89]
	v_mfma_f32_16x16x32_bf16 v[78:81], v[156:159], v[216:219], v[78:81]
	v_mfma_f32_16x16x32_bf16 v[70:73], v[164:167], v[216:219], v[70:73]
	s_setprio 0
	s_setprio 1
	v_mfma_f32_16x16x32_bf16 v[122:125], v[168:171], v[188:191], v[122:125]
	v_mfma_f32_16x16x32_bf16 v[114:117], v[180:183], v[188:191], v[114:117]
	v_mfma_f32_16x16x32_bf16 v[106:109], v[168:171], v[196:199], v[106:109]
	v_mfma_f32_16x16x32_bf16 v[98:101], v[180:183], v[196:199], v[98:101]
	v_mfma_f32_16x16x32_bf16 v[90:93], v[168:171], v[204:207], v[90:93]
	v_mfma_f32_16x16x32_bf16 v[82:85], v[180:183], v[204:207], v[82:85]
	v_mfma_f32_16x16x32_bf16 v[74:77], v[168:171], v[212:215], v[74:77]
	v_mfma_f32_16x16x32_bf16 v[66:69], v[180:183], v[212:215], v[66:69]
	v_mfma_f32_16x16x32_bf16 v[122:125], v[172:175], v[192:195], v[122:125]
	v_mfma_f32_16x16x32_bf16 v[114:117], v[184:187], v[192:195], v[114:117]
	v_mfma_f32_16x16x32_bf16 v[106:109], v[172:175], v[200:203], v[106:109]
	v_mfma_f32_16x16x32_bf16 v[98:101], v[184:187], v[200:203], v[98:101]
	v_mfma_f32_16x16x32_bf16 v[90:93], v[172:175], v[208:211], v[90:93]
	v_mfma_f32_16x16x32_bf16 v[82:85], v[184:187], v[208:211], v[82:85]
	v_mfma_f32_16x16x32_bf16 v[74:77], v[172:175], v[216:219], v[74:77]
	v_mfma_f32_16x16x32_bf16 v[66:69], v[184:187], v[216:219], v[66:69]
	s_barrier
	s_setprio 0
	ds_read_b128 v[188:191], v155 offset:16384
	ds_read_b128 v[192:195], v155 offset:17408
	ds_read_b128 v[196:199], v155 offset:18432
	ds_read_b128 v[200:203], v155 offset:19456
	ds_read_b128 v[204:207], v155 offset:20480
	ds_read_b128 v[208:211], v155 offset:21504
	ds_read_b128 v[212:215], v155 offset:22528
	ds_read_b128 v[216:219], v155 offset:23552
	s_add_i32 s79, s70, s29
	s_add_u32 s98, s42, 0x80
	s_addc_u32 s99, s43, 0
	s_mov_b32 m0, s79
	s_nop 0
	global_load_lds_dwordx4 v134, s[42:43]
	s_add_i32 m0, s79, 0x2000
	s_add_u32 s80, s42, 0x80000
	s_addc_u32 s81, s43, 0
	s_add_i32 s79, s71, s29
	global_load_lds_dwordx4 v130, s[42:43]
	s_mov_b32 m0, s79
	s_nop 0
	global_load_lds_dwordx4 v134, s[80:81]
	s_add_i32 m0, s79, 0x2000
	s_nop 0
	global_load_lds_dwordx4 v130, s[80:81]
	s_add_u32 s100, s54, 0x80
	s_addc_u32 s101, s55, 0
	s_mov_b32 m0, s35
	s_nop 0
	global_load_lds_dwordx4 v136, s[54:55]
	s_mov_b32 m0, s57
	s_nop 0
	global_load_lds_dwordx4 v132, s[54:55]
	s_waitcnt vmcnt(8)
	s_waitcnt lgkmcnt(0)
	s_setprio 1
	s_barrier
	v_mfma_f32_16x16x32_bf16 v[62:65], v[146:149], v[188:191], v[62:65]
	v_mfma_f32_16x16x32_bf16 v[54:57], v[160:163], v[188:191], v[54:57]
	v_mfma_f32_16x16x32_bf16 v[46:49], v[146:149], v[196:199], v[46:49]
	v_mfma_f32_16x16x32_bf16 v[38:41], v[160:163], v[196:199], v[38:41]
	v_mfma_f32_16x16x32_bf16 v[30:33], v[146:149], v[204:207], v[30:33]
	v_mfma_f32_16x16x32_bf16 v[22:25], v[160:163], v[204:207], v[22:25]
	v_mfma_f32_16x16x32_bf16 v[14:17], v[146:149], v[212:215], v[14:17]
	v_mfma_f32_16x16x32_bf16 v[6:9], v[160:163], v[212:215], v[6:9]
	v_mfma_f32_16x16x32_bf16 v[62:65], v[156:159], v[192:195], v[62:65]
	v_mfma_f32_16x16x32_bf16 v[54:57], v[164:167], v[192:195], v[54:57]
	v_mfma_f32_16x16x32_bf16 v[46:49], v[156:159], v[200:203], v[46:49]
	v_mfma_f32_16x16x32_bf16 v[38:41], v[164:167], v[200:203], v[38:41]
	v_mfma_f32_16x16x32_bf16 v[30:33], v[156:159], v[208:211], v[30:33]
	v_mfma_f32_16x16x32_bf16 v[22:25], v[164:167], v[208:211], v[22:25]
	v_mfma_f32_16x16x32_bf16 v[14:17], v[156:159], v[216:219], v[14:17]
	v_mfma_f32_16x16x32_bf16 v[6:9], v[164:167], v[216:219], v[6:9]
	s_setprio 0
	s_setprio 1
	v_mfma_f32_16x16x32_bf16 v[58:61], v[168:171], v[188:191], v[58:61]
	v_mfma_f32_16x16x32_bf16 v[50:53], v[180:183], v[188:191], v[50:53]
	v_mfma_f32_16x16x32_bf16 v[42:45], v[168:171], v[196:199], v[42:45]
	v_mfma_f32_16x16x32_bf16 v[34:37], v[180:183], v[196:199], v[34:37]
	v_mfma_f32_16x16x32_bf16 v[26:29], v[168:171], v[204:207], v[26:29]
	v_mfma_f32_16x16x32_bf16 v[18:21], v[180:183], v[204:207], v[18:21]
	v_mfma_f32_16x16x32_bf16 v[10:13], v[168:171], v[212:215], v[10:13]
	v_mfma_f32_16x16x32_bf16 v[2:5], v[180:183], v[212:215], v[2:5]
	v_mfma_f32_16x16x32_bf16 v[58:61], v[172:175], v[192:195], v[58:61]
	v_mfma_f32_16x16x32_bf16 v[50:53], v[184:187], v[192:195], v[50:53]
	v_mfma_f32_16x16x32_bf16 v[42:45], v[172:175], v[200:203], v[42:45]
	v_mfma_f32_16x16x32_bf16 v[34:37], v[184:187], v[200:203], v[34:37]
	v_mfma_f32_16x16x32_bf16 v[26:29], v[172:175], v[208:211], v[26:29]
	v_mfma_f32_16x16x32_bf16 v[18:21], v[184:187], v[208:211], v[18:21]
	v_mfma_f32_16x16x32_bf16 v[10:13], v[172:175], v[216:219], v[10:13]
	v_mfma_f32_16x16x32_bf16 v[2:5], v[184:187], v[216:219], v[2:5]
	s_barrier
	s_setprio 0
	ds_read_b128 v[146:149], v153 offset:32768
	ds_read_b128 v[156:159], v153 offset:33792
	ds_read_b128 v[160:163], v153 offset:34816
	ds_read_b128 v[164:167], v153 offset:35840
	ds_read_b128 v[168:171], v154 offset:32768
	ds_read_b128 v[172:175], v154 offset:33792
	ds_read_b128 v[180:183], v154 offset:34816
	ds_read_b128 v[184:187], v154 offset:35840
	ds_read_b128 v[188:191], v155 offset:32768
	ds_read_b128 v[192:195], v155 offset:33792
	ds_read_b128 v[196:199], v155 offset:34816
	ds_read_b128 v[200:203], v155 offset:35840
	ds_read_b128 v[204:207], v155 offset:36864
	ds_read_b128 v[208:211], v155 offset:37888
	ds_read_b128 v[212:215], v155 offset:38912
	ds_read_b128 v[216:219], v155 offset:39936
	s_add_i32 s79, 0, 0x18000
	s_add_i32 s80, 0, 0x1c000
	s_add_u32 s54, s54, 0x80000
	s_addc_u32 s55, s55, 0
	s_mov_b32 m0, s58
	s_nop 0
	global_load_lds_dwordx4 v136, s[54:55]
	s_mov_b32 m0, s59
	s_nop 0
	global_load_lds_dwordx4 v132, s[54:55]
	s_waitcnt vmcnt(8)
	s_waitcnt lgkmcnt(0)
	s_setprio 1
	s_barrier
	v_mfma_f32_16x16x32_bf16 v[126:129], v[146:149], v[188:191], v[126:129]
	v_mfma_f32_16x16x32_bf16 v[118:121], v[160:163], v[188:191], v[118:121]
	v_mfma_f32_16x16x32_bf16 v[110:113], v[146:149], v[196:199], v[110:113]
	v_mfma_f32_16x16x32_bf16 v[102:105], v[160:163], v[196:199], v[102:105]
	v_mfma_f32_16x16x32_bf16 v[94:97], v[146:149], v[204:207], v[94:97]
	v_mfma_f32_16x16x32_bf16 v[86:89], v[160:163], v[204:207], v[86:89]
	v_mfma_f32_16x16x32_bf16 v[78:81], v[146:149], v[212:215], v[78:81]
	v_mfma_f32_16x16x32_bf16 v[70:73], v[160:163], v[212:215], v[70:73]
	v_mfma_f32_16x16x32_bf16 v[126:129], v[156:159], v[192:195], v[126:129]
	v_mfma_f32_16x16x32_bf16 v[118:121], v[164:167], v[192:195], v[118:121]
	v_mfma_f32_16x16x32_bf16 v[110:113], v[156:159], v[200:203], v[110:113]
	v_mfma_f32_16x16x32_bf16 v[102:105], v[164:167], v[200:203], v[102:105]
	v_mfma_f32_16x16x32_bf16 v[94:97], v[156:159], v[208:211], v[94:97]
	v_mfma_f32_16x16x32_bf16 v[86:89], v[164:167], v[208:211], v[86:89]
	v_mfma_f32_16x16x32_bf16 v[78:81], v[156:159], v[216:219], v[78:81]
	v_mfma_f32_16x16x32_bf16 v[70:73], v[164:167], v[216:219], v[70:73]
	s_setprio 0
	s_setprio 1
	v_mfma_f32_16x16x32_bf16 v[122:125], v[168:171], v[188:191], v[122:125]
	v_mfma_f32_16x16x32_bf16 v[114:117], v[180:183], v[188:191], v[114:117]
	v_mfma_f32_16x16x32_bf16 v[106:109], v[168:171], v[196:199], v[106:109]
	v_mfma_f32_16x16x32_bf16 v[98:101], v[180:183], v[196:199], v[98:101]
	v_mfma_f32_16x16x32_bf16 v[90:93], v[168:171], v[204:207], v[90:93]
	v_mfma_f32_16x16x32_bf16 v[82:85], v[180:183], v[204:207], v[82:85]
	v_mfma_f32_16x16x32_bf16 v[74:77], v[168:171], v[212:215], v[74:77]
	v_mfma_f32_16x16x32_bf16 v[66:69], v[180:183], v[212:215], v[66:69]
	v_mfma_f32_16x16x32_bf16 v[122:125], v[172:175], v[192:195], v[122:125]
	v_mfma_f32_16x16x32_bf16 v[114:117], v[184:187], v[192:195], v[114:117]
	v_mfma_f32_16x16x32_bf16 v[106:109], v[172:175], v[200:203], v[106:109]
	v_mfma_f32_16x16x32_bf16 v[98:101], v[184:187], v[200:203], v[98:101]
	v_mfma_f32_16x16x32_bf16 v[90:93], v[172:175], v[208:211], v[90:93]
	v_mfma_f32_16x16x32_bf16 v[82:85], v[184:187], v[208:211], v[82:85]
	v_mfma_f32_16x16x32_bf16 v[74:77], v[172:175], v[216:219], v[74:77]
	v_mfma_f32_16x16x32_bf16 v[66:69], v[184:187], v[216:219], v[66:69]
	s_barrier
	s_setprio 0
	ds_read_b128 v[188:191], v155 offset:49152
	ds_read_b128 v[192:195], v155 offset:50176
	ds_read_b128 v[196:199], v155 offset:51200
	ds_read_b128 v[200:203], v155 offset:52224
	ds_read_b128 v[204:207], v155 offset:53248
	ds_read_b128 v[208:211], v155 offset:54272
	ds_read_b128 v[212:215], v155 offset:55296
	ds_read_b128 v[216:219], v155 offset:56320
	s_add_i32 s54, s79, s29
	s_mov_b32 m0, s54
	s_nop 0
	global_load_lds_dwordx4 v134, s[98:99]
	s_add_i32 m0, s54, 0x2000
	s_add_u32 s42, s42, 0x80080
	s_addc_u32 s43, s43, 0
	s_add_i32 s54, s80, s29
	global_load_lds_dwordx4 v130, s[98:99]
	s_mov_b32 m0, s54
	s_nop 0
	global_load_lds_dwordx4 v134, s[42:43]
	s_add_i32 m0, s54, 0x2000
	s_nop 0
	global_load_lds_dwordx4 v130, s[42:43]
	s_mov_b32 m0, s64
	s_nop 0
	global_load_lds_dwordx4 v136, s[100:101]
	s_mov_b32 m0, s65
	s_nop 0
	global_load_lds_dwordx4 v132, s[100:101]
	s_add_i32 s78, s78, 2
	s_add_u32 s40, s40, 0x100
	s_addc_u32 s41, s41, 0
	s_add_u32 s76, s76, 0x100
	s_addc_u32 s77, s77, 0
	s_cmp_gt_u32 s78, 29
	s_waitcnt vmcnt(8)
	s_waitcnt lgkmcnt(0)
	s_setprio 1
	s_barrier
	v_mfma_f32_16x16x32_bf16 v[62:65], v[146:149], v[188:191], v[62:65]
	v_mfma_f32_16x16x32_bf16 v[54:57], v[160:163], v[188:191], v[54:57]
	v_mfma_f32_16x16x32_bf16 v[46:49], v[146:149], v[196:199], v[46:49]
	v_mfma_f32_16x16x32_bf16 v[38:41], v[160:163], v[196:199], v[38:41]
	v_mfma_f32_16x16x32_bf16 v[30:33], v[146:149], v[204:207], v[30:33]
	v_mfma_f32_16x16x32_bf16 v[22:25], v[160:163], v[204:207], v[22:25]
	v_mfma_f32_16x16x32_bf16 v[14:17], v[146:149], v[212:215], v[14:17]
	v_mfma_f32_16x16x32_bf16 v[6:9], v[160:163], v[212:215], v[6:9]
	v_mfma_f32_16x16x32_bf16 v[62:65], v[156:159], v[192:195], v[62:65]
	v_mfma_f32_16x16x32_bf16 v[54:57], v[164:167], v[192:195], v[54:57]
	v_mfma_f32_16x16x32_bf16 v[46:49], v[156:159], v[200:203], v[46:49]
	v_mfma_f32_16x16x32_bf16 v[38:41], v[164:167], v[200:203], v[38:41]
	v_mfma_f32_16x16x32_bf16 v[30:33], v[156:159], v[208:211], v[30:33]
	v_mfma_f32_16x16x32_bf16 v[22:25], v[164:167], v[208:211], v[22:25]
	v_mfma_f32_16x16x32_bf16 v[14:17], v[156:159], v[216:219], v[14:17]
	v_mfma_f32_16x16x32_bf16 v[6:9], v[164:167], v[216:219], v[6:9]
	s_setprio 0
	s_setprio 1
	v_mfma_f32_16x16x32_bf16 v[58:61], v[168:171], v[188:191], v[58:61]
	v_mfma_f32_16x16x32_bf16 v[50:53], v[180:183], v[188:191], v[50:53]
	v_mfma_f32_16x16x32_bf16 v[42:45], v[168:171], v[196:199], v[42:45]
	v_mfma_f32_16x16x32_bf16 v[34:37], v[180:183], v[196:199], v[34:37]
	v_mfma_f32_16x16x32_bf16 v[26:29], v[168:171], v[204:207], v[26:29]
	v_mfma_f32_16x16x32_bf16 v[18:21], v[180:183], v[204:207], v[18:21]
	v_mfma_f32_16x16x32_bf16 v[10:13], v[168:171], v[212:215], v[10:13]
	v_mfma_f32_16x16x32_bf16 v[2:5], v[180:183], v[212:215], v[2:5]
	v_mfma_f32_16x16x32_bf16 v[58:61], v[172:175], v[192:195], v[58:61]
	v_mfma_f32_16x16x32_bf16 v[50:53], v[184:187], v[192:195], v[50:53]
	v_mfma_f32_16x16x32_bf16 v[42:45], v[172:175], v[200:203], v[42:45]
	v_mfma_f32_16x16x32_bf16 v[34:37], v[184:187], v[200:203], v[34:37]
	v_mfma_f32_16x16x32_bf16 v[26:29], v[172:175], v[208:211], v[26:29]
	v_mfma_f32_16x16x32_bf16 v[18:21], v[184:187], v[208:211], v[18:21]
	v_mfma_f32_16x16x32_bf16 v[10:13], v[172:175], v[216:219], v[10:13]
	v_mfma_f32_16x16x32_bf16 v[2:5], v[184:187], v[216:219], v[2:5]
	s_barrier
	s_setprio 0
	s_cbranch_scc0 .LBB0_293
	s_and_b64 vcc, exec, s[8:9]
	s_cbranch_vccz .LBB0_296
	s_barrier

.LBB0_378:
	s_add_u32 s12, s58, 0x160080
	s_addc_u32 s13, s59, 0
	s_add_u32 s81, s56, 0x100
	s_addc_u32 s82, s57, 0
	s_mov_b32 s83, -2
	s_add_u32 s56, s12, 0xffea0080
	s_addc_u32 s57, s13, -1
	s_cmpk_eq_i32 s83, 0x54
	s_cselect_b32 s59, s43, s57
	s_cselect_b32 s58, s42, s56
	s_cselect_b32 s57, s55, s82
	s_cselect_b32 s56, s54, s81
	s_add_i32 m0, s31, 0xc000
	s_nop 0
	global_load_lds_dwordx4 v188, s[12:13]
	s_add_i32 m0, s31, 0xe000
	s_nop 0
	global_load_lds_dwordx4 v190, s[12:13]
	s_waitcnt vmcnt(8)
	s_waitcnt lgkmcnt(0)
	s_setprio 1
	s_barrier
	v_mfma_f32_16x16x32_bf16 v[126:129], v[130:133], v[162:165], 0
	v_mfma_f32_16x16x32_bf16 v[122:125], v[138:141], v[162:165], 0
	v_mfma_f32_16x16x32_bf16 v[110:113], v[130:133], v[170:173], 0
	v_mfma_f32_16x16x32_bf16 v[106:109], v[138:141], v[170:173], 0
	v_mfma_f32_16x16x32_bf16 v[94:97], v[130:133], v[196:199], 0
	v_mfma_f32_16x16x32_bf16 v[90:93], v[138:141], v[196:199], 0
	v_mfma_f32_16x16x32_bf16 v[78:81], v[130:133], v[212:215], 0
	v_mfma_f32_16x16x32_bf16 v[74:77], v[138:141], v[212:215], 0
	v_mfma_f32_16x16x32_bf16 v[126:129], v[134:137], v[166:169], v[126:129]
	v_mfma_f32_16x16x32_bf16 v[122:125], v[142:145], v[166:169], v[122:125]
	v_mfma_f32_16x16x32_bf16 v[110:113], v[134:137], v[174:177], v[110:113]
	v_mfma_f32_16x16x32_bf16 v[106:109], v[142:145], v[174:177], v[106:109]
	v_mfma_f32_16x16x32_bf16 v[94:97], v[134:137], v[200:203], v[94:97]
	v_mfma_f32_16x16x32_bf16 v[90:93], v[142:145], v[200:203], v[90:93]
	v_mfma_f32_16x16x32_bf16 v[78:81], v[134:137], v[216:219], v[78:81]
	v_mfma_f32_16x16x32_bf16 v[74:77], v[142:145], v[216:219], v[74:77]
	s_setprio 0
	s_setprio 1
	v_mfma_f32_16x16x32_bf16 v[118:121], v[146:149], v[162:165], 0
	v_mfma_f32_16x16x32_bf16 v[114:117], v[154:157], v[162:165], 0
	v_mfma_f32_16x16x32_bf16 v[102:105], v[146:149], v[170:173], 0
	v_mfma_f32_16x16x32_bf16 v[98:101], v[154:157], v[170:173], 0
	v_mfma_f32_16x16x32_bf16 v[86:89], v[146:149], v[196:199], 0
	v_mfma_f32_16x16x32_bf16 v[82:85], v[154:157], v[196:199], 0
	v_mfma_f32_16x16x32_bf16 v[70:73], v[146:149], v[212:215], 0
	v_mfma_f32_16x16x32_bf16 v[66:69], v[154:157], v[212:215], 0
	v_mfma_f32_16x16x32_bf16 v[118:121], v[150:153], v[166:169], v[118:121]
	v_mfma_f32_16x16x32_bf16 v[114:117], v[158:161], v[166:169], v[114:117]
	v_mfma_f32_16x16x32_bf16 v[102:105], v[150:153], v[174:177], v[102:105]
	v_mfma_f32_16x16x32_bf16 v[98:101], v[158:161], v[174:177], v[98:101]
	v_mfma_f32_16x16x32_bf16 v[86:89], v[150:153], v[200:203], v[86:89]
	v_mfma_f32_16x16x32_bf16 v[82:85], v[158:161], v[200:203], v[82:85]
	v_mfma_f32_16x16x32_bf16 v[70:73], v[150:153], v[216:219], v[70:73]
	v_mfma_f32_16x16x32_bf16 v[66:69], v[158:161], v[216:219], v[66:69]
	s_barrier
	s_setprio 0
	ds_read_b128 v[162:165], v210 offset:16384
	ds_read_b128 v[166:169], v210 offset:17408
	ds_read_b128 v[170:173], v210 offset:18432
	ds_read_b128 v[174:177], v210 offset:19456
	ds_read_b128 v[196:199], v210 offset:20480
	ds_read_b128 v[200:203], v210 offset:21504
	ds_read_b128 v[212:215], v210 offset:22528
	ds_read_b128 v[216:219], v210 offset:23552
	s_add_i32 s85, s75, s29
	s_add_u32 s98, s56, 0x80
	s_addc_u32 s99, s57, 0
	s_mov_b32 m0, s85
	s_nop 0
	global_load_lds_dwordx4 v182, s[56:57]
	s_add_i32 m0, s85, 0x2000
	s_add_u32 s88, s56, 0x160000
	s_addc_u32 s89, s57, 0
	s_add_i32 s85, s76, s29
	global_load_lds_dwordx4 v186, s[56:57]
	s_mov_b32 m0, s85
	s_nop 0
	global_load_lds_dwordx4 v182, s[88:89]
	s_add_i32 m0, s85, 0x2000
	s_nop 0
	global_load_lds_dwordx4 v186, s[88:89]
	s_add_u32 s100, s58, 0x80
	s_addc_u32 s101, s59, 0
	s_mov_b32 m0, s31
	s_nop 0
	global_load_lds_dwordx4 v180, s[58:59]
	s_mov_b32 m0, s64
	s_nop 0
	global_load_lds_dwordx4 v184, s[58:59]
	s_waitcnt vmcnt(8)
	s_waitcnt lgkmcnt(0)
	s_setprio 1
	s_barrier
	v_mfma_f32_16x16x32_bf16 v[62:65], v[130:133], v[162:165], 0
	v_mfma_f32_16x16x32_bf16 v[58:61], v[138:141], v[162:165], 0
	v_mfma_f32_16x16x32_bf16 v[46:49], v[130:133], v[170:173], 0
	v_mfma_f32_16x16x32_bf16 v[42:45], v[138:141], v[170:173], 0
	v_mfma_f32_16x16x32_bf16 v[30:33], v[130:133], v[196:199], 0
	v_mfma_f32_16x16x32_bf16 v[26:29], v[138:141], v[196:199], 0
	v_mfma_f32_16x16x32_bf16 v[14:17], v[130:133], v[212:215], 0
	v_mfma_f32_16x16x32_bf16 v[10:13], v[138:141], v[212:215], 0
	v_mfma_f32_16x16x32_bf16 v[62:65], v[134:137], v[166:169], v[62:65]
	v_mfma_f32_16x16x32_bf16 v[58:61], v[142:145], v[166:169], v[58:61]
	v_mfma_f32_16x16x32_bf16 v[46:49], v[134:137], v[174:177], v[46:49]
	v_mfma_f32_16x16x32_bf16 v[42:45], v[142:145], v[174:177], v[42:45]
	v_mfma_f32_16x16x32_bf16 v[30:33], v[134:137], v[200:203], v[30:33]
	v_mfma_f32_16x16x32_bf16 v[26:29], v[142:145], v[200:203], v[26:29]
	v_mfma_f32_16x16x32_bf16 v[14:17], v[134:137], v[216:219], v[14:17]
	v_mfma_f32_16x16x32_bf16 v[10:13], v[142:145], v[216:219], v[10:13]
	s_setprio 0
	s_setprio 1
	v_mfma_f32_16x16x32_bf16 v[54:57], v[146:149], v[162:165], 0
	v_mfma_f32_16x16x32_bf16 v[50:53], v[154:157], v[162:165], 0
	v_mfma_f32_16x16x32_bf16 v[38:41], v[146:149], v[170:173], 0
	v_mfma_f32_16x16x32_bf16 v[34:37], v[154:157], v[170:173], 0
	v_mfma_f32_16x16x32_bf16 v[22:25], v[146:149], v[196:199], 0
	v_mfma_f32_16x16x32_bf16 v[18:21], v[154:157], v[196:199], 0
	v_mfma_f32_16x16x32_bf16 v[6:9], v[146:149], v[212:215], 0
	v_mfma_f32_16x16x32_bf16 v[2:5], v[154:157], v[212:215], 0
	v_mfma_f32_16x16x32_bf16 v[54:57], v[150:153], v[166:169], v[54:57]
	v_mfma_f32_16x16x32_bf16 v[50:53], v[158:161], v[166:169], v[50:53]
	v_mfma_f32_16x16x32_bf16 v[38:41], v[150:153], v[174:177], v[38:41]
	v_mfma_f32_16x16x32_bf16 v[34:37], v[158:161], v[174:177], v[34:37]
	v_mfma_f32_16x16x32_bf16 v[22:25], v[150:153], v[200:203], v[22:25]
	v_mfma_f32_16x16x32_bf16 v[18:21], v[158:161], v[200:203], v[18:21]
	v_mfma_f32_16x16x32_bf16 v[6:9], v[150:153], v[216:219], v[6:9]
	v_mfma_f32_16x16x32_bf16 v[2:5], v[158:161], v[216:219], v[2:5]
	s_barrier
	s_setprio 0
	ds_read_b128 v[130:133], v208 offset:32768
	ds_read_b128 v[134:137], v208 offset:33792
	ds_read_b128 v[138:141], v208 offset:34816
	ds_read_b128 v[142:145], v208 offset:35840
	ds_read_b128 v[146:149], v209 offset:32768
	ds_read_b128 v[150:153], v209 offset:33792
	ds_read_b128 v[154:157], v209 offset:34816
	ds_read_b128 v[158:161], v209 offset:35840
	ds_read_b128 v[162:165], v210 offset:32768
	ds_read_b128 v[166:169], v210 offset:33792
	ds_read_b128 v[170:173], v210 offset:34816
	ds_read_b128 v[174:177], v210 offset:35840
	ds_read_b128 v[196:199], v210 offset:36864
	ds_read_b128 v[200:203], v210 offset:37888
	ds_read_b128 v[212:215], v210 offset:38912
	ds_read_b128 v[216:219], v210 offset:39936
	s_add_i32 s85, 0, 0x18000
	s_add_i32 s87, 0, 0x1c000
	s_add_u32 s58, s58, 0x160000
	s_addc_u32 s59, s59, 0
	s_mov_b32 m0, s65
	s_nop 0
	global_load_lds_dwordx4 v180, s[58:59]
	s_mov_b32 m0, s66
	s_nop 0
	global_load_lds_dwordx4 v184, s[58:59]
	s_waitcnt vmcnt(8)
	s_waitcnt lgkmcnt(0)
	s_setprio 1
	s_barrier
	v_mfma_f32_16x16x32_bf16 v[126:129], v[130:133], v[162:165], v[126:129]
	v_mfma_f32_16x16x32_bf16 v[122:125], v[138:141], v[162:165], v[122:125]
	v_mfma_f32_16x16x32_bf16 v[110:113], v[130:133], v[170:173], v[110:113]
	v_mfma_f32_16x16x32_bf16 v[106:109], v[138:141], v[170:173], v[106:109]
	v_mfma_f32_16x16x32_bf16 v[94:97], v[130:133], v[196:199], v[94:97]
	v_mfma_f32_16x16x32_bf16 v[90:93], v[138:141], v[196:199], v[90:93]
	v_mfma_f32_16x16x32_bf16 v[78:81], v[130:133], v[212:215], v[78:81]
	v_mfma_f32_16x16x32_bf16 v[74:77], v[138:141], v[212:215], v[74:77]
	v_mfma_f32_16x16x32_bf16 v[126:129], v[134:137], v[166:169], v[126:129]
	v_mfma_f32_16x16x32_bf16 v[122:125], v[142:145], v[166:169], v[122:125]
	v_mfma_f32_16x16x32_bf16 v[110:113], v[134:137], v[174:177], v[110:113]
	v_mfma_f32_16x16x32_bf16 v[106:109], v[142:145], v[174:177], v[106:109]
	v_mfma_f32_16x16x32_bf16 v[94:97], v[134:137], v[200:203], v[94:97]
	v_mfma_f32_16x16x32_bf16 v[90:93], v[142:145], v[200:203], v[90:93]
	v_mfma_f32_16x16x32_bf16 v[78:81], v[134:137], v[216:219], v[78:81]
	v_mfma_f32_16x16x32_bf16 v[74:77], v[142:145], v[216:219], v[74:77]
	s_setprio 0
	s_setprio 1
	v_mfma_f32_16x16x32_bf16 v[118:121], v[146:149], v[162:165], v[118:121]
	v_mfma_f32_16x16x32_bf16 v[114:117], v[154:157], v[162:165], v[114:117]
	v_mfma_f32_16x16x32_bf16 v[102:105], v[146:149], v[170:173], v[102:105]
	v_mfma_f32_16x16x32_bf16 v[98:101], v[154:157], v[170:173], v[98:101]
	v_mfma_f32_16x16x32_bf16 v[86:89], v[146:149], v[196:199], v[86:89]
	v_mfma_f32_16x16x32_bf16 v[82:85], v[154:157], v[196:199], v[82:85]
	v_mfma_f32_16x16x32_bf16 v[70:73], v[146:149], v[212:215], v[70:73]
	v_mfma_f32_16x16x32_bf16 v[66:69], v[154:157], v[212:215], v[66:69]
	v_mfma_f32_16x16x32_bf16 v[118:121], v[150:153], v[166:169], v[118:121]
	v_mfma_f32_16x16x32_bf16 v[114:117], v[158:161], v[166:169], v[114:117]
	v_mfma_f32_16x16x32_bf16 v[102:105], v[150:153], v[174:177], v[102:105]
	v_mfma_f32_16x16x32_bf16 v[98:101], v[158:161], v[174:177], v[98:101]
	v_mfma_f32_16x16x32_bf16 v[86:89], v[150:153], v[200:203], v[86:89]
	v_mfma_f32_16x16x32_bf16 v[82:85], v[158:161], v[200:203], v[82:85]
	v_mfma_f32_16x16x32_bf16 v[70:73], v[150:153], v[216:219], v[70:73]
	v_mfma_f32_16x16x32_bf16 v[66:69], v[158:161], v[216:219], v[66:69]
	s_barrier
	s_setprio 0
	ds_read_b128 v[162:165], v210 offset:49152
	ds_read_b128 v[166:169], v210 offset:50176
	ds_read_b128 v[170:173], v210 offset:51200
	ds_read_b128 v[174:177], v210 offset:52224
	ds_read_b128 v[196:199], v210 offset:53248
	ds_read_b128 v[200:203], v210 offset:54272
	ds_read_b128 v[212:215], v210 offset:55296
	ds_read_b128 v[216:219], v210 offset:56320
	s_add_i32 s58, s85, s29
	s_mov_b32 m0, s58
	s_nop 0
	global_load_lds_dwordx4 v182, s[98:99]
	s_add_i32 m0, s58, 0x2000
	s_add_u32 s56, s56, 0x160080
	s_addc_u32 s57, s57, 0
	s_add_i32 s58, s87, s29
	global_load_lds_dwordx4 v186, s[98:99]
	s_mov_b32 m0, s58
	s_nop 0
	global_load_lds_dwordx4 v182, s[56:57]
	s_add_i32 m0, s58, 0x2000
	s_nop 0
	global_load_lds_dwordx4 v186, s[56:57]
	s_mov_b32 m0, s71
	s_nop 0
	global_load_lds_dwordx4 v180, s[100:101]
	s_mov_b32 m0, s72
	s_nop 0
	global_load_lds_dwordx4 v184, s[100:101]
	s_waitcnt vmcnt(8)
	s_waitcnt lgkmcnt(0)
	s_setprio 1
	s_barrier
	v_mfma_f32_16x16x32_bf16 v[62:65], v[130:133], v[162:165], v[62:65]
	v_mfma_f32_16x16x32_bf16 v[58:61], v[138:141], v[162:165], v[58:61]
	v_mfma_f32_16x16x32_bf16 v[46:49], v[130:133], v[170:173], v[46:49]
	v_mfma_f32_16x16x32_bf16 v[42:45], v[138:141], v[170:173], v[42:45]
	v_mfma_f32_16x16x32_bf16 v[30:33], v[130:133], v[196:199], v[30:33]
	v_mfma_f32_16x16x32_bf16 v[26:29], v[138:141], v[196:199], v[26:29]
	v_mfma_f32_16x16x32_bf16 v[14:17], v[130:133], v[212:215], v[14:17]
	v_mfma_f32_16x16x32_bf16 v[10:13], v[138:141], v[212:215], v[10:13]
	v_mfma_f32_16x16x32_bf16 v[62:65], v[134:137], v[166:169], v[62:65]
	v_mfma_f32_16x16x32_bf16 v[58:61], v[142:145], v[166:169], v[58:61]
	v_mfma_f32_16x16x32_bf16 v[46:49], v[134:137], v[174:177], v[46:49]
	v_mfma_f32_16x16x32_bf16 v[42:45], v[142:145], v[174:177], v[42:45]
	v_mfma_f32_16x16x32_bf16 v[30:33], v[134:137], v[200:203], v[30:33]
	v_mfma_f32_16x16x32_bf16 v[26:29], v[142:145], v[200:203], v[26:29]
	v_mfma_f32_16x16x32_bf16 v[14:17], v[134:137], v[216:219], v[14:17]
	v_mfma_f32_16x16x32_bf16 v[10:13], v[142:145], v[216:219], v[10:13]
	s_setprio 0
	s_setprio 1
	v_mfma_f32_16x16x32_bf16 v[54:57], v[146:149], v[162:165], v[54:57]
	v_mfma_f32_16x16x32_bf16 v[50:53], v[154:157], v[162:165], v[50:53]
	v_mfma_f32_16x16x32_bf16 v[38:41], v[146:149], v[170:173], v[38:41]
	v_mfma_f32_16x16x32_bf16 v[34:37], v[154:157], v[170:173], v[34:37]
	v_mfma_f32_16x16x32_bf16 v[22:25], v[146:149], v[196:199], v[22:25]
	v_mfma_f32_16x16x32_bf16 v[18:21], v[154:157], v[196:199], v[18:21]
	v_mfma_f32_16x16x32_bf16 v[6:9], v[146:149], v[212:215], v[6:9]
	v_mfma_f32_16x16x32_bf16 v[2:5], v[154:157], v[212:215], v[2:5]
	v_mfma_f32_16x16x32_bf16 v[54:57], v[150:153], v[166:169], v[54:57]
	v_mfma_f32_16x16x32_bf16 v[50:53], v[158:161], v[166:169], v[50:53]
	v_mfma_f32_16x16x32_bf16 v[38:41], v[150:153], v[174:177], v[38:41]
	v_mfma_f32_16x16x32_bf16 v[34:37], v[158:161], v[174:177], v[34:37]
	v_mfma_f32_16x16x32_bf16 v[22:25], v[150:153], v[200:203], v[22:25]
	v_mfma_f32_16x16x32_bf16 v[18:21], v[158:161], v[200:203], v[18:21]
	v_mfma_f32_16x16x32_bf16 v[6:9], v[150:153], v[216:219], v[6:9]
	v_mfma_f32_16x16x32_bf16 v[2:5], v[158:161], v[216:219], v[2:5]
	s_barrier
	s_setprio 0
	s_add_i32 s83, s83, 2
	s_add_u32 s12, s12, 0x100
	s_addc_u32 s13, s13, 0
	s_add_u32 s81, s81, 0x100
	s_addc_u32 s82, s82, 0
	s_cmpk_gt_u32 s83, 0x55
.LBB0_379:
	ds_read_b128 v[130:133], v208
	ds_read_b128 v[134:137], v208 offset:1024
	ds_read_b128 v[138:141], v208 offset:2048
	ds_read_b128 v[142:145], v208 offset:3072
	ds_read_b128 v[146:149], v209
	ds_read_b128 v[150:153], v209 offset:1024
	ds_read_b128 v[154:157], v209 offset:2048
	ds_read_b128 v[158:161], v209 offset:3072
	ds_read_b128 v[162:165], v210
	ds_read_b128 v[166:169], v210 offset:1024
	ds_read_b128 v[170:173], v210 offset:2048
	ds_read_b128 v[174:177], v210 offset:3072
	ds_read_b128 v[196:199], v210 offset:4096
	ds_read_b128 v[200:203], v210 offset:5120
	ds_read_b128 v[212:215], v210 offset:6144
	ds_read_b128 v[216:219], v210 offset:7168
	s_add_u32 s56, s12, 0xffea0080
	s_addc_u32 s57, s13, -1
	s_cmpk_eq_i32 s83, 0x54
	s_cselect_b32 s59, s43, s57
	s_cselect_b32 s58, s42, s56
	s_cselect_b32 s57, s55, s82
	s_cselect_b32 s56, s54, s81
	s_add_i32 m0, s31, 0xc000
	s_nop 0
	global_load_lds_dwordx4 v188, s[12:13]
	s_add_i32 m0, s31, 0xe000
	s_nop 0
	global_load_lds_dwordx4 v190, s[12:13]
	s_waitcnt vmcnt(8)
	s_waitcnt lgkmcnt(0)
	s_setprio 1
	s_barrier
	v_mfma_f32_16x16x32_bf16 v[126:129], v[130:133], v[162:165], v[126:129]
	v_mfma_f32_16x16x32_bf16 v[122:125], v[138:141], v[162:165], v[122:125]
	v_mfma_f32_16x16x32_bf16 v[110:113], v[130:133], v[170:173], v[110:113]
	v_mfma_f32_16x16x32_bf16 v[106:109], v[138:141], v[170:173], v[106:109]
	v_mfma_f32_16x16x32_bf16 v[94:97], v[130:133], v[196:199], v[94:97]
	v_mfma_f32_16x16x32_bf16 v[90:93], v[138:141], v[196:199], v[90:93]
	v_mfma_f32_16x16x32_bf16 v[78:81], v[130:133], v[212:215], v[78:81]
	v_mfma_f32_16x16x32_bf16 v[74:77], v[138:141], v[212:215], v[74:77]
	v_mfma_f32_16x16x32_bf16 v[126:129], v[134:137], v[166:169], v[126:129]
	v_mfma_f32_16x16x32_bf16 v[122:125], v[142:145], v[166:169], v[122:125]
	v_mfma_f32_16x16x32_bf16 v[110:113], v[134:137], v[174:177], v[110:113]
	v_mfma_f32_16x16x32_bf16 v[106:109], v[142:145], v[174:177], v[106:109]
	v_mfma_f32_16x16x32_bf16 v[94:97], v[134:137], v[200:203], v[94:97]
	v_mfma_f32_16x16x32_bf16 v[90:93], v[142:145], v[200:203], v[90:93]
	v_mfma_f32_16x16x32_bf16 v[78:81], v[134:137], v[216:219], v[78:81]
	v_mfma_f32_16x16x32_bf16 v[74:77], v[142:145], v[216:219], v[74:77]
	s_setprio 0
	s_setprio 1
	v_mfma_f32_16x16x32_bf16 v[118:121], v[146:149], v[162:165], v[118:121]
	v_mfma_f32_16x16x32_bf16 v[114:117], v[154:157], v[162:165], v[114:117]
	v_mfma_f32_16x16x32_bf16 v[102:105], v[146:149], v[170:173], v[102:105]
	v_mfma_f32_16x16x32_bf16 v[98:101], v[154:157], v[170:173], v[98:101]
	v_mfma_f32_16x16x32_bf16 v[86:89], v[146:149], v[196:199], v[86:89]
	v_mfma_f32_16x16x32_bf16 v[82:85], v[154:157], v[196:199], v[82:85]
	v_mfma_f32_16x16x32_bf16 v[70:73], v[146:149], v[212:215], v[70:73]
	v_mfma_f32_16x16x32_bf16 v[66:69], v[154:157], v[212:215], v[66:69]
	v_mfma_f32_16x16x32_bf16 v[118:121], v[150:153], v[166:169], v[118:121]
	v_mfma_f32_16x16x32_bf16 v[114:117], v[158:161], v[166:169], v[114:117]
	v_mfma_f32_16x16x32_bf16 v[102:105], v[150:153], v[174:177], v[102:105]
	v_mfma_f32_16x16x32_bf16 v[98:101], v[158:161], v[174:177], v[98:101]
	v_mfma_f32_16x16x32_bf16 v[86:89], v[150:153], v[200:203], v[86:89]
	v_mfma_f32_16x16x32_bf16 v[82:85], v[158:161], v[200:203], v[82:85]
	v_mfma_f32_16x16x32_bf16 v[70:73], v[150:153], v[216:219], v[70:73]
	v_mfma_f32_16x16x32_bf16 v[66:69], v[158:161], v[216:219], v[66:69]
	s_barrier
	s_setprio 0
	ds_read_b128 v[162:165], v210 offset:16384
	ds_read_b128 v[166:169], v210 offset:17408
	ds_read_b128 v[170:173], v210 offset:18432
	ds_read_b128 v[174:177], v210 offset:19456
	ds_read_b128 v[196:199], v210 offset:20480
	ds_read_b128 v[200:203], v210 offset:21504
	ds_read_b128 v[212:215], v210 offset:22528
	ds_read_b128 v[216:219], v210 offset:23552
	s_add_i32 s85, s75, s29
	s_add_u32 s98, s56, 0x80
	s_addc_u32 s99, s57, 0
	s_mov_b32 m0, s85
	s_nop 0
	global_load_lds_dwordx4 v182, s[56:57]
	s_add_i32 m0, s85, 0x2000
	s_add_u32 s88, s56, 0x160000
	s_addc_u32 s89, s57, 0
	s_add_i32 s85, s76, s29
	global_load_lds_dwordx4 v186, s[56:57]
	s_mov_b32 m0, s85
	s_nop 0
	global_load_lds_dwordx4 v182, s[88:89]
	s_add_i32 m0, s85, 0x2000
	s_nop 0
	global_load_lds_dwordx4 v186, s[88:89]
	s_add_u32 s100, s58, 0x80
	s_addc_u32 s101, s59, 0
	s_mov_b32 m0, s31
	s_nop 0
	global_load_lds_dwordx4 v180, s[58:59]
	s_mov_b32 m0, s64
	s_nop 0
	global_load_lds_dwordx4 v184, s[58:59]
	s_waitcnt vmcnt(8)
	s_waitcnt lgkmcnt(0)
	s_setprio 1
	s_barrier
	v_mfma_f32_16x16x32_bf16 v[62:65], v[130:133], v[162:165], v[62:65]
	v_mfma_f32_16x16x32_bf16 v[58:61], v[138:141], v[162:165], v[58:61]
	v_mfma_f32_16x16x32_bf16 v[46:49], v[130:133], v[170:173], v[46:49]
	v_mfma_f32_16x16x32_bf16 v[42:45], v[138:141], v[170:173], v[42:45]
	v_mfma_f32_16x16x32_bf16 v[30:33], v[130:133], v[196:199], v[30:33]
	v_mfma_f32_16x16x32_bf16 v[26:29], v[138:141], v[196:199], v[26:29]
	v_mfma_f32_16x16x32_bf16 v[14:17], v[130:133], v[212:215], v[14:17]
	v_mfma_f32_16x16x32_bf16 v[10:13], v[138:141], v[212:215], v[10:13]
	v_mfma_f32_16x16x32_bf16 v[62:65], v[134:137], v[166:169], v[62:65]
	v_mfma_f32_16x16x32_bf16 v[58:61], v[142:145], v[166:169], v[58:61]
	v_mfma_f32_16x16x32_bf16 v[46:49], v[134:137], v[174:177], v[46:49]
	v_mfma_f32_16x16x32_bf16 v[42:45], v[142:145], v[174:177], v[42:45]
	v_mfma_f32_16x16x32_bf16 v[30:33], v[134:137], v[200:203], v[30:33]
	v_mfma_f32_16x16x32_bf16 v[26:29], v[142:145], v[200:203], v[26:29]
	v_mfma_f32_16x16x32_bf16 v[14:17], v[134:137], v[216:219], v[14:17]
	v_mfma_f32_16x16x32_bf16 v[10:13], v[142:145], v[216:219], v[10:13]
	s_setprio 0
	s_setprio 1
	v_mfma_f32_16x16x32_bf16 v[54:57], v[146:149], v[162:165], v[54:57]
	v_mfma_f32_16x16x32_bf16 v[50:53], v[154:157], v[162:165], v[50:53]
	v_mfma_f32_16x16x32_bf16 v[38:41], v[146:149], v[170:173], v[38:41]
	v_mfma_f32_16x16x32_bf16 v[34:37], v[154:157], v[170:173], v[34:37]
	v_mfma_f32_16x16x32_bf16 v[22:25], v[146:149], v[196:199], v[22:25]
	v_mfma_f32_16x16x32_bf16 v[18:21], v[154:157], v[196:199], v[18:21]
	v_mfma_f32_16x16x32_bf16 v[6:9], v[146:149], v[212:215], v[6:9]
	v_mfma_f32_16x16x32_bf16 v[2:5], v[154:157], v[212:215], v[2:5]
	v_mfma_f32_16x16x32_bf16 v[54:57], v[150:153], v[166:169], v[54:57]
	v_mfma_f32_16x16x32_bf16 v[50:53], v[158:161], v[166:169], v[50:53]
	v_mfma_f32_16x16x32_bf16 v[38:41], v[150:153], v[174:177], v[38:41]
	v_mfma_f32_16x16x32_bf16 v[34:37], v[158:161], v[174:177], v[34:37]
	v_mfma_f32_16x16x32_bf16 v[22:25], v[150:153], v[200:203], v[22:25]
	v_mfma_f32_16x16x32_bf16 v[18:21], v[158:161], v[200:203], v[18:21]
	v_mfma_f32_16x16x32_bf16 v[6:9], v[150:153], v[216:219], v[6:9]
	v_mfma_f32_16x16x32_bf16 v[2:5], v[158:161], v[216:219], v[2:5]
	s_barrier
	s_setprio 0
	s_add_i32 s85, 0, 0x18000
	s_add_i32 s87, 0, 0x1c000
	ds_read_b128 v[130:133], v208 offset:32768
	ds_read_b128 v[134:137], v208 offset:33792
	ds_read_b128 v[138:141], v208 offset:34816
	ds_read_b128 v[142:145], v208 offset:35840
	ds_read_b128 v[146:149], v209 offset:32768
	ds_read_b128 v[150:153], v209 offset:33792
	ds_read_b128 v[154:157], v209 offset:34816
	ds_read_b128 v[158:161], v209 offset:35840
	s_add_u32 s58, s58, 0x160000
	s_addc_u32 s59, s59, 0
	s_mov_b32 m0, s65
	ds_read_b128 v[162:165], v210 offset:32768
	ds_read_b128 v[166:169], v210 offset:33792
	ds_read_b128 v[170:173], v210 offset:34816
	ds_read_b128 v[174:177], v210 offset:35840
	ds_read_b128 v[196:199], v210 offset:36864
	ds_read_b128 v[200:203], v210 offset:37888
	ds_read_b128 v[212:215], v210 offset:38912
	ds_read_b128 v[216:219], v210 offset:39936
	global_load_lds_dwordx4 v180, s[58:59]
	v_lshl_add_u64 v[226:227], s[58:59], 0, v[184:185]
	s_mov_b32 m0, s66
	s_nop 0
	global_load_lds_dwordx4 v[226:227], off
	s_waitcnt vmcnt(8)
	s_waitcnt lgkmcnt(0)
	s_setprio 1
	s_barrier
	v_mfma_f32_16x16x32_bf16 v[126:129], v[130:133], v[162:165], v[126:129]
	v_mfma_f32_16x16x32_bf16 v[122:125], v[138:141], v[162:165], v[122:125]
	v_mfma_f32_16x16x32_bf16 v[110:113], v[130:133], v[170:173], v[110:113]
	v_mfma_f32_16x16x32_bf16 v[106:109], v[138:141], v[170:173], v[106:109]
	v_mfma_f32_16x16x32_bf16 v[94:97], v[130:133], v[196:199], v[94:97]
	v_mfma_f32_16x16x32_bf16 v[90:93], v[138:141], v[196:199], v[90:93]
	v_mfma_f32_16x16x32_bf16 v[78:81], v[130:133], v[212:215], v[78:81]
	v_mfma_f32_16x16x32_bf16 v[74:77], v[138:141], v[212:215], v[74:77]
	v_mfma_f32_16x16x32_bf16 v[126:129], v[134:137], v[166:169], v[126:129]
	v_mfma_f32_16x16x32_bf16 v[122:125], v[142:145], v[166:169], v[122:125]
	v_mfma_f32_16x16x32_bf16 v[110:113], v[134:137], v[174:177], v[110:113]
	v_mfma_f32_16x16x32_bf16 v[106:109], v[142:145], v[174:177], v[106:109]
	v_mfma_f32_16x16x32_bf16 v[94:97], v[134:137], v[200:203], v[94:97]
	v_mfma_f32_16x16x32_bf16 v[90:93], v[142:145], v[200:203], v[90:93]
	v_mfma_f32_16x16x32_bf16 v[78:81], v[134:137], v[216:219], v[78:81]
	v_mfma_f32_16x16x32_bf16 v[74:77], v[142:145], v[216:219], v[74:77]
	s_setprio 0
	s_setprio 1
	v_mfma_f32_16x16x32_bf16 v[118:121], v[146:149], v[162:165], v[118:121]
	v_mfma_f32_16x16x32_bf16 v[114:117], v[154:157], v[162:165], v[114:117]
	v_mfma_f32_16x16x32_bf16 v[102:105], v[146:149], v[170:173], v[102:105]
	v_mfma_f32_16x16x32_bf16 v[98:101], v[154:157], v[170:173], v[98:101]
	v_mfma_f32_16x16x32_bf16 v[86:89], v[146:149], v[196:199], v[86:89]
	v_mfma_f32_16x16x32_bf16 v[82:85], v[154:157], v[196:199], v[82:85]
	v_mfma_f32_16x16x32_bf16 v[70:73], v[146:149], v[212:215], v[70:73]
	v_mfma_f32_16x16x32_bf16 v[66:69], v[154:157], v[212:215], v[66:69]
	v_mfma_f32_16x16x32_bf16 v[118:121], v[150:153], v[166:169], v[118:121]
	v_mfma_f32_16x16x32_bf16 v[114:117], v[158:161], v[166:169], v[114:117]
	v_mfma_f32_16x16x32_bf16 v[102:105], v[150:153], v[174:177], v[102:105]
	v_mfma_f32_16x16x32_bf16 v[98:101], v[158:161], v[174:177], v[98:101]
	v_mfma_f32_16x16x32_bf16 v[86:89], v[150:153], v[200:203], v[86:89]
	v_mfma_f32_16x16x32_bf16 v[82:85], v[158:161], v[200:203], v[82:85]
	v_mfma_f32_16x16x32_bf16 v[70:73], v[150:153], v[216:219], v[70:73]
	v_mfma_f32_16x16x32_bf16 v[66:69], v[158:161], v[216:219], v[66:69]
	s_barrier
	s_setprio 0
	ds_read_b128 v[162:165], v210 offset:49152
	ds_read_b128 v[166:169], v210 offset:50176
	ds_read_b128 v[170:173], v210 offset:51200
	ds_read_b128 v[174:177], v210 offset:52224
	ds_read_b128 v[196:199], v210 offset:53248
	ds_read_b128 v[200:203], v210 offset:54272
	ds_read_b128 v[212:215], v210 offset:55296
	ds_read_b128 v[216:219], v210 offset:56320
	s_add_i32 s58, s85, s29
	s_mov_b32 m0, s58
	s_nop 0
	global_load_lds_dwordx4 v182, s[98:99]
	s_add_i32 m0, s58, 0x2000
	s_add_u32 s56, s56, 0x160080
	s_addc_u32 s57, s57, 0
	s_add_i32 s58, s87, s29
	global_load_lds_dwordx4 v186, s[98:99]
	s_mov_b32 m0, s58
	s_nop 0
	global_load_lds_dwordx4 v182, s[56:57]
	s_add_i32 m0, s58, 0x2000
	s_nop 0
	global_load_lds_dwordx4 v186, s[56:57]
	s_mov_b32 m0, s71
	s_nop 0
	global_load_lds_dwordx4 v180, s[100:101]
	s_mov_b32 m0, s72
	s_nop 0
	global_load_lds_dwordx4 v184, s[100:101]
	s_add_i32 s83, s83, 2
	s_add_u32 s12, s12, 0x100
	s_addc_u32 s13, s13, 0
	s_add_u32 s81, s81, 0x100
	s_addc_u32 s82, s82, 0
	s_cmpk_gt_u32 s83, 0x55
	s_waitcnt vmcnt(8)
	s_waitcnt lgkmcnt(0)
	s_setprio 1
	s_barrier
	v_mfma_f32_16x16x32_bf16 v[62:65], v[130:133], v[162:165], v[62:65]
	v_mfma_f32_16x16x32_bf16 v[58:61], v[138:141], v[162:165], v[58:61]
	v_mfma_f32_16x16x32_bf16 v[46:49], v[130:133], v[170:173], v[46:49]
	v_mfma_f32_16x16x32_bf16 v[42:45], v[138:141], v[170:173], v[42:45]
	v_mfma_f32_16x16x32_bf16 v[30:33], v[130:133], v[196:199], v[30:33]
	v_mfma_f32_16x16x32_bf16 v[26:29], v[138:141], v[196:199], v[26:29]
	v_mfma_f32_16x16x32_bf16 v[14:17], v[130:133], v[212:215], v[14:17]
	v_mfma_f32_16x16x32_bf16 v[10:13], v[138:141], v[212:215], v[10:13]
	v_mfma_f32_16x16x32_bf16 v[62:65], v[134:137], v[166:169], v[62:65]
	v_mfma_f32_16x16x32_bf16 v[58:61], v[142:145], v[166:169], v[58:61]
	v_mfma_f32_16x16x32_bf16 v[46:49], v[134:137], v[174:177], v[46:49]
	v_mfma_f32_16x16x32_bf16 v[42:45], v[142:145], v[174:177], v[42:45]
	v_mfma_f32_16x16x32_bf16 v[30:33], v[134:137], v[200:203], v[30:33]
	v_mfma_f32_16x16x32_bf16 v[26:29], v[142:145], v[200:203], v[26:29]
	v_mfma_f32_16x16x32_bf16 v[14:17], v[134:137], v[216:219], v[14:17]
	v_mfma_f32_16x16x32_bf16 v[10:13], v[142:145], v[216:219], v[10:13]
	s_setprio 0
	s_setprio 1
	v_mfma_f32_16x16x32_bf16 v[54:57], v[146:149], v[162:165], v[54:57]
	v_mfma_f32_16x16x32_bf16 v[50:53], v[154:157], v[162:165], v[50:53]
	v_mfma_f32_16x16x32_bf16 v[38:41], v[146:149], v[170:173], v[38:41]
	v_mfma_f32_16x16x32_bf16 v[34:37], v[154:157], v[170:173], v[34:37]
	v_mfma_f32_16x16x32_bf16 v[22:25], v[146:149], v[196:199], v[22:25]
	v_mfma_f32_16x16x32_bf16 v[18:21], v[154:157], v[196:199], v[18:21]
	v_mfma_f32_16x16x32_bf16 v[6:9], v[146:149], v[212:215], v[6:9]
	v_mfma_f32_16x16x32_bf16 v[2:5], v[154:157], v[212:215], v[2:5]
	v_mfma_f32_16x16x32_bf16 v[54:57], v[150:153], v[166:169], v[54:57]
	v_mfma_f32_16x16x32_bf16 v[50:53], v[158:161], v[166:169], v[50:53]
	v_mfma_f32_16x16x32_bf16 v[38:41], v[150:153], v[174:177], v[38:41]
	v_mfma_f32_16x16x32_bf16 v[34:37], v[158:161], v[174:177], v[34:37]
	v_mfma_f32_16x16x32_bf16 v[22:25], v[150:153], v[200:203], v[22:25]
	v_mfma_f32_16x16x32_bf16 v[18:21], v[158:161], v[200:203], v[18:21]
	v_mfma_f32_16x16x32_bf16 v[6:9], v[150:153], v[216:219], v[6:9]
	v_mfma_f32_16x16x32_bf16 v[2:5], v[158:161], v[216:219], v[2:5]
	s_barrier
	s_setprio 0
	s_cbranch_scc0 .LBB0_379
	s_and_b64 vcc, exec, s[34:35]
	s_cbranch_vccz .LBB0_382
	s_barrier

.LBB0_468:
	s_ashr_i32 s11, s10, 31
	s_lshl_b64 s[70:71], s[10:11], 20
	s_add_u32 s70, s89, s70
	s_addc_u32 s71, s90, s71
	s_and_b64 s[72:73], s[4:5], exec
	s_cselect_b32 s11, s71, s1
	s_cselect_b32 s76, s70, s0
	s_ashr_i32 s69, s68, 31
	s_lshl_b64 s[72:73], s[68:69], 20
	s_add_u32 s72, s91, s72
	s_addc_u32 s73, s92, s73
	s_and_b64 s[74:75], s[4:5], exec
	s_cselect_b32 s69, s73, s9
	s_cselect_b32 s77, s72, s8
	s_add_u32 s0, s0, 0x80080
	s_addc_u32 s1, s1, 0
	s_add_u32 s78, s8, 0x100
	s_addc_u32 s79, s9, 0
	s_mov_b32 s80, -2
	s_add_u32 s8, s0, 0xfff80080
	s_addc_u32 s9, s1, -1
	s_cmp_eq_u32 s80, 28
	s_cselect_b32 s75, s11, s9
	s_cselect_b32 s74, s76, s8
	s_cselect_b32 s9, s69, s79
	s_cselect_b32 s8, s77, s78
	s_add_i32 m0, s94, 0xc000
	s_nop 0
	global_load_lds_dwordx4 v162, s[0:1]
	s_add_i32 m0, s94, 0xe000
	s_nop 0
	global_load_lds_dwordx4 v164, s[0:1]
	s_waitcnt vmcnt(8)
	s_waitcnt lgkmcnt(0)
	s_setprio 1
	s_barrier
	v_mfma_f32_16x16x32_bf16 v[66:69], v[78:81], v[214:217], 0
	v_mfma_f32_16x16x32_bf16 v[62:65], v[142:145], v[214:217], 0
	v_mfma_f32_16x16x32_bf16 v[58:61], v[78:81], v[222:225], 0
	v_mfma_f32_16x16x32_bf16 v[54:57], v[142:145], v[222:225], 0
	v_mfma_f32_16x16x32_bf16 v[46:49], v[78:81], v[230:233], 0
	v_mfma_f32_16x16x32_bf16 v[42:45], v[142:145], v[230:233], 0
	v_mfma_f32_16x16x32_bf16 v[38:41], v[78:81], v[238:241], 0
	v_mfma_f32_16x16x32_bf16 v[34:37], v[142:145], v[238:241], 0
	v_mfma_f32_16x16x32_bf16 v[66:69], v[138:141], v[218:221], v[66:69]
	v_mfma_f32_16x16x32_bf16 v[62:65], v[146:149], v[218:221], v[62:65]
	v_mfma_f32_16x16x32_bf16 v[58:61], v[138:141], v[226:229], v[58:61]
	v_mfma_f32_16x16x32_bf16 v[54:57], v[146:149], v[226:229], v[54:57]
	v_mfma_f32_16x16x32_bf16 v[46:49], v[138:141], v[234:237], v[46:49]
	v_mfma_f32_16x16x32_bf16 v[42:45], v[146:149], v[234:237], v[42:45]
	v_mfma_f32_16x16x32_bf16 v[38:41], v[138:141], v[242:245], v[38:41]
	v_mfma_f32_16x16x32_bf16 v[34:37], v[146:149], v[242:245], v[34:37]
	s_setprio 0
	s_setprio 1
	v_mfma_f32_16x16x32_bf16 v[134:137], v[170:173], v[214:217], 0
	v_mfma_f32_16x16x32_bf16 v[130:133], v[180:183], v[214:217], 0
	v_mfma_f32_16x16x32_bf16 v[126:129], v[170:173], v[222:225], 0
	v_mfma_f32_16x16x32_bf16 v[122:125], v[180:183], v[222:225], 0
	v_mfma_f32_16x16x32_bf16 v[118:121], v[170:173], v[230:233], 0
	v_mfma_f32_16x16x32_bf16 v[114:117], v[180:183], v[230:233], 0
	v_mfma_f32_16x16x32_bf16 v[110:113], v[170:173], v[238:241], 0
	v_mfma_f32_16x16x32_bf16 v[106:109], v[180:183], v[238:241], 0
	v_mfma_f32_16x16x32_bf16 v[134:137], v[174:177], v[218:221], v[134:137]
	v_mfma_f32_16x16x32_bf16 v[130:133], v[210:213], v[218:221], v[130:133]
	v_mfma_f32_16x16x32_bf16 v[126:129], v[174:177], v[226:229], v[126:129]
	v_mfma_f32_16x16x32_bf16 v[122:125], v[210:213], v[226:229], v[122:125]
	v_mfma_f32_16x16x32_bf16 v[118:121], v[174:177], v[234:237], v[118:121]
	v_mfma_f32_16x16x32_bf16 v[114:117], v[210:213], v[234:237], v[114:117]
	v_mfma_f32_16x16x32_bf16 v[110:113], v[174:177], v[242:245], v[110:113]
	v_mfma_f32_16x16x32_bf16 v[106:109], v[210:213], v[242:245], v[106:109]
	s_barrier
	s_setprio 0
	ds_read_b128 v[214:217], v206 offset:16384
	ds_read_b128 v[218:221], v206 offset:17408
	ds_read_b128 v[222:225], v206 offset:18432
	ds_read_b128 v[226:229], v206 offset:19456
	ds_read_b128 v[230:233], v206 offset:20480
	ds_read_b128 v[234:237], v206 offset:21504
	ds_read_b128 v[238:241], v206 offset:22528
	ds_read_b128 v[242:245], v206 offset:23552
	s_add_i32 s81, s53, s93
	s_add_u32 s98, s8, 0x80
	s_addc_u32 s99, s9, 0
	s_mov_b32 m0, s81
	s_nop 0
	global_load_lds_dwordx4 v152, s[8:9]
	s_add_i32 m0, s81, 0x2000
	s_add_u32 s82, s8, 0x80000
	s_addc_u32 s83, s9, 0
	s_add_i32 s81, s54, s93
	global_load_lds_dwordx4 v156, s[8:9]
	s_mov_b32 m0, s81
	s_nop 0
	global_load_lds_dwordx4 v152, s[82:83]
	s_add_i32 m0, s81, 0x2000
	s_nop 0
	global_load_lds_dwordx4 v156, s[82:83]
	s_add_u32 s100, s74, 0x80
	s_addc_u32 s101, s75, 0
	s_mov_b32 m0, s94
	s_nop 0
	global_load_lds_dwordx4 v150, s[74:75]
	s_mov_b32 m0, s95
	s_nop 0
	global_load_lds_dwordx4 v154, s[74:75]
	s_waitcnt vmcnt(8)
	s_waitcnt lgkmcnt(0)
	s_setprio 1
	s_barrier
	v_mfma_f32_16x16x32_bf16 v[30:33], v[78:81], v[214:217], 0
	v_mfma_f32_16x16x32_bf16 v[26:29], v[142:145], v[214:217], 0
	v_mfma_f32_16x16x32_bf16 v[22:25], v[78:81], v[222:225], 0
	v_mfma_f32_16x16x32_bf16 v[18:21], v[142:145], v[222:225], 0
	v_mfma_f32_16x16x32_bf16 v[14:17], v[78:81], v[230:233], 0
	v_mfma_f32_16x16x32_bf16 v[10:13], v[142:145], v[230:233], 0
	v_mfma_f32_16x16x32_bf16 v[6:9], v[78:81], v[238:241], 0
	v_mfma_f32_16x16x32_bf16 v[2:5], v[142:145], v[238:241], 0
	v_mfma_f32_16x16x32_bf16 v[30:33], v[138:141], v[218:221], v[30:33]
	v_mfma_f32_16x16x32_bf16 v[26:29], v[146:149], v[218:221], v[26:29]
	v_mfma_f32_16x16x32_bf16 v[22:25], v[138:141], v[226:229], v[22:25]
	v_mfma_f32_16x16x32_bf16 v[18:21], v[146:149], v[226:229], v[18:21]
	v_mfma_f32_16x16x32_bf16 v[14:17], v[138:141], v[234:237], v[14:17]
	v_mfma_f32_16x16x32_bf16 v[10:13], v[146:149], v[234:237], v[10:13]
	v_mfma_f32_16x16x32_bf16 v[6:9], v[138:141], v[242:245], v[6:9]
	v_mfma_f32_16x16x32_bf16 v[2:5], v[146:149], v[242:245], v[2:5]
	s_setprio 0
	s_setprio 1
	v_mfma_f32_16x16x32_bf16 v[98:101], v[180:183], v[214:217], 0
	v_mfma_f32_16x16x32_bf16 v[94:97], v[170:173], v[222:225], 0
	v_mfma_f32_16x16x32_bf16 v[90:93], v[180:183], v[222:225], 0
	v_mfma_f32_16x16x32_bf16 v[86:89], v[170:173], v[230:233], 0
	v_mfma_f32_16x16x32_bf16 v[82:85], v[180:183], v[230:233], 0
	v_mfma_f32_16x16x32_bf16 v[74:77], v[170:173], v[238:241], 0
	v_mfma_f32_16x16x32_bf16 v[70:73], v[180:183], v[238:241], 0
	v_mfma_f32_16x16x32_bf16 v[78:81], v[170:173], v[214:217], 0
	v_mfma_f32_16x16x32_bf16 v[98:101], v[210:213], v[218:221], v[98:101]
	v_mfma_f32_16x16x32_bf16 v[94:97], v[174:177], v[226:229], v[94:97]
	v_mfma_f32_16x16x32_bf16 v[90:93], v[210:213], v[226:229], v[90:93]
	v_mfma_f32_16x16x32_bf16 v[86:89], v[174:177], v[234:237], v[86:89]
	v_mfma_f32_16x16x32_bf16 v[82:85], v[210:213], v[234:237], v[82:85]
	v_mfma_f32_16x16x32_bf16 v[74:77], v[174:177], v[242:245], v[74:77]
	v_mfma_f32_16x16x32_bf16 v[70:73], v[210:213], v[242:245], v[70:73]
	v_mfma_f32_16x16x32_bf16 v[78:81], v[174:177], v[218:221], v[78:81]
	s_barrier
	s_setprio 0
	ds_read_b128 v[102:105], v204 offset:32768
	ds_read_b128 v[138:141], v204 offset:33792
	ds_read_b128 v[142:145], v204 offset:34816
	ds_read_b128 v[146:149], v204 offset:35840
	ds_read_b128 v[170:173], v205 offset:32768
	ds_read_b128 v[174:177], v205 offset:33792
	ds_read_b128 v[180:183], v205 offset:34816
	ds_read_b128 v[210:213], v205 offset:35840
	ds_read_b128 v[214:217], v206 offset:32768
	ds_read_b128 v[218:221], v206 offset:33792
	ds_read_b128 v[222:225], v206 offset:34816
	ds_read_b128 v[226:229], v206 offset:35840
	ds_read_b128 v[230:233], v206 offset:36864
	ds_read_b128 v[234:237], v206 offset:37888
	ds_read_b128 v[238:241], v206 offset:38912
	ds_read_b128 v[242:245], v206 offset:39936
	s_add_i32 s81, 0, 0x18000
	s_add_i32 s82, 0, 0x1c000
	s_add_u32 s74, s74, 0x80000
	s_addc_u32 s75, s75, 0
	s_mov_b32 m0, s96
	s_nop 0
	global_load_lds_dwordx4 v150, s[74:75]
	s_mov_b32 m0, s97
	s_nop 0
	global_load_lds_dwordx4 v154, s[74:75]
	s_waitcnt vmcnt(8)
	s_waitcnt lgkmcnt(0)
	s_setprio 1
	s_barrier
	v_mfma_f32_16x16x32_bf16 v[66:69], v[102:105], v[214:217], v[66:69]
	v_mfma_f32_16x16x32_bf16 v[62:65], v[142:145], v[214:217], v[62:65]
	v_mfma_f32_16x16x32_bf16 v[58:61], v[102:105], v[222:225], v[58:61]
	v_mfma_f32_16x16x32_bf16 v[54:57], v[142:145], v[222:225], v[54:57]
	v_mfma_f32_16x16x32_bf16 v[46:49], v[102:105], v[230:233], v[46:49]
	v_mfma_f32_16x16x32_bf16 v[42:45], v[142:145], v[230:233], v[42:45]
	v_mfma_f32_16x16x32_bf16 v[38:41], v[102:105], v[238:241], v[38:41]
	v_mfma_f32_16x16x32_bf16 v[34:37], v[142:145], v[238:241], v[34:37]
	v_mfma_f32_16x16x32_bf16 v[66:69], v[138:141], v[218:221], v[66:69]
	v_mfma_f32_16x16x32_bf16 v[62:65], v[146:149], v[218:221], v[62:65]
	v_mfma_f32_16x16x32_bf16 v[58:61], v[138:141], v[226:229], v[58:61]
	v_mfma_f32_16x16x32_bf16 v[54:57], v[146:149], v[226:229], v[54:57]
	v_mfma_f32_16x16x32_bf16 v[46:49], v[138:141], v[234:237], v[46:49]
	v_mfma_f32_16x16x32_bf16 v[42:45], v[146:149], v[234:237], v[42:45]
	v_mfma_f32_16x16x32_bf16 v[38:41], v[138:141], v[242:245], v[38:41]
	v_mfma_f32_16x16x32_bf16 v[34:37], v[146:149], v[242:245], v[34:37]
	s_setprio 0
	s_setprio 1
	v_mfma_f32_16x16x32_bf16 v[134:137], v[170:173], v[214:217], v[134:137]
	v_mfma_f32_16x16x32_bf16 v[130:133], v[180:183], v[214:217], v[130:133]
	v_mfma_f32_16x16x32_bf16 v[126:129], v[170:173], v[222:225], v[126:129]
	v_mfma_f32_16x16x32_bf16 v[122:125], v[180:183], v[222:225], v[122:125]
	v_mfma_f32_16x16x32_bf16 v[118:121], v[170:173], v[230:233], v[118:121]
	v_mfma_f32_16x16x32_bf16 v[114:117], v[180:183], v[230:233], v[114:117]
	v_mfma_f32_16x16x32_bf16 v[110:113], v[170:173], v[238:241], v[110:113]
	v_mfma_f32_16x16x32_bf16 v[106:109], v[180:183], v[238:241], v[106:109]
	v_mfma_f32_16x16x32_bf16 v[134:137], v[174:177], v[218:221], v[134:137]
	v_mfma_f32_16x16x32_bf16 v[130:133], v[210:213], v[218:221], v[130:133]
	v_mfma_f32_16x16x32_bf16 v[126:129], v[174:177], v[226:229], v[126:129]
	v_mfma_f32_16x16x32_bf16 v[122:125], v[210:213], v[226:229], v[122:125]
	v_mfma_f32_16x16x32_bf16 v[118:121], v[174:177], v[234:237], v[118:121]
	v_mfma_f32_16x16x32_bf16 v[114:117], v[210:213], v[234:237], v[114:117]
	v_mfma_f32_16x16x32_bf16 v[110:113], v[174:177], v[242:245], v[110:113]
	v_mfma_f32_16x16x32_bf16 v[106:109], v[210:213], v[242:245], v[106:109]
	s_barrier
	s_setprio 0
	ds_read_b128 v[214:217], v206 offset:49152
	ds_read_b128 v[218:221], v206 offset:50176
	ds_read_b128 v[222:225], v206 offset:51200
	ds_read_b128 v[226:229], v206 offset:52224
	ds_read_b128 v[230:233], v206 offset:53248
	ds_read_b128 v[234:237], v206 offset:54272
	ds_read_b128 v[238:241], v206 offset:55296
	ds_read_b128 v[242:245], v206 offset:56320
	s_add_i32 s74, s81, s93
	s_mov_b32 m0, s74
	s_nop 0
	global_load_lds_dwordx4 v152, s[98:99]
	s_add_i32 m0, s74, 0x2000
	s_add_u32 s8, s8, 0x80080
	s_addc_u32 s9, s9, 0
	s_add_i32 s74, s82, s93
	global_load_lds_dwordx4 v156, s[98:99]
	s_mov_b32 m0, s74
	s_nop 0
	global_load_lds_dwordx4 v152, s[8:9]
	s_add_i32 m0, s74, 0x2000
	s_nop 0
	global_load_lds_dwordx4 v156, s[8:9]
	s_mov_b32 m0, s85
	s_nop 0
	global_load_lds_dwordx4 v150, s[100:101]
	s_mov_b32 m0, s18
	s_nop 0
	global_load_lds_dwordx4 v154, s[100:101]
	s_waitcnt vmcnt(8)
	s_waitcnt lgkmcnt(0)
	s_setprio 1
	s_barrier
	v_mfma_f32_16x16x32_bf16 v[30:33], v[102:105], v[214:217], v[30:33]
	v_mfma_f32_16x16x32_bf16 v[26:29], v[142:145], v[214:217], v[26:29]
	v_mfma_f32_16x16x32_bf16 v[22:25], v[102:105], v[222:225], v[22:25]
	v_mfma_f32_16x16x32_bf16 v[18:21], v[142:145], v[222:225], v[18:21]
	v_mfma_f32_16x16x32_bf16 v[14:17], v[102:105], v[230:233], v[14:17]
	v_mfma_f32_16x16x32_bf16 v[10:13], v[142:145], v[230:233], v[10:13]
	v_mfma_f32_16x16x32_bf16 v[6:9], v[102:105], v[238:241], v[6:9]
	v_mfma_f32_16x16x32_bf16 v[2:5], v[142:145], v[238:241], v[2:5]
	v_mfma_f32_16x16x32_bf16 v[30:33], v[138:141], v[218:221], v[30:33]
	v_mfma_f32_16x16x32_bf16 v[26:29], v[146:149], v[218:221], v[26:29]
	v_mfma_f32_16x16x32_bf16 v[22:25], v[138:141], v[226:229], v[22:25]
	v_mfma_f32_16x16x32_bf16 v[18:21], v[146:149], v[226:229], v[18:21]
	v_mfma_f32_16x16x32_bf16 v[14:17], v[138:141], v[234:237], v[14:17]
	v_mfma_f32_16x16x32_bf16 v[10:13], v[146:149], v[234:237], v[10:13]
	v_mfma_f32_16x16x32_bf16 v[6:9], v[138:141], v[242:245], v[6:9]
	v_mfma_f32_16x16x32_bf16 v[2:5], v[146:149], v[242:245], v[2:5]
	s_setprio 0
	s_setprio 1
	v_mfma_f32_16x16x32_bf16 v[78:81], v[170:173], v[214:217], v[78:81]
	v_mfma_f32_16x16x32_bf16 v[102:105], v[174:177], v[218:221], v[78:81]
	v_mfma_f32_16x16x32_bf16 v[78:81], v[180:183], v[214:217], v[98:101]
	v_mfma_f32_16x16x32_bf16 v[98:101], v[210:213], v[218:221], v[78:81]
	v_mfma_f32_16x16x32_bf16 v[78:81], v[170:173], v[222:225], v[94:97]
	v_mfma_f32_16x16x32_bf16 v[94:97], v[174:177], v[226:229], v[78:81]
	v_mfma_f32_16x16x32_bf16 v[78:81], v[180:183], v[222:225], v[90:93]
	v_mfma_f32_16x16x32_bf16 v[90:93], v[210:213], v[226:229], v[78:81]
	v_mfma_f32_16x16x32_bf16 v[78:81], v[170:173], v[230:233], v[86:89]
	v_mfma_f32_16x16x32_bf16 v[86:89], v[174:177], v[234:237], v[78:81]
	v_mfma_f32_16x16x32_bf16 v[78:81], v[180:183], v[230:233], v[82:85]
	v_mfma_f32_16x16x32_bf16 v[74:77], v[170:173], v[238:241], v[74:77]
	v_mfma_f32_16x16x32_bf16 v[70:73], v[180:183], v[238:241], v[70:73]
	v_mfma_f32_16x16x32_bf16 v[82:85], v[210:213], v[234:237], v[78:81]
	v_mfma_f32_16x16x32_bf16 v[74:77], v[174:177], v[242:245], v[74:77]
	v_mfma_f32_16x16x32_bf16 v[70:73], v[210:213], v[242:245], v[70:73]
	s_barrier
	s_setprio 0
	s_add_i32 s80, s80, 2
	s_add_u32 s0, s0, 0x100
	s_addc_u32 s1, s1, 0
	s_add_u32 s78, s78, 0x100
	s_addc_u32 s79, s79, 0
	s_cmp_gt_u32 s80, 29
.LBB0_469:
	ds_read_b128 v[78:81], v204
	ds_read_b128 v[138:141], v204 offset:1024
	ds_read_b128 v[142:145], v204 offset:2048
	ds_read_b128 v[146:149], v204 offset:3072
	ds_read_b128 v[170:173], v205
	ds_read_b128 v[174:177], v205 offset:1024
	ds_read_b128 v[180:183], v205 offset:2048
	ds_read_b128 v[210:213], v205 offset:3072
	ds_read_b128 v[214:217], v206
	ds_read_b128 v[218:221], v206 offset:1024
	ds_read_b128 v[222:225], v206 offset:2048
	ds_read_b128 v[226:229], v206 offset:3072
	ds_read_b128 v[230:233], v206 offset:4096
	ds_read_b128 v[234:237], v206 offset:5120
	ds_read_b128 v[238:241], v206 offset:6144
	ds_read_b128 v[242:245], v206 offset:7168
	s_add_u32 s8, s0, 0xfff80080
	s_addc_u32 s9, s1, -1
	s_cmp_eq_u32 s80, 28
	s_cselect_b32 s75, s11, s9
	s_cselect_b32 s74, s76, s8
	s_cselect_b32 s9, s69, s79
	s_cselect_b32 s8, s77, s78
	s_add_i32 m0, s94, 0xc000
	s_nop 0
	global_load_lds_dwordx4 v162, s[0:1]
	s_add_i32 m0, s94, 0xe000
	s_nop 0
	global_load_lds_dwordx4 v164, s[0:1]
	s_waitcnt vmcnt(8)
	s_waitcnt lgkmcnt(0)
	s_setprio 1
	s_barrier
	v_mfma_f32_16x16x32_bf16 v[66:69], v[78:81], v[214:217], v[66:69]
	v_mfma_f32_16x16x32_bf16 v[62:65], v[142:145], v[214:217], v[62:65]
	v_mfma_f32_16x16x32_bf16 v[58:61], v[78:81], v[222:225], v[58:61]
	v_mfma_f32_16x16x32_bf16 v[54:57], v[142:145], v[222:225], v[54:57]
	v_mfma_f32_16x16x32_bf16 v[46:49], v[78:81], v[230:233], v[46:49]
	v_mfma_f32_16x16x32_bf16 v[42:45], v[142:145], v[230:233], v[42:45]
	v_mfma_f32_16x16x32_bf16 v[38:41], v[78:81], v[238:241], v[38:41]
	v_mfma_f32_16x16x32_bf16 v[34:37], v[142:145], v[238:241], v[34:37]
	v_mfma_f32_16x16x32_bf16 v[66:69], v[138:141], v[218:221], v[66:69]
	v_mfma_f32_16x16x32_bf16 v[62:65], v[146:149], v[218:221], v[62:65]
	v_mfma_f32_16x16x32_bf16 v[58:61], v[138:141], v[226:229], v[58:61]
	v_mfma_f32_16x16x32_bf16 v[54:57], v[146:149], v[226:229], v[54:57]
	v_mfma_f32_16x16x32_bf16 v[46:49], v[138:141], v[234:237], v[46:49]
	v_mfma_f32_16x16x32_bf16 v[42:45], v[146:149], v[234:237], v[42:45]
	v_mfma_f32_16x16x32_bf16 v[38:41], v[138:141], v[242:245], v[38:41]
	v_mfma_f32_16x16x32_bf16 v[34:37], v[146:149], v[242:245], v[34:37]
	s_setprio 0
	s_setprio 1
	v_mfma_f32_16x16x32_bf16 v[134:137], v[170:173], v[214:217], v[134:137]
	v_mfma_f32_16x16x32_bf16 v[130:133], v[180:183], v[214:217], v[130:133]
	v_mfma_f32_16x16x32_bf16 v[126:129], v[170:173], v[222:225], v[126:129]
	v_mfma_f32_16x16x32_bf16 v[122:125], v[180:183], v[222:225], v[122:125]
	v_mfma_f32_16x16x32_bf16 v[118:121], v[170:173], v[230:233], v[118:121]
	v_mfma_f32_16x16x32_bf16 v[114:117], v[180:183], v[230:233], v[114:117]
	v_mfma_f32_16x16x32_bf16 v[110:113], v[170:173], v[238:241], v[110:113]
	v_mfma_f32_16x16x32_bf16 v[106:109], v[180:183], v[238:241], v[106:109]
	v_mfma_f32_16x16x32_bf16 v[134:137], v[174:177], v[218:221], v[134:137]
	v_mfma_f32_16x16x32_bf16 v[130:133], v[210:213], v[218:221], v[130:133]
	v_mfma_f32_16x16x32_bf16 v[126:129], v[174:177], v[226:229], v[126:129]
	v_mfma_f32_16x16x32_bf16 v[122:125], v[210:213], v[226:229], v[122:125]
	v_mfma_f32_16x16x32_bf16 v[118:121], v[174:177], v[234:237], v[118:121]
	v_mfma_f32_16x16x32_bf16 v[114:117], v[210:213], v[234:237], v[114:117]
	v_mfma_f32_16x16x32_bf16 v[110:113], v[174:177], v[242:245], v[110:113]
	v_mfma_f32_16x16x32_bf16 v[106:109], v[210:213], v[242:245], v[106:109]
	s_barrier
	s_setprio 0
	ds_read_b128 v[214:217], v206 offset:16384
	ds_read_b128 v[218:221], v206 offset:17408
	ds_read_b128 v[222:225], v206 offset:18432
	ds_read_b128 v[226:229], v206 offset:19456
	ds_read_b128 v[230:233], v206 offset:20480
	ds_read_b128 v[234:237], v206 offset:21504
	ds_read_b128 v[238:241], v206 offset:22528
	ds_read_b128 v[242:245], v206 offset:23552
	s_add_i32 s81, s53, s93
	s_add_u32 s98, s8, 0x80
	s_addc_u32 s99, s9, 0
	s_mov_b32 m0, s81
	s_nop 0
	global_load_lds_dwordx4 v152, s[8:9]
	s_add_i32 m0, s81, 0x2000
	s_add_u32 s82, s8, 0x80000
	s_addc_u32 s83, s9, 0
	s_add_i32 s81, s54, s93
	global_load_lds_dwordx4 v156, s[8:9]
	s_mov_b32 m0, s81
	s_nop 0
	global_load_lds_dwordx4 v152, s[82:83]
	s_add_i32 m0, s81, 0x2000
	s_nop 0
	global_load_lds_dwordx4 v156, s[82:83]
	s_add_u32 s100, s74, 0x80
	s_addc_u32 s101, s75, 0
	s_mov_b32 m0, s94
	s_nop 0
	global_load_lds_dwordx4 v150, s[74:75]
	s_mov_b32 m0, s95
	s_nop 0
	global_load_lds_dwordx4 v154, s[74:75]
	s_waitcnt vmcnt(8)
	s_waitcnt lgkmcnt(0)
	s_setprio 1
	s_barrier
	v_mfma_f32_16x16x32_bf16 v[30:33], v[78:81], v[214:217], v[30:33]
	v_mfma_f32_16x16x32_bf16 v[26:29], v[142:145], v[214:217], v[26:29]
	v_mfma_f32_16x16x32_bf16 v[22:25], v[78:81], v[222:225], v[22:25]
	v_mfma_f32_16x16x32_bf16 v[18:21], v[142:145], v[222:225], v[18:21]
	v_mfma_f32_16x16x32_bf16 v[14:17], v[78:81], v[230:233], v[14:17]
	v_mfma_f32_16x16x32_bf16 v[10:13], v[142:145], v[230:233], v[10:13]
	v_mfma_f32_16x16x32_bf16 v[6:9], v[78:81], v[238:241], v[6:9]
	v_mfma_f32_16x16x32_bf16 v[2:5], v[142:145], v[238:241], v[2:5]
	v_mfma_f32_16x16x32_bf16 v[30:33], v[138:141], v[218:221], v[30:33]
	v_mfma_f32_16x16x32_bf16 v[26:29], v[146:149], v[218:221], v[26:29]
	v_mfma_f32_16x16x32_bf16 v[22:25], v[138:141], v[226:229], v[22:25]
	v_mfma_f32_16x16x32_bf16 v[18:21], v[146:149], v[226:229], v[18:21]
	v_mfma_f32_16x16x32_bf16 v[14:17], v[138:141], v[234:237], v[14:17]
	v_mfma_f32_16x16x32_bf16 v[10:13], v[146:149], v[234:237], v[10:13]
	v_mfma_f32_16x16x32_bf16 v[6:9], v[138:141], v[242:245], v[6:9]
	v_mfma_f32_16x16x32_bf16 v[2:5], v[146:149], v[242:245], v[2:5]
	s_setprio 0
	s_setprio 1
	v_mfma_f32_16x16x32_bf16 v[98:101], v[180:183], v[214:217], v[98:101]
	v_mfma_f32_16x16x32_bf16 v[94:97], v[170:173], v[222:225], v[94:97]
	v_mfma_f32_16x16x32_bf16 v[90:93], v[180:183], v[222:225], v[90:93]
	v_mfma_f32_16x16x32_bf16 v[86:89], v[170:173], v[230:233], v[86:89]
	v_mfma_f32_16x16x32_bf16 v[82:85], v[180:183], v[230:233], v[82:85]
	v_mfma_f32_16x16x32_bf16 v[74:77], v[170:173], v[238:241], v[74:77]
	v_mfma_f32_16x16x32_bf16 v[70:73], v[180:183], v[238:241], v[70:73]
	v_mfma_f32_16x16x32_bf16 v[78:81], v[170:173], v[214:217], v[102:105]
	v_mfma_f32_16x16x32_bf16 v[98:101], v[210:213], v[218:221], v[98:101]
	v_mfma_f32_16x16x32_bf16 v[94:97], v[174:177], v[226:229], v[94:97]
	v_mfma_f32_16x16x32_bf16 v[90:93], v[210:213], v[226:229], v[90:93]
	v_mfma_f32_16x16x32_bf16 v[86:89], v[174:177], v[234:237], v[86:89]
	v_mfma_f32_16x16x32_bf16 v[82:85], v[210:213], v[234:237], v[82:85]
	v_mfma_f32_16x16x32_bf16 v[74:77], v[174:177], v[242:245], v[74:77]
	v_mfma_f32_16x16x32_bf16 v[70:73], v[210:213], v[242:245], v[70:73]
	v_mfma_f32_16x16x32_bf16 v[78:81], v[174:177], v[218:221], v[78:81]
	s_barrier
	s_setprio 0
	ds_read_b128 v[102:105], v204 offset:32768
	ds_read_b128 v[138:141], v204 offset:33792
	ds_read_b128 v[142:145], v204 offset:34816
	ds_read_b128 v[146:149], v204 offset:35840
	ds_read_b128 v[170:173], v205 offset:32768
	ds_read_b128 v[174:177], v205 offset:33792
	ds_read_b128 v[180:183], v205 offset:34816
	ds_read_b128 v[210:213], v205 offset:35840
	ds_read_b128 v[214:217], v206 offset:32768
	ds_read_b128 v[218:221], v206 offset:33792
	ds_read_b128 v[222:225], v206 offset:34816
	ds_read_b128 v[226:229], v206 offset:35840
	ds_read_b128 v[230:233], v206 offset:36864
	ds_read_b128 v[234:237], v206 offset:37888
	ds_read_b128 v[238:241], v206 offset:38912
	ds_read_b128 v[242:245], v206 offset:39936
	s_add_i32 s81, 0, 0x18000
	s_add_i32 s82, 0, 0x1c000
	s_add_u32 s74, s74, 0x80000
	s_addc_u32 s75, s75, 0
	s_mov_b32 m0, s96
	s_nop 0
	global_load_lds_dwordx4 v150, s[74:75]
	s_mov_b32 m0, s97
	s_nop 0
	global_load_lds_dwordx4 v154, s[74:75]
	s_waitcnt vmcnt(8)
	s_waitcnt lgkmcnt(0)
	s_setprio 1
	s_barrier
	v_mfma_f32_16x16x32_bf16 v[66:69], v[102:105], v[214:217], v[66:69]
	v_mfma_f32_16x16x32_bf16 v[62:65], v[142:145], v[214:217], v[62:65]
	v_mfma_f32_16x16x32_bf16 v[58:61], v[102:105], v[222:225], v[58:61]
	v_mfma_f32_16x16x32_bf16 v[54:57], v[142:145], v[222:225], v[54:57]
	v_mfma_f32_16x16x32_bf16 v[46:49], v[102:105], v[230:233], v[46:49]
	v_mfma_f32_16x16x32_bf16 v[42:45], v[142:145], v[230:233], v[42:45]
	v_mfma_f32_16x16x32_bf16 v[38:41], v[102:105], v[238:241], v[38:41]
	v_mfma_f32_16x16x32_bf16 v[34:37], v[142:145], v[238:241], v[34:37]
	v_mfma_f32_16x16x32_bf16 v[66:69], v[138:141], v[218:221], v[66:69]
	v_mfma_f32_16x16x32_bf16 v[62:65], v[146:149], v[218:221], v[62:65]
	v_mfma_f32_16x16x32_bf16 v[58:61], v[138:141], v[226:229], v[58:61]
	v_mfma_f32_16x16x32_bf16 v[54:57], v[146:149], v[226:229], v[54:57]
	v_mfma_f32_16x16x32_bf16 v[46:49], v[138:141], v[234:237], v[46:49]
	v_mfma_f32_16x16x32_bf16 v[42:45], v[146:149], v[234:237], v[42:45]
	v_mfma_f32_16x16x32_bf16 v[38:41], v[138:141], v[242:245], v[38:41]
	v_mfma_f32_16x16x32_bf16 v[34:37], v[146:149], v[242:245], v[34:37]
	s_setprio 0
	s_setprio 1
	v_mfma_f32_16x16x32_bf16 v[134:137], v[170:173], v[214:217], v[134:137]
	v_mfma_f32_16x16x32_bf16 v[130:133], v[180:183], v[214:217], v[130:133]
	v_mfma_f32_16x16x32_bf16 v[126:129], v[170:173], v[222:225], v[126:129]
	v_mfma_f32_16x16x32_bf16 v[122:125], v[180:183], v[222:225], v[122:125]
	v_mfma_f32_16x16x32_bf16 v[118:121], v[170:173], v[230:233], v[118:121]
	v_mfma_f32_16x16x32_bf16 v[114:117], v[180:183], v[230:233], v[114:117]
	v_mfma_f32_16x16x32_bf16 v[110:113], v[170:173], v[238:241], v[110:113]
	v_mfma_f32_16x16x32_bf16 v[106:109], v[180:183], v[238:241], v[106:109]
	v_mfma_f32_16x16x32_bf16 v[134:137], v[174:177], v[218:221], v[134:137]
	v_mfma_f32_16x16x32_bf16 v[130:133], v[210:213], v[218:221], v[130:133]
	v_mfma_f32_16x16x32_bf16 v[126:129], v[174:177], v[226:229], v[126:129]
	v_mfma_f32_16x16x32_bf16 v[122:125], v[210:213], v[226:229], v[122:125]
	v_mfma_f32_16x16x32_bf16 v[118:121], v[174:177], v[234:237], v[118:121]
	v_mfma_f32_16x16x32_bf16 v[114:117], v[210:213], v[234:237], v[114:117]
	v_mfma_f32_16x16x32_bf16 v[110:113], v[174:177], v[242:245], v[110:113]
	v_mfma_f32_16x16x32_bf16 v[106:109], v[210:213], v[242:245], v[106:109]
	s_barrier
	s_setprio 0
	ds_read_b128 v[214:217], v206 offset:49152
	ds_read_b128 v[218:221], v206 offset:50176
	ds_read_b128 v[222:225], v206 offset:51200
	ds_read_b128 v[226:229], v206 offset:52224
	ds_read_b128 v[230:233], v206 offset:53248
	ds_read_b128 v[234:237], v206 offset:54272
	ds_read_b128 v[238:241], v206 offset:55296
	ds_read_b128 v[242:245], v206 offset:56320
	s_add_i32 s74, s81, s93
	s_mov_b32 m0, s74
	s_nop 0
	global_load_lds_dwordx4 v152, s[98:99]
	s_add_i32 m0, s74, 0x2000
	s_add_u32 s8, s8, 0x80080
	s_addc_u32 s9, s9, 0
	s_add_i32 s74, s82, s93
	global_load_lds_dwordx4 v156, s[98:99]
	s_mov_b32 m0, s74
	s_nop 0
	global_load_lds_dwordx4 v152, s[8:9]
	s_add_i32 m0, s74, 0x2000
	s_nop 0
	global_load_lds_dwordx4 v156, s[8:9]
	s_mov_b32 m0, s85
	s_nop 0
	global_load_lds_dwordx4 v150, s[100:101]
	s_mov_b32 m0, s18
	s_nop 0
	global_load_lds_dwordx4 v154, s[100:101]
	s_add_i32 s80, s80, 2
	s_add_u32 s0, s0, 0x100
	s_addc_u32 s1, s1, 0
	s_add_u32 s78, s78, 0x100
	s_addc_u32 s79, s79, 0
	s_cmp_gt_u32 s80, 29
	s_waitcnt vmcnt(8)
	s_waitcnt lgkmcnt(0)
	s_setprio 1
	s_barrier
	v_mfma_f32_16x16x32_bf16 v[30:33], v[102:105], v[214:217], v[30:33]
	v_mfma_f32_16x16x32_bf16 v[26:29], v[142:145], v[214:217], v[26:29]
	v_mfma_f32_16x16x32_bf16 v[22:25], v[102:105], v[222:225], v[22:25]
	v_mfma_f32_16x16x32_bf16 v[18:21], v[142:145], v[222:225], v[18:21]
	v_mfma_f32_16x16x32_bf16 v[14:17], v[102:105], v[230:233], v[14:17]
	v_mfma_f32_16x16x32_bf16 v[10:13], v[142:145], v[230:233], v[10:13]
	v_mfma_f32_16x16x32_bf16 v[6:9], v[102:105], v[238:241], v[6:9]
	v_mfma_f32_16x16x32_bf16 v[2:5], v[142:145], v[238:241], v[2:5]
	v_mfma_f32_16x16x32_bf16 v[30:33], v[138:141], v[218:221], v[30:33]
	v_mfma_f32_16x16x32_bf16 v[26:29], v[146:149], v[218:221], v[26:29]
	v_mfma_f32_16x16x32_bf16 v[22:25], v[138:141], v[226:229], v[22:25]
	v_mfma_f32_16x16x32_bf16 v[18:21], v[146:149], v[226:229], v[18:21]
	v_mfma_f32_16x16x32_bf16 v[14:17], v[138:141], v[234:237], v[14:17]
	v_mfma_f32_16x16x32_bf16 v[10:13], v[146:149], v[234:237], v[10:13]
	v_mfma_f32_16x16x32_bf16 v[6:9], v[138:141], v[242:245], v[6:9]
	v_mfma_f32_16x16x32_bf16 v[2:5], v[146:149], v[242:245], v[2:5]
	s_setprio 0
	s_setprio 1
	v_mfma_f32_16x16x32_bf16 v[78:81], v[170:173], v[214:217], v[78:81]
	v_mfma_f32_16x16x32_bf16 v[102:105], v[174:177], v[218:221], v[78:81]
	v_mfma_f32_16x16x32_bf16 v[78:81], v[180:183], v[214:217], v[98:101]
	v_mfma_f32_16x16x32_bf16 v[98:101], v[210:213], v[218:221], v[78:81]
	v_mfma_f32_16x16x32_bf16 v[78:81], v[170:173], v[222:225], v[94:97]
	v_mfma_f32_16x16x32_bf16 v[94:97], v[174:177], v[226:229], v[78:81]
	v_mfma_f32_16x16x32_bf16 v[78:81], v[180:183], v[222:225], v[90:93]
	v_mfma_f32_16x16x32_bf16 v[90:93], v[210:213], v[226:229], v[78:81]
	v_mfma_f32_16x16x32_bf16 v[78:81], v[170:173], v[230:233], v[86:89]
	v_mfma_f32_16x16x32_bf16 v[86:89], v[174:177], v[234:237], v[78:81]
	v_mfma_f32_16x16x32_bf16 v[78:81], v[180:183], v[230:233], v[82:85]
	v_mfma_f32_16x16x32_bf16 v[74:77], v[170:173], v[238:241], v[74:77]
	v_mfma_f32_16x16x32_bf16 v[70:73], v[180:183], v[238:241], v[70:73]
	v_mfma_f32_16x16x32_bf16 v[82:85], v[210:213], v[234:237], v[78:81]
	v_mfma_f32_16x16x32_bf16 v[74:77], v[174:177], v[242:245], v[74:77]
	v_mfma_f32_16x16x32_bf16 v[70:73], v[210:213], v[242:245], v[70:73]
	s_barrier
	s_setprio 0
	s_cbranch_scc0 .LBB0_469
	s_and_b64 vcc, exec, s[58:59]
	s_cbranch_vccz .LBB0_472
	s_barrier

.LBB0_700:
	s_ashr_i32 s37, s36, 31
	s_lshl_b64 s[40:41], s[36:37], 20
	s_add_u32 s40, s18, s40
	s_addc_u32 s41, s19, s41
	s_and_b64 s[42:43], s[16:17], exec
	s_cselect_b32 s37, s41, s55
	s_cselect_b32 s75, s40, s54
	s_ashr_i32 s35, s34, 31
	s_lshl_b64 s[42:43], s[34:35], 20
	s_add_u32 s42, s28, s42
	s_addc_u32 s43, s29, s43
	s_and_b64 s[58:59], s[16:17], exec
	s_cselect_b32 s35, s43, s57
	s_cselect_b32 s76, s42, s56
	s_add_u32 s54, s54, 0x80080
	s_addc_u32 s55, s55, 0
	s_add_u32 s77, s56, 0x100
	s_addc_u32 s78, s57, 0
	s_mov_b32 s79, -2
	s_add_u32 s56, s54, 0xfff80080
	s_addc_u32 s57, s55, -1
	s_cmp_eq_u32 s79, 28
	s_cselect_b32 s59, s37, s57
	s_cselect_b32 s58, s75, s56
	s_cselect_b32 s57, s35, s78
	s_cselect_b32 s56, s76, s77
	s_add_i32 m0, s53, 0xc000
	s_nop 0
	global_load_lds_dwordx4 v130, s[54:55]
	s_add_i32 m0, s53, 0xe000
	s_nop 0
	global_load_lds_dwordx4 v132, s[54:55]
	s_waitcnt vmcnt(8)
	s_waitcnt lgkmcnt(0)
	s_setprio 1
	s_barrier
	v_mfma_f32_16x16x32_bf16 v[126:129], v[144:147], v[194:197], 0
	v_mfma_f32_16x16x32_bf16 v[122:125], v[162:165], v[194:197], 0
	v_mfma_f32_16x16x32_bf16 v[114:117], v[144:147], v[202:205], 0
	v_mfma_f32_16x16x32_bf16 v[106:109], v[162:165], v[202:205], 0
	v_mfma_f32_16x16x32_bf16 v[98:101], v[144:147], v[210:213], 0
	v_mfma_f32_16x16x32_bf16 v[90:93], v[162:165], v[210:213], 0
	v_mfma_f32_16x16x32_bf16 v[82:85], v[144:147], v[218:221], 0
	v_mfma_f32_16x16x32_bf16 v[74:77], v[162:165], v[218:221], 0
	v_mfma_f32_16x16x32_bf16 v[126:129], v[158:161], v[198:201], v[126:129]
	v_mfma_f32_16x16x32_bf16 v[122:125], v[166:169], v[198:201], v[122:125]
	v_mfma_f32_16x16x32_bf16 v[114:117], v[158:161], v[206:209], v[114:117]
	v_mfma_f32_16x16x32_bf16 v[106:109], v[166:169], v[206:209], v[106:109]
	v_mfma_f32_16x16x32_bf16 v[98:101], v[158:161], v[214:217], v[98:101]
	v_mfma_f32_16x16x32_bf16 v[90:93], v[166:169], v[214:217], v[90:93]
	v_mfma_f32_16x16x32_bf16 v[82:85], v[158:161], v[222:225], v[82:85]
	v_mfma_f32_16x16x32_bf16 v[74:77], v[166:169], v[222:225], v[74:77]
	s_setprio 0
	s_setprio 1
	v_mfma_f32_16x16x32_bf16 v[118:121], v[170:173], v[194:197], 0
	v_mfma_f32_16x16x32_bf16 v[110:113], v[180:183], v[194:197], 0
	v_mfma_f32_16x16x32_bf16 v[102:105], v[170:173], v[202:205], 0
	v_mfma_f32_16x16x32_bf16 v[94:97], v[180:183], v[202:205], 0
	v_mfma_f32_16x16x32_bf16 v[86:89], v[170:173], v[210:213], 0
	v_mfma_f32_16x16x32_bf16 v[78:81], v[180:183], v[210:213], 0
	v_mfma_f32_16x16x32_bf16 v[70:73], v[170:173], v[218:221], 0
	v_mfma_f32_16x16x32_bf16 v[66:69], v[180:183], v[218:221], 0
	v_mfma_f32_16x16x32_bf16 v[118:121], v[174:177], v[198:201], v[118:121]
	v_mfma_f32_16x16x32_bf16 v[110:113], v[190:193], v[198:201], v[110:113]
	v_mfma_f32_16x16x32_bf16 v[102:105], v[174:177], v[206:209], v[102:105]
	v_mfma_f32_16x16x32_bf16 v[94:97], v[190:193], v[206:209], v[94:97]
	v_mfma_f32_16x16x32_bf16 v[86:89], v[174:177], v[214:217], v[86:89]
	v_mfma_f32_16x16x32_bf16 v[78:81], v[190:193], v[214:217], v[78:81]
	v_mfma_f32_16x16x32_bf16 v[70:73], v[174:177], v[222:225], v[70:73]
	v_mfma_f32_16x16x32_bf16 v[66:69], v[190:193], v[222:225], v[66:69]
	s_barrier
	s_setprio 0
	ds_read_b128 v[194:197], v143 offset:16384
	ds_read_b128 v[198:201], v143 offset:17408
	ds_read_b128 v[202:205], v143 offset:18432
	ds_read_b128 v[206:209], v143 offset:19456
	ds_read_b128 v[210:213], v143 offset:20480
	ds_read_b128 v[214:217], v143 offset:21504
	ds_read_b128 v[218:221], v143 offset:22528
	ds_read_b128 v[222:225], v143 offset:23552
	s_add_i32 s80, s68, s60
	s_add_u32 s98, s56, 0x80
	s_addc_u32 s99, s57, 0
	s_mov_b32 m0, s80
	s_nop 0
	global_load_lds_dwordx4 v152, s[56:57]
	s_add_i32 m0, s80, 0x2000
	s_add_u32 s80, s56, 0x80000
	s_addc_u32 s81, s57, 0
	s_add_i32 s82, s69, s60
	global_load_lds_dwordx4 v156, s[56:57]
	s_mov_b32 m0, s82
	s_nop 0
	global_load_lds_dwordx4 v152, s[80:81]
	s_add_i32 m0, s82, 0x2000
	s_nop 0
	global_load_lds_dwordx4 v156, s[80:81]
	s_add_u32 s100, s58, 0x80
	s_addc_u32 s101, s59, 0
	s_mov_b32 m0, s53
	s_nop 0
	global_load_lds_dwordx4 v150, s[58:59]
	s_mov_b32 m0, s61
	s_nop 0
	global_load_lds_dwordx4 v154, s[58:59]
	s_waitcnt vmcnt(8)
	s_waitcnt lgkmcnt(0)
	s_setprio 1
	s_barrier
	v_mfma_f32_16x16x32_bf16 v[62:65], v[144:147], v[194:197], 0
	v_mfma_f32_16x16x32_bf16 v[58:61], v[162:165], v[194:197], 0
	v_mfma_f32_16x16x32_bf16 v[50:53], v[144:147], v[202:205], 0
	v_mfma_f32_16x16x32_bf16 v[42:45], v[162:165], v[202:205], 0
	v_mfma_f32_16x16x32_bf16 v[34:37], v[144:147], v[210:213], 0
	v_mfma_f32_16x16x32_bf16 v[26:29], v[162:165], v[210:213], 0
	v_mfma_f32_16x16x32_bf16 v[18:21], v[144:147], v[218:221], 0
	v_mfma_f32_16x16x32_bf16 v[10:13], v[162:165], v[218:221], 0
	v_mfma_f32_16x16x32_bf16 v[62:65], v[158:161], v[198:201], v[62:65]
	v_mfma_f32_16x16x32_bf16 v[58:61], v[166:169], v[198:201], v[58:61]
	v_mfma_f32_16x16x32_bf16 v[50:53], v[158:161], v[206:209], v[50:53]
	v_mfma_f32_16x16x32_bf16 v[42:45], v[166:169], v[206:209], v[42:45]
	v_mfma_f32_16x16x32_bf16 v[34:37], v[158:161], v[214:217], v[34:37]
	v_mfma_f32_16x16x32_bf16 v[26:29], v[166:169], v[214:217], v[26:29]
	v_mfma_f32_16x16x32_bf16 v[18:21], v[158:161], v[222:225], v[18:21]
	v_mfma_f32_16x16x32_bf16 v[10:13], v[166:169], v[222:225], v[10:13]
	s_setprio 0
	s_setprio 1
	v_mfma_f32_16x16x32_bf16 v[54:57], v[170:173], v[194:197], 0
	v_mfma_f32_16x16x32_bf16 v[46:49], v[180:183], v[194:197], 0
	v_mfma_f32_16x16x32_bf16 v[38:41], v[170:173], v[202:205], 0
	v_mfma_f32_16x16x32_bf16 v[30:33], v[180:183], v[202:205], 0
	v_mfma_f32_16x16x32_bf16 v[22:25], v[170:173], v[210:213], 0
	v_mfma_f32_16x16x32_bf16 v[14:17], v[180:183], v[210:213], 0
	v_mfma_f32_16x16x32_bf16 v[6:9], v[170:173], v[218:221], 0
	v_mfma_f32_16x16x32_bf16 v[2:5], v[180:183], v[218:221], 0
	v_mfma_f32_16x16x32_bf16 v[54:57], v[174:177], v[198:201], v[54:57]
	v_mfma_f32_16x16x32_bf16 v[46:49], v[190:193], v[198:201], v[46:49]
	v_mfma_f32_16x16x32_bf16 v[38:41], v[174:177], v[206:209], v[38:41]
	v_mfma_f32_16x16x32_bf16 v[30:33], v[190:193], v[206:209], v[30:33]
	v_mfma_f32_16x16x32_bf16 v[22:25], v[174:177], v[214:217], v[22:25]
	v_mfma_f32_16x16x32_bf16 v[14:17], v[190:193], v[214:217], v[14:17]
	v_mfma_f32_16x16x32_bf16 v[6:9], v[174:177], v[222:225], v[6:9]
	v_mfma_f32_16x16x32_bf16 v[2:5], v[190:193], v[222:225], v[2:5]
	s_barrier
	s_setprio 0
	ds_read_b128 v[144:147], v141 offset:32768
	ds_read_b128 v[158:161], v141 offset:33792
	ds_read_b128 v[162:165], v141 offset:34816
	ds_read_b128 v[166:169], v141 offset:35840
	ds_read_b128 v[170:173], v142 offset:32768
	ds_read_b128 v[174:177], v142 offset:33792
	ds_read_b128 v[180:183], v142 offset:34816
	ds_read_b128 v[190:193], v142 offset:35840
	ds_read_b128 v[194:197], v143 offset:32768
	ds_read_b128 v[198:201], v143 offset:33792
	ds_read_b128 v[202:205], v143 offset:34816
	ds_read_b128 v[206:209], v143 offset:35840
	ds_read_b128 v[210:213], v143 offset:36864
	ds_read_b128 v[214:217], v143 offset:37888
	ds_read_b128 v[218:221], v143 offset:38912
	ds_read_b128 v[222:225], v143 offset:39936
	s_add_i32 s80, 0, 0x18000
	s_add_i32 s81, 0, 0x1c000
	s_add_u32 s58, s58, 0x80000
	s_addc_u32 s59, s59, 0
	s_mov_b32 m0, s62
	s_nop 0
	global_load_lds_dwordx4 v150, s[58:59]
	s_mov_b32 m0, s63
	s_nop 0
	global_load_lds_dwordx4 v154, s[58:59]
	s_waitcnt vmcnt(8)
	s_waitcnt lgkmcnt(0)
	s_setprio 1
	s_barrier
	v_mfma_f32_16x16x32_bf16 v[126:129], v[144:147], v[194:197], v[126:129]
	v_mfma_f32_16x16x32_bf16 v[122:125], v[162:165], v[194:197], v[122:125]
	v_mfma_f32_16x16x32_bf16 v[114:117], v[144:147], v[202:205], v[114:117]
	v_mfma_f32_16x16x32_bf16 v[106:109], v[162:165], v[202:205], v[106:109]
	v_mfma_f32_16x16x32_bf16 v[98:101], v[144:147], v[210:213], v[98:101]
	v_mfma_f32_16x16x32_bf16 v[90:93], v[162:165], v[210:213], v[90:93]
	v_mfma_f32_16x16x32_bf16 v[82:85], v[144:147], v[218:221], v[82:85]
	v_mfma_f32_16x16x32_bf16 v[74:77], v[162:165], v[218:221], v[74:77]
	v_mfma_f32_16x16x32_bf16 v[126:129], v[158:161], v[198:201], v[126:129]
	v_mfma_f32_16x16x32_bf16 v[122:125], v[166:169], v[198:201], v[122:125]
	v_mfma_f32_16x16x32_bf16 v[114:117], v[158:161], v[206:209], v[114:117]
	v_mfma_f32_16x16x32_bf16 v[106:109], v[166:169], v[206:209], v[106:109]
	v_mfma_f32_16x16x32_bf16 v[98:101], v[158:161], v[214:217], v[98:101]
	v_mfma_f32_16x16x32_bf16 v[90:93], v[166:169], v[214:217], v[90:93]
	v_mfma_f32_16x16x32_bf16 v[82:85], v[158:161], v[222:225], v[82:85]
	v_mfma_f32_16x16x32_bf16 v[74:77], v[166:169], v[222:225], v[74:77]
	s_setprio 0
	s_setprio 1
	v_mfma_f32_16x16x32_bf16 v[118:121], v[170:173], v[194:197], v[118:121]
	v_mfma_f32_16x16x32_bf16 v[110:113], v[180:183], v[194:197], v[110:113]
	v_mfma_f32_16x16x32_bf16 v[102:105], v[170:173], v[202:205], v[102:105]
	v_mfma_f32_16x16x32_bf16 v[94:97], v[180:183], v[202:205], v[94:97]
	v_mfma_f32_16x16x32_bf16 v[86:89], v[170:173], v[210:213], v[86:89]
	v_mfma_f32_16x16x32_bf16 v[78:81], v[180:183], v[210:213], v[78:81]
	v_mfma_f32_16x16x32_bf16 v[70:73], v[170:173], v[218:221], v[70:73]
	v_mfma_f32_16x16x32_bf16 v[66:69], v[180:183], v[218:221], v[66:69]
	v_mfma_f32_16x16x32_bf16 v[118:121], v[174:177], v[198:201], v[118:121]
	v_mfma_f32_16x16x32_bf16 v[110:113], v[190:193], v[198:201], v[110:113]
	v_mfma_f32_16x16x32_bf16 v[102:105], v[174:177], v[206:209], v[102:105]
	v_mfma_f32_16x16x32_bf16 v[94:97], v[190:193], v[206:209], v[94:97]
	v_mfma_f32_16x16x32_bf16 v[86:89], v[174:177], v[214:217], v[86:89]
	v_mfma_f32_16x16x32_bf16 v[78:81], v[190:193], v[214:217], v[78:81]
	v_mfma_f32_16x16x32_bf16 v[70:73], v[174:177], v[222:225], v[70:73]
	v_mfma_f32_16x16x32_bf16 v[66:69], v[190:193], v[222:225], v[66:69]
	s_barrier
	s_setprio 0
	ds_read_b128 v[194:197], v143 offset:49152
	ds_read_b128 v[198:201], v143 offset:50176
	ds_read_b128 v[202:205], v143 offset:51200
	ds_read_b128 v[206:209], v143 offset:52224
	ds_read_b128 v[210:213], v143 offset:53248
	ds_read_b128 v[214:217], v143 offset:54272
	ds_read_b128 v[218:221], v143 offset:55296
	ds_read_b128 v[222:225], v143 offset:56320
	s_add_i32 s58, s80, s60
	s_mov_b32 m0, s58
	s_nop 0
	global_load_lds_dwordx4 v152, s[98:99]
	s_add_i32 m0, s58, 0x2000
	s_add_u32 s56, s56, 0x80080
	s_addc_u32 s57, s57, 0
	s_add_i32 s58, s81, s60
	global_load_lds_dwordx4 v156, s[98:99]
	s_mov_b32 m0, s58
	s_nop 0
	global_load_lds_dwordx4 v152, s[56:57]
	s_add_i32 m0, s58, 0x2000
	s_nop 0
	global_load_lds_dwordx4 v156, s[56:57]
	s_mov_b32 m0, s65
	s_nop 0
	global_load_lds_dwordx4 v150, s[100:101]
	s_mov_b32 m0, s66
	s_nop 0
	global_load_lds_dwordx4 v154, s[100:101]
	s_waitcnt vmcnt(8)
	s_waitcnt lgkmcnt(0)
	s_setprio 1
	s_barrier
	v_mfma_f32_16x16x32_bf16 v[62:65], v[144:147], v[194:197], v[62:65]
	v_mfma_f32_16x16x32_bf16 v[58:61], v[162:165], v[194:197], v[58:61]
	v_mfma_f32_16x16x32_bf16 v[50:53], v[144:147], v[202:205], v[50:53]
	v_mfma_f32_16x16x32_bf16 v[42:45], v[162:165], v[202:205], v[42:45]
	v_mfma_f32_16x16x32_bf16 v[34:37], v[144:147], v[210:213], v[34:37]
	v_mfma_f32_16x16x32_bf16 v[26:29], v[162:165], v[210:213], v[26:29]
	v_mfma_f32_16x16x32_bf16 v[18:21], v[144:147], v[218:221], v[18:21]
	v_mfma_f32_16x16x32_bf16 v[10:13], v[162:165], v[218:221], v[10:13]
	v_mfma_f32_16x16x32_bf16 v[62:65], v[158:161], v[198:201], v[62:65]
	v_mfma_f32_16x16x32_bf16 v[58:61], v[166:169], v[198:201], v[58:61]
	v_mfma_f32_16x16x32_bf16 v[50:53], v[158:161], v[206:209], v[50:53]
	v_mfma_f32_16x16x32_bf16 v[42:45], v[166:169], v[206:209], v[42:45]
	v_mfma_f32_16x16x32_bf16 v[34:37], v[158:161], v[214:217], v[34:37]
	v_mfma_f32_16x16x32_bf16 v[26:29], v[166:169], v[214:217], v[26:29]
	v_mfma_f32_16x16x32_bf16 v[18:21], v[158:161], v[222:225], v[18:21]
	v_mfma_f32_16x16x32_bf16 v[10:13], v[166:169], v[222:225], v[10:13]
	s_setprio 0
	s_setprio 1
	v_mfma_f32_16x16x32_bf16 v[54:57], v[170:173], v[194:197], v[54:57]
	v_mfma_f32_16x16x32_bf16 v[46:49], v[180:183], v[194:197], v[46:49]
	v_mfma_f32_16x16x32_bf16 v[38:41], v[170:173], v[202:205], v[38:41]
	v_mfma_f32_16x16x32_bf16 v[30:33], v[180:183], v[202:205], v[30:33]
	v_mfma_f32_16x16x32_bf16 v[22:25], v[170:173], v[210:213], v[22:25]
	v_mfma_f32_16x16x32_bf16 v[14:17], v[180:183], v[210:213], v[14:17]
	v_mfma_f32_16x16x32_bf16 v[6:9], v[170:173], v[218:221], v[6:9]
	v_mfma_f32_16x16x32_bf16 v[2:5], v[180:183], v[218:221], v[2:5]
	v_mfma_f32_16x16x32_bf16 v[54:57], v[174:177], v[198:201], v[54:57]
	v_mfma_f32_16x16x32_bf16 v[46:49], v[190:193], v[198:201], v[46:49]
	v_mfma_f32_16x16x32_bf16 v[38:41], v[174:177], v[206:209], v[38:41]
	v_mfma_f32_16x16x32_bf16 v[30:33], v[190:193], v[206:209], v[30:33]
	v_mfma_f32_16x16x32_bf16 v[22:25], v[174:177], v[214:217], v[22:25]
	v_mfma_f32_16x16x32_bf16 v[14:17], v[190:193], v[214:217], v[14:17]
	v_mfma_f32_16x16x32_bf16 v[6:9], v[174:177], v[222:225], v[6:9]
	v_mfma_f32_16x16x32_bf16 v[2:5], v[190:193], v[222:225], v[2:5]
	s_barrier
	s_setprio 0
	s_add_i32 s79, s79, 2
	s_add_u32 s54, s54, 0x100
	s_addc_u32 s55, s55, 0
	s_add_u32 s77, s77, 0x100
	s_addc_u32 s78, s78, 0
	s_cmp_gt_u32 s79, 29
.LBB0_701:
	ds_read_b128 v[144:147], v141
	ds_read_b128 v[158:161], v141 offset:1024
	ds_read_b128 v[162:165], v141 offset:2048
	ds_read_b128 v[166:169], v141 offset:3072
	ds_read_b128 v[170:173], v142
	ds_read_b128 v[174:177], v142 offset:1024
	ds_read_b128 v[180:183], v142 offset:2048
	ds_read_b128 v[190:193], v142 offset:3072
	ds_read_b128 v[194:197], v143
	ds_read_b128 v[198:201], v143 offset:1024
	ds_read_b128 v[202:205], v143 offset:2048
	ds_read_b128 v[206:209], v143 offset:3072
	ds_read_b128 v[210:213], v143 offset:4096
	ds_read_b128 v[214:217], v143 offset:5120
	ds_read_b128 v[218:221], v143 offset:6144
	ds_read_b128 v[222:225], v143 offset:7168
	s_add_u32 s56, s54, 0xfff80080
	s_addc_u32 s57, s55, -1
	s_cmp_eq_u32 s79, 28
	s_cselect_b32 s59, s37, s57
	s_cselect_b32 s58, s75, s56
	s_cselect_b32 s57, s35, s78
	s_cselect_b32 s56, s76, s77
	s_add_i32 m0, s53, 0xc000
	s_nop 0
	global_load_lds_dwordx4 v130, s[54:55]
	s_add_i32 m0, s53, 0xe000
	s_nop 0
	global_load_lds_dwordx4 v132, s[54:55]
	s_waitcnt vmcnt(8)
	s_waitcnt lgkmcnt(0)
	s_setprio 1
	s_barrier
	v_mfma_f32_16x16x32_bf16 v[126:129], v[144:147], v[194:197], v[126:129]
	v_mfma_f32_16x16x32_bf16 v[122:125], v[162:165], v[194:197], v[122:125]
	v_mfma_f32_16x16x32_bf16 v[114:117], v[144:147], v[202:205], v[114:117]
	v_mfma_f32_16x16x32_bf16 v[106:109], v[162:165], v[202:205], v[106:109]
	v_mfma_f32_16x16x32_bf16 v[98:101], v[144:147], v[210:213], v[98:101]
	v_mfma_f32_16x16x32_bf16 v[90:93], v[162:165], v[210:213], v[90:93]
	v_mfma_f32_16x16x32_bf16 v[82:85], v[144:147], v[218:221], v[82:85]
	v_mfma_f32_16x16x32_bf16 v[74:77], v[162:165], v[218:221], v[74:77]
	v_mfma_f32_16x16x32_bf16 v[126:129], v[158:161], v[198:201], v[126:129]
	v_mfma_f32_16x16x32_bf16 v[122:125], v[166:169], v[198:201], v[122:125]
	v_mfma_f32_16x16x32_bf16 v[114:117], v[158:161], v[206:209], v[114:117]
	v_mfma_f32_16x16x32_bf16 v[106:109], v[166:169], v[206:209], v[106:109]
	v_mfma_f32_16x16x32_bf16 v[98:101], v[158:161], v[214:217], v[98:101]
	v_mfma_f32_16x16x32_bf16 v[90:93], v[166:169], v[214:217], v[90:93]
	v_mfma_f32_16x16x32_bf16 v[82:85], v[158:161], v[222:225], v[82:85]
	v_mfma_f32_16x16x32_bf16 v[74:77], v[166:169], v[222:225], v[74:77]
	s_setprio 0
	s_setprio 1
	v_mfma_f32_16x16x32_bf16 v[118:121], v[170:173], v[194:197], v[118:121]
	v_mfma_f32_16x16x32_bf16 v[110:113], v[180:183], v[194:197], v[110:113]
	v_mfma_f32_16x16x32_bf16 v[102:105], v[170:173], v[202:205], v[102:105]
	v_mfma_f32_16x16x32_bf16 v[94:97], v[180:183], v[202:205], v[94:97]
	v_mfma_f32_16x16x32_bf16 v[86:89], v[170:173], v[210:213], v[86:89]
	v_mfma_f32_16x16x32_bf16 v[78:81], v[180:183], v[210:213], v[78:81]
	v_mfma_f32_16x16x32_bf16 v[70:73], v[170:173], v[218:221], v[70:73]
	v_mfma_f32_16x16x32_bf16 v[66:69], v[180:183], v[218:221], v[66:69]
	v_mfma_f32_16x16x32_bf16 v[118:121], v[174:177], v[198:201], v[118:121]
	v_mfma_f32_16x16x32_bf16 v[110:113], v[190:193], v[198:201], v[110:113]
	v_mfma_f32_16x16x32_bf16 v[102:105], v[174:177], v[206:209], v[102:105]
	v_mfma_f32_16x16x32_bf16 v[94:97], v[190:193], v[206:209], v[94:97]
	v_mfma_f32_16x16x32_bf16 v[86:89], v[174:177], v[214:217], v[86:89]
	v_mfma_f32_16x16x32_bf16 v[78:81], v[190:193], v[214:217], v[78:81]
	v_mfma_f32_16x16x32_bf16 v[70:73], v[174:177], v[222:225], v[70:73]
	v_mfma_f32_16x16x32_bf16 v[66:69], v[190:193], v[222:225], v[66:69]
	s_barrier
	s_setprio 0
	ds_read_b128 v[194:197], v143 offset:16384
	ds_read_b128 v[198:201], v143 offset:17408
	ds_read_b128 v[202:205], v143 offset:18432
	ds_read_b128 v[206:209], v143 offset:19456
	ds_read_b128 v[210:213], v143 offset:20480
	ds_read_b128 v[214:217], v143 offset:21504
	ds_read_b128 v[218:221], v143 offset:22528
	ds_read_b128 v[222:225], v143 offset:23552
	s_add_i32 s80, s68, s60
	s_add_u32 s98, s56, 0x80
	s_addc_u32 s99, s57, 0
	s_mov_b32 m0, s80
	s_nop 0
	global_load_lds_dwordx4 v152, s[56:57]
	s_add_i32 m0, s80, 0x2000
	s_add_u32 s80, s56, 0x80000
	s_addc_u32 s81, s57, 0
	s_add_i32 s82, s69, s60
	global_load_lds_dwordx4 v156, s[56:57]
	s_mov_b32 m0, s82
	s_nop 0
	global_load_lds_dwordx4 v152, s[80:81]
	s_add_i32 m0, s82, 0x2000
	s_nop 0
	global_load_lds_dwordx4 v156, s[80:81]
	s_add_u32 s100, s58, 0x80
	s_addc_u32 s101, s59, 0
	s_mov_b32 m0, s53
	s_nop 0
	global_load_lds_dwordx4 v150, s[58:59]
	s_mov_b32 m0, s61
	s_nop 0
	global_load_lds_dwordx4 v154, s[58:59]
	s_waitcnt vmcnt(8)
	s_waitcnt lgkmcnt(0)
	s_setprio 1
	s_barrier
	v_mfma_f32_16x16x32_bf16 v[62:65], v[144:147], v[194:197], v[62:65]
	v_mfma_f32_16x16x32_bf16 v[58:61], v[162:165], v[194:197], v[58:61]
	v_mfma_f32_16x16x32_bf16 v[50:53], v[144:147], v[202:205], v[50:53]
	v_mfma_f32_16x16x32_bf16 v[42:45], v[162:165], v[202:205], v[42:45]
	v_mfma_f32_16x16x32_bf16 v[34:37], v[144:147], v[210:213], v[34:37]
	v_mfma_f32_16x16x32_bf16 v[26:29], v[162:165], v[210:213], v[26:29]
	v_mfma_f32_16x16x32_bf16 v[18:21], v[144:147], v[218:221], v[18:21]
	v_mfma_f32_16x16x32_bf16 v[10:13], v[162:165], v[218:221], v[10:13]
	v_mfma_f32_16x16x32_bf16 v[62:65], v[158:161], v[198:201], v[62:65]
	v_mfma_f32_16x16x32_bf16 v[58:61], v[166:169], v[198:201], v[58:61]
	v_mfma_f32_16x16x32_bf16 v[50:53], v[158:161], v[206:209], v[50:53]
	v_mfma_f32_16x16x32_bf16 v[42:45], v[166:169], v[206:209], v[42:45]
	v_mfma_f32_16x16x32_bf16 v[34:37], v[158:161], v[214:217], v[34:37]
	v_mfma_f32_16x16x32_bf16 v[26:29], v[166:169], v[214:217], v[26:29]
	v_mfma_f32_16x16x32_bf16 v[18:21], v[158:161], v[222:225], v[18:21]
	v_mfma_f32_16x16x32_bf16 v[10:13], v[166:169], v[222:225], v[10:13]
	s_setprio 0
	s_setprio 1
	v_mfma_f32_16x16x32_bf16 v[54:57], v[170:173], v[194:197], v[54:57]
	v_mfma_f32_16x16x32_bf16 v[46:49], v[180:183], v[194:197], v[46:49]
	v_mfma_f32_16x16x32_bf16 v[38:41], v[170:173], v[202:205], v[38:41]
	v_mfma_f32_16x16x32_bf16 v[30:33], v[180:183], v[202:205], v[30:33]
	v_mfma_f32_16x16x32_bf16 v[22:25], v[170:173], v[210:213], v[22:25]
	v_mfma_f32_16x16x32_bf16 v[14:17], v[180:183], v[210:213], v[14:17]
	v_mfma_f32_16x16x32_bf16 v[6:9], v[170:173], v[218:221], v[6:9]
	v_mfma_f32_16x16x32_bf16 v[2:5], v[180:183], v[218:221], v[2:5]
	v_mfma_f32_16x16x32_bf16 v[54:57], v[174:177], v[198:201], v[54:57]
	v_mfma_f32_16x16x32_bf16 v[46:49], v[190:193], v[198:201], v[46:49]
	v_mfma_f32_16x16x32_bf16 v[38:41], v[174:177], v[206:209], v[38:41]
	v_mfma_f32_16x16x32_bf16 v[30:33], v[190:193], v[206:209], v[30:33]
	v_mfma_f32_16x16x32_bf16 v[22:25], v[174:177], v[214:217], v[22:25]
	v_mfma_f32_16x16x32_bf16 v[14:17], v[190:193], v[214:217], v[14:17]
	v_mfma_f32_16x16x32_bf16 v[6:9], v[174:177], v[222:225], v[6:9]
	v_mfma_f32_16x16x32_bf16 v[2:5], v[190:193], v[222:225], v[2:5]
	s_barrier
	s_setprio 0
	ds_read_b128 v[144:147], v141 offset:32768
	ds_read_b128 v[158:161], v141 offset:33792
	ds_read_b128 v[162:165], v141 offset:34816
	ds_read_b128 v[166:169], v141 offset:35840
	ds_read_b128 v[170:173], v142 offset:32768
	ds_read_b128 v[174:177], v142 offset:33792
	ds_read_b128 v[180:183], v142 offset:34816
	ds_read_b128 v[190:193], v142 offset:35840
	ds_read_b128 v[194:197], v143 offset:32768
	ds_read_b128 v[198:201], v143 offset:33792
	ds_read_b128 v[202:205], v143 offset:34816
	ds_read_b128 v[206:209], v143 offset:35840
	ds_read_b128 v[210:213], v143 offset:36864
	ds_read_b128 v[214:217], v143 offset:37888
	ds_read_b128 v[218:221], v143 offset:38912
	ds_read_b128 v[222:225], v143 offset:39936
	s_add_i32 s80, 0, 0x18000
	s_add_i32 s81, 0, 0x1c000
	s_add_u32 s58, s58, 0x80000
	s_addc_u32 s59, s59, 0
	s_mov_b32 m0, s62
	s_nop 0
	global_load_lds_dwordx4 v150, s[58:59]
	s_mov_b32 m0, s63
	s_nop 0
	global_load_lds_dwordx4 v154, s[58:59]
	s_waitcnt vmcnt(8)
	s_waitcnt lgkmcnt(0)
	s_setprio 1
	s_barrier
	v_mfma_f32_16x16x32_bf16 v[126:129], v[144:147], v[194:197], v[126:129]
	v_mfma_f32_16x16x32_bf16 v[122:125], v[162:165], v[194:197], v[122:125]
	v_mfma_f32_16x16x32_bf16 v[114:117], v[144:147], v[202:205], v[114:117]
	v_mfma_f32_16x16x32_bf16 v[106:109], v[162:165], v[202:205], v[106:109]
	v_mfma_f32_16x16x32_bf16 v[98:101], v[144:147], v[210:213], v[98:101]
	v_mfma_f32_16x16x32_bf16 v[90:93], v[162:165], v[210:213], v[90:93]
	v_mfma_f32_16x16x32_bf16 v[82:85], v[144:147], v[218:221], v[82:85]
	v_mfma_f32_16x16x32_bf16 v[74:77], v[162:165], v[218:221], v[74:77]
	v_mfma_f32_16x16x32_bf16 v[126:129], v[158:161], v[198:201], v[126:129]
	v_mfma_f32_16x16x32_bf16 v[122:125], v[166:169], v[198:201], v[122:125]
	v_mfma_f32_16x16x32_bf16 v[114:117], v[158:161], v[206:209], v[114:117]
	v_mfma_f32_16x16x32_bf16 v[106:109], v[166:169], v[206:209], v[106:109]
	v_mfma_f32_16x16x32_bf16 v[98:101], v[158:161], v[214:217], v[98:101]
	v_mfma_f32_16x16x32_bf16 v[90:93], v[166:169], v[214:217], v[90:93]
	v_mfma_f32_16x16x32_bf16 v[82:85], v[158:161], v[222:225], v[82:85]
	v_mfma_f32_16x16x32_bf16 v[74:77], v[166:169], v[222:225], v[74:77]
	s_setprio 0
	s_setprio 1
	v_mfma_f32_16x16x32_bf16 v[118:121], v[170:173], v[194:197], v[118:121]
	v_mfma_f32_16x16x32_bf16 v[110:113], v[180:183], v[194:197], v[110:113]
	v_mfma_f32_16x16x32_bf16 v[102:105], v[170:173], v[202:205], v[102:105]
	v_mfma_f32_16x16x32_bf16 v[94:97], v[180:183], v[202:205], v[94:97]
	v_mfma_f32_16x16x32_bf16 v[86:89], v[170:173], v[210:213], v[86:89]
	v_mfma_f32_16x16x32_bf16 v[78:81], v[180:183], v[210:213], v[78:81]
	v_mfma_f32_16x16x32_bf16 v[70:73], v[170:173], v[218:221], v[70:73]
	v_mfma_f32_16x16x32_bf16 v[66:69], v[180:183], v[218:221], v[66:69]
	v_mfma_f32_16x16x32_bf16 v[118:121], v[174:177], v[198:201], v[118:121]
	v_mfma_f32_16x16x32_bf16 v[110:113], v[190:193], v[198:201], v[110:113]
	v_mfma_f32_16x16x32_bf16 v[102:105], v[174:177], v[206:209], v[102:105]
	v_mfma_f32_16x16x32_bf16 v[94:97], v[190:193], v[206:209], v[94:97]
	v_mfma_f32_16x16x32_bf16 v[86:89], v[174:177], v[214:217], v[86:89]
	v_mfma_f32_16x16x32_bf16 v[78:81], v[190:193], v[214:217], v[78:81]
	v_mfma_f32_16x16x32_bf16 v[70:73], v[174:177], v[222:225], v[70:73]
	v_mfma_f32_16x16x32_bf16 v[66:69], v[190:193], v[222:225], v[66:69]
	s_barrier
	s_setprio 0
	ds_read_b128 v[194:197], v143 offset:49152
	ds_read_b128 v[198:201], v143 offset:50176
	ds_read_b128 v[202:205], v143 offset:51200
	ds_read_b128 v[206:209], v143 offset:52224
	ds_read_b128 v[210:213], v143 offset:53248
	ds_read_b128 v[214:217], v143 offset:54272
	ds_read_b128 v[218:221], v143 offset:55296
	ds_read_b128 v[222:225], v143 offset:56320
	s_add_i32 s58, s80, s60
	s_mov_b32 m0, s58
	s_nop 0
	global_load_lds_dwordx4 v152, s[98:99]
	s_add_i32 m0, s58, 0x2000
	s_add_u32 s56, s56, 0x80080
	s_addc_u32 s57, s57, 0
	s_add_i32 s58, s81, s60
	global_load_lds_dwordx4 v156, s[98:99]
	s_mov_b32 m0, s58
	s_nop 0
	global_load_lds_dwordx4 v152, s[56:57]
	s_add_i32 m0, s58, 0x2000
	s_nop 0
	global_load_lds_dwordx4 v156, s[56:57]
	s_mov_b32 m0, s65
	s_nop 0
	global_load_lds_dwordx4 v150, s[100:101]
	s_mov_b32 m0, s66
	s_nop 0
	global_load_lds_dwordx4 v154, s[100:101]
	s_add_i32 s79, s79, 2
	s_add_u32 s54, s54, 0x100
	s_addc_u32 s55, s55, 0
	s_add_u32 s77, s77, 0x100
	s_addc_u32 s78, s78, 0
	s_cmp_gt_u32 s79, 29
	s_waitcnt vmcnt(8)
	s_waitcnt lgkmcnt(0)
	s_setprio 1
	s_barrier
	v_mfma_f32_16x16x32_bf16 v[62:65], v[144:147], v[194:197], v[62:65]
	v_mfma_f32_16x16x32_bf16 v[58:61], v[162:165], v[194:197], v[58:61]
	v_mfma_f32_16x16x32_bf16 v[50:53], v[144:147], v[202:205], v[50:53]
	v_mfma_f32_16x16x32_bf16 v[42:45], v[162:165], v[202:205], v[42:45]
	v_mfma_f32_16x16x32_bf16 v[34:37], v[144:147], v[210:213], v[34:37]
	v_mfma_f32_16x16x32_bf16 v[26:29], v[162:165], v[210:213], v[26:29]
	v_mfma_f32_16x16x32_bf16 v[18:21], v[144:147], v[218:221], v[18:21]
	v_mfma_f32_16x16x32_bf16 v[10:13], v[162:165], v[218:221], v[10:13]
	v_mfma_f32_16x16x32_bf16 v[62:65], v[158:161], v[198:201], v[62:65]
	v_mfma_f32_16x16x32_bf16 v[58:61], v[166:169], v[198:201], v[58:61]
	v_mfma_f32_16x16x32_bf16 v[50:53], v[158:161], v[206:209], v[50:53]
	v_mfma_f32_16x16x32_bf16 v[42:45], v[166:169], v[206:209], v[42:45]
	v_mfma_f32_16x16x32_bf16 v[34:37], v[158:161], v[214:217], v[34:37]
	v_mfma_f32_16x16x32_bf16 v[26:29], v[166:169], v[214:217], v[26:29]
	v_mfma_f32_16x16x32_bf16 v[18:21], v[158:161], v[222:225], v[18:21]
	v_mfma_f32_16x16x32_bf16 v[10:13], v[166:169], v[222:225], v[10:13]
	s_setprio 0
	s_setprio 1
	v_mfma_f32_16x16x32_bf16 v[54:57], v[170:173], v[194:197], v[54:57]
	v_mfma_f32_16x16x32_bf16 v[46:49], v[180:183], v[194:197], v[46:49]
	v_mfma_f32_16x16x32_bf16 v[38:41], v[170:173], v[202:205], v[38:41]
	v_mfma_f32_16x16x32_bf16 v[30:33], v[180:183], v[202:205], v[30:33]
	v_mfma_f32_16x16x32_bf16 v[22:25], v[170:173], v[210:213], v[22:25]
	v_mfma_f32_16x16x32_bf16 v[14:17], v[180:183], v[210:213], v[14:17]
	v_mfma_f32_16x16x32_bf16 v[6:9], v[170:173], v[218:221], v[6:9]
	v_mfma_f32_16x16x32_bf16 v[2:5], v[180:183], v[218:221], v[2:5]
	v_mfma_f32_16x16x32_bf16 v[54:57], v[174:177], v[198:201], v[54:57]
	v_mfma_f32_16x16x32_bf16 v[46:49], v[190:193], v[198:201], v[46:49]
	v_mfma_f32_16x16x32_bf16 v[38:41], v[174:177], v[206:209], v[38:41]
	v_mfma_f32_16x16x32_bf16 v[30:33], v[190:193], v[206:209], v[30:33]
	v_mfma_f32_16x16x32_bf16 v[22:25], v[174:177], v[214:217], v[22:25]
	v_mfma_f32_16x16x32_bf16 v[14:17], v[190:193], v[214:217], v[14:17]
	v_mfma_f32_16x16x32_bf16 v[6:9], v[174:177], v[222:225], v[6:9]
	v_mfma_f32_16x16x32_bf16 v[2:5], v[190:193], v[222:225], v[2:5]
	s_barrier
	s_setprio 0
	s_cbranch_scc0 .LBB0_701
	s_and_b64 vcc, exec, s[6:7]
	s_cbranch_vccz .LBB0_704
	s_barrier

.LBB0_724:
	s_ashr_i32 s37, s36, 31
	s_lshl_b64 s[40:41], s[36:37], 20
	s_add_u32 s40, s31, s40
	s_addc_u32 s41, s60, s41
	s_and_b64 s[42:43], s[16:17], exec
	s_cselect_b32 s37, s41, s55
	s_cselect_b32 s76, s40, s54
	s_ashr_i32 s35, s34, 31
	s_lshl_b64 s[42:43], s[34:35], 20
	s_add_u32 s42, s18, s42
	s_addc_u32 s43, s19, s43
	s_and_b64 s[58:59], s[16:17], exec
	s_cselect_b32 s35, s43, s57
	s_cselect_b32 s77, s42, s56
	s_add_u32 s54, s54, 0x80080
	s_addc_u32 s55, s55, 0
	s_add_u32 s78, s56, 0x100
	s_addc_u32 s79, s57, 0
	s_mov_b32 s80, -2
	s_add_u32 s56, s54, 0xfff80080
	s_addc_u32 s57, s55, -1
	s_cmp_eq_u32 s80, 28
	s_cselect_b32 s59, s37, s57
	s_cselect_b32 s58, s76, s56
	s_cselect_b32 s57, s35, s79
	s_cselect_b32 s56, s77, s78
	s_add_i32 m0, s53, 0xc000
	s_nop 0
	global_load_lds_dwordx4 v130, s[54:55]
	s_add_i32 m0, s53, 0xe000
	s_nop 0
	global_load_lds_dwordx4 v132, s[54:55]
	s_waitcnt vmcnt(8)
	s_waitcnt lgkmcnt(0)
	s_setprio 1
	s_barrier
	v_mfma_f32_16x16x32_bf16 v[126:129], v[142:145], v[184:187], 0
	v_mfma_f32_16x16x32_bf16 v[122:125], v[158:161], v[184:187], 0
	v_mfma_f32_16x16x32_bf16 v[114:117], v[142:145], v[192:195], 0
	v_mfma_f32_16x16x32_bf16 v[106:109], v[158:161], v[192:195], 0
	v_mfma_f32_16x16x32_bf16 v[98:101], v[142:145], v[200:203], 0
	v_mfma_f32_16x16x32_bf16 v[90:93], v[158:161], v[200:203], 0
	v_mfma_f32_16x16x32_bf16 v[82:85], v[142:145], v[208:211], 0
	v_mfma_f32_16x16x32_bf16 v[74:77], v[158:161], v[208:211], 0
	v_mfma_f32_16x16x32_bf16 v[126:129], v[146:149], v[188:191], v[126:129]
	v_mfma_f32_16x16x32_bf16 v[122:125], v[162:165], v[188:191], v[122:125]
	v_mfma_f32_16x16x32_bf16 v[114:117], v[146:149], v[196:199], v[114:117]
	v_mfma_f32_16x16x32_bf16 v[106:109], v[162:165], v[196:199], v[106:109]
	v_mfma_f32_16x16x32_bf16 v[98:101], v[146:149], v[204:207], v[98:101]
	v_mfma_f32_16x16x32_bf16 v[90:93], v[162:165], v[204:207], v[90:93]
	v_mfma_f32_16x16x32_bf16 v[82:85], v[146:149], v[212:215], v[82:85]
	v_mfma_f32_16x16x32_bf16 v[74:77], v[162:165], v[212:215], v[74:77]
	s_setprio 0
	s_setprio 1
	v_mfma_f32_16x16x32_bf16 v[118:121], v[166:169], v[184:187], 0
	v_mfma_f32_16x16x32_bf16 v[110:113], v[174:177], v[184:187], 0
	v_mfma_f32_16x16x32_bf16 v[102:105], v[166:169], v[192:195], 0
	v_mfma_f32_16x16x32_bf16 v[94:97], v[174:177], v[192:195], 0
	v_mfma_f32_16x16x32_bf16 v[86:89], v[166:169], v[200:203], 0
	v_mfma_f32_16x16x32_bf16 v[78:81], v[174:177], v[200:203], 0
	v_mfma_f32_16x16x32_bf16 v[70:73], v[166:169], v[208:211], 0
	v_mfma_f32_16x16x32_bf16 v[66:69], v[174:177], v[208:211], 0
	v_mfma_f32_16x16x32_bf16 v[118:121], v[170:173], v[188:191], v[118:121]
	v_mfma_f32_16x16x32_bf16 v[110:113], v[180:183], v[188:191], v[110:113]
	v_mfma_f32_16x16x32_bf16 v[102:105], v[170:173], v[196:199], v[102:105]
	v_mfma_f32_16x16x32_bf16 v[94:97], v[180:183], v[196:199], v[94:97]
	v_mfma_f32_16x16x32_bf16 v[86:89], v[170:173], v[204:207], v[86:89]
	v_mfma_f32_16x16x32_bf16 v[78:81], v[180:183], v[204:207], v[78:81]
	v_mfma_f32_16x16x32_bf16 v[70:73], v[170:173], v[212:215], v[70:73]
	v_mfma_f32_16x16x32_bf16 v[66:69], v[180:183], v[212:215], v[66:69]
	s_barrier
	s_setprio 0
	ds_read_b128 v[184:187], v141 offset:16384
	ds_read_b128 v[188:191], v141 offset:17408
	ds_read_b128 v[192:195], v141 offset:18432
	ds_read_b128 v[196:199], v141 offset:19456
	ds_read_b128 v[200:203], v141 offset:20480
	ds_read_b128 v[204:207], v141 offset:21504
	ds_read_b128 v[208:211], v141 offset:22528
	ds_read_b128 v[212:215], v141 offset:23552
	s_add_i32 s81, s69, s61
	s_add_u32 s98, s56, 0x80
	s_addc_u32 s99, s57, 0
	s_mov_b32 m0, s81
	s_nop 0
	global_load_lds_dwordx4 v152, s[56:57]
	s_add_i32 m0, s81, 0x2000
	s_add_u32 s82, s56, 0x80000
	s_addc_u32 s83, s57, 0
	s_add_i32 s81, s70, s61
	global_load_lds_dwordx4 v156, s[56:57]
	s_mov_b32 m0, s81
	s_nop 0
	global_load_lds_dwordx4 v152, s[82:83]
	s_add_i32 m0, s81, 0x2000
	s_nop 0
	global_load_lds_dwordx4 v156, s[82:83]
	s_add_u32 s100, s58, 0x80
	s_addc_u32 s101, s59, 0
	s_mov_b32 m0, s53
	s_nop 0
	global_load_lds_dwordx4 v150, s[58:59]
	s_mov_b32 m0, s62
	s_nop 0
	global_load_lds_dwordx4 v154, s[58:59]
	s_waitcnt vmcnt(8)
	s_waitcnt lgkmcnt(0)
	s_setprio 1
	s_barrier
	v_mfma_f32_16x16x32_bf16 v[62:65], v[142:145], v[184:187], 0
	v_mfma_f32_16x16x32_bf16 v[58:61], v[158:161], v[184:187], 0
	v_mfma_f32_16x16x32_bf16 v[50:53], v[142:145], v[192:195], 0
	v_mfma_f32_16x16x32_bf16 v[42:45], v[158:161], v[192:195], 0
	v_mfma_f32_16x16x32_bf16 v[34:37], v[142:145], v[200:203], 0
	v_mfma_f32_16x16x32_bf16 v[26:29], v[158:161], v[200:203], 0
	v_mfma_f32_16x16x32_bf16 v[18:21], v[142:145], v[208:211], 0
	v_mfma_f32_16x16x32_bf16 v[10:13], v[158:161], v[208:211], 0
	v_mfma_f32_16x16x32_bf16 v[62:65], v[146:149], v[188:191], v[62:65]
	v_mfma_f32_16x16x32_bf16 v[58:61], v[162:165], v[188:191], v[58:61]
	v_mfma_f32_16x16x32_bf16 v[50:53], v[146:149], v[196:199], v[50:53]
	v_mfma_f32_16x16x32_bf16 v[42:45], v[162:165], v[196:199], v[42:45]
	v_mfma_f32_16x16x32_bf16 v[34:37], v[146:149], v[204:207], v[34:37]
	v_mfma_f32_16x16x32_bf16 v[26:29], v[162:165], v[204:207], v[26:29]
	v_mfma_f32_16x16x32_bf16 v[18:21], v[146:149], v[212:215], v[18:21]
	v_mfma_f32_16x16x32_bf16 v[10:13], v[162:165], v[212:215], v[10:13]
	s_setprio 0
	s_setprio 1
	v_mfma_f32_16x16x32_bf16 v[54:57], v[166:169], v[184:187], 0
	v_mfma_f32_16x16x32_bf16 v[46:49], v[174:177], v[184:187], 0
	v_mfma_f32_16x16x32_bf16 v[38:41], v[166:169], v[192:195], 0
	v_mfma_f32_16x16x32_bf16 v[30:33], v[174:177], v[192:195], 0
	v_mfma_f32_16x16x32_bf16 v[22:25], v[166:169], v[200:203], 0
	v_mfma_f32_16x16x32_bf16 v[14:17], v[174:177], v[200:203], 0
	v_mfma_f32_16x16x32_bf16 v[6:9], v[166:169], v[208:211], 0
	v_mfma_f32_16x16x32_bf16 v[2:5], v[174:177], v[208:211], 0
	v_mfma_f32_16x16x32_bf16 v[54:57], v[170:173], v[188:191], v[54:57]
	v_mfma_f32_16x16x32_bf16 v[46:49], v[180:183], v[188:191], v[46:49]
	v_mfma_f32_16x16x32_bf16 v[38:41], v[170:173], v[196:199], v[38:41]
	v_mfma_f32_16x16x32_bf16 v[30:33], v[180:183], v[196:199], v[30:33]
	v_mfma_f32_16x16x32_bf16 v[22:25], v[170:173], v[204:207], v[22:25]
	v_mfma_f32_16x16x32_bf16 v[14:17], v[180:183], v[204:207], v[14:17]
	v_mfma_f32_16x16x32_bf16 v[6:9], v[170:173], v[212:215], v[6:9]
	v_mfma_f32_16x16x32_bf16 v[2:5], v[180:183], v[212:215], v[2:5]
	s_barrier
	s_setprio 0
	ds_read_b128 v[142:145], v139 offset:32768
	ds_read_b128 v[146:149], v139 offset:33792
	ds_read_b128 v[158:161], v139 offset:34816
	ds_read_b128 v[162:165], v139 offset:35840
	ds_read_b128 v[166:169], v140 offset:32768
	ds_read_b128 v[170:173], v140 offset:33792
	ds_read_b128 v[174:177], v140 offset:34816
	ds_read_b128 v[180:183], v140 offset:35840
	ds_read_b128 v[184:187], v141 offset:32768
	ds_read_b128 v[188:191], v141 offset:33792
	ds_read_b128 v[192:195], v141 offset:34816
	ds_read_b128 v[196:199], v141 offset:35840
	ds_read_b128 v[200:203], v141 offset:36864
	ds_read_b128 v[204:207], v141 offset:37888
	ds_read_b128 v[208:211], v141 offset:38912
	ds_read_b128 v[212:215], v141 offset:39936
	s_add_i32 s81, 0, 0x18000
	s_add_i32 s82, 0, 0x1c000
	s_add_u32 s58, s58, 0x80000
	s_addc_u32 s59, s59, 0
	s_mov_b32 m0, s63
	s_nop 0
	global_load_lds_dwordx4 v150, s[58:59]
	s_mov_b32 m0, s64
	s_nop 0
	global_load_lds_dwordx4 v154, s[58:59]
	s_waitcnt vmcnt(8)
	s_waitcnt lgkmcnt(0)
	s_setprio 1
	s_barrier
	v_mfma_f32_16x16x32_bf16 v[126:129], v[142:145], v[184:187], v[126:129]
	v_mfma_f32_16x16x32_bf16 v[122:125], v[158:161], v[184:187], v[122:125]
	v_mfma_f32_16x16x32_bf16 v[114:117], v[142:145], v[192:195], v[114:117]
	v_mfma_f32_16x16x32_bf16 v[106:109], v[158:161], v[192:195], v[106:109]
	v_mfma_f32_16x16x32_bf16 v[98:101], v[142:145], v[200:203], v[98:101]
	v_mfma_f32_16x16x32_bf16 v[90:93], v[158:161], v[200:203], v[90:93]
	v_mfma_f32_16x16x32_bf16 v[82:85], v[142:145], v[208:211], v[82:85]
	v_mfma_f32_16x16x32_bf16 v[74:77], v[158:161], v[208:211], v[74:77]
	v_mfma_f32_16x16x32_bf16 v[126:129], v[146:149], v[188:191], v[126:129]
	v_mfma_f32_16x16x32_bf16 v[122:125], v[162:165], v[188:191], v[122:125]
	v_mfma_f32_16x16x32_bf16 v[114:117], v[146:149], v[196:199], v[114:117]
	v_mfma_f32_16x16x32_bf16 v[106:109], v[162:165], v[196:199], v[106:109]
	v_mfma_f32_16x16x32_bf16 v[98:101], v[146:149], v[204:207], v[98:101]
	v_mfma_f32_16x16x32_bf16 v[90:93], v[162:165], v[204:207], v[90:93]
	v_mfma_f32_16x16x32_bf16 v[82:85], v[146:149], v[212:215], v[82:85]
	v_mfma_f32_16x16x32_bf16 v[74:77], v[162:165], v[212:215], v[74:77]
	s_setprio 0
	s_setprio 1
	v_mfma_f32_16x16x32_bf16 v[118:121], v[166:169], v[184:187], v[118:121]
	v_mfma_f32_16x16x32_bf16 v[110:113], v[174:177], v[184:187], v[110:113]
	v_mfma_f32_16x16x32_bf16 v[102:105], v[166:169], v[192:195], v[102:105]
	v_mfma_f32_16x16x32_bf16 v[94:97], v[174:177], v[192:195], v[94:97]
	v_mfma_f32_16x16x32_bf16 v[86:89], v[166:169], v[200:203], v[86:89]
	v_mfma_f32_16x16x32_bf16 v[78:81], v[174:177], v[200:203], v[78:81]
	v_mfma_f32_16x16x32_bf16 v[70:73], v[166:169], v[208:211], v[70:73]
	v_mfma_f32_16x16x32_bf16 v[66:69], v[174:177], v[208:211], v[66:69]
	v_mfma_f32_16x16x32_bf16 v[118:121], v[170:173], v[188:191], v[118:121]
	v_mfma_f32_16x16x32_bf16 v[110:113], v[180:183], v[188:191], v[110:113]
	v_mfma_f32_16x16x32_bf16 v[102:105], v[170:173], v[196:199], v[102:105]
	v_mfma_f32_16x16x32_bf16 v[94:97], v[180:183], v[196:199], v[94:97]
	v_mfma_f32_16x16x32_bf16 v[86:89], v[170:173], v[204:207], v[86:89]
	v_mfma_f32_16x16x32_bf16 v[78:81], v[180:183], v[204:207], v[78:81]
	v_mfma_f32_16x16x32_bf16 v[70:73], v[170:173], v[212:215], v[70:73]
	v_mfma_f32_16x16x32_bf16 v[66:69], v[180:183], v[212:215], v[66:69]
	s_barrier
	s_setprio 0
	ds_read_b128 v[184:187], v141 offset:49152
	ds_read_b128 v[188:191], v141 offset:50176
	ds_read_b128 v[192:195], v141 offset:51200
	ds_read_b128 v[196:199], v141 offset:52224
	ds_read_b128 v[200:203], v141 offset:53248
	ds_read_b128 v[204:207], v141 offset:54272
	ds_read_b128 v[208:211], v141 offset:55296
	ds_read_b128 v[212:215], v141 offset:56320
	s_add_i32 s58, s81, s61
	s_mov_b32 m0, s58
	s_nop 0
	global_load_lds_dwordx4 v152, s[98:99]
	s_add_i32 m0, s58, 0x2000
	s_add_u32 s56, s56, 0x80080
	s_addc_u32 s57, s57, 0
	s_add_i32 s58, s82, s61
	global_load_lds_dwordx4 v156, s[98:99]
	s_mov_b32 m0, s58
	s_nop 0
	global_load_lds_dwordx4 v152, s[56:57]
	s_add_i32 m0, s58, 0x2000
	s_nop 0
	global_load_lds_dwordx4 v156, s[56:57]
	s_mov_b32 m0, s66
	s_nop 0
	global_load_lds_dwordx4 v150, s[100:101]
	s_mov_b32 m0, s67
	s_nop 0
	global_load_lds_dwordx4 v154, s[100:101]
	s_waitcnt vmcnt(8)
	s_waitcnt lgkmcnt(0)
	s_setprio 1
	s_barrier
	v_mfma_f32_16x16x32_bf16 v[62:65], v[142:145], v[184:187], v[62:65]
	v_mfma_f32_16x16x32_bf16 v[58:61], v[158:161], v[184:187], v[58:61]
	v_mfma_f32_16x16x32_bf16 v[50:53], v[142:145], v[192:195], v[50:53]
	v_mfma_f32_16x16x32_bf16 v[42:45], v[158:161], v[192:195], v[42:45]
	v_mfma_f32_16x16x32_bf16 v[34:37], v[142:145], v[200:203], v[34:37]
	v_mfma_f32_16x16x32_bf16 v[26:29], v[158:161], v[200:203], v[26:29]
	v_mfma_f32_16x16x32_bf16 v[18:21], v[142:145], v[208:211], v[18:21]
	v_mfma_f32_16x16x32_bf16 v[10:13], v[158:161], v[208:211], v[10:13]
	v_mfma_f32_16x16x32_bf16 v[62:65], v[146:149], v[188:191], v[62:65]
	v_mfma_f32_16x16x32_bf16 v[58:61], v[162:165], v[188:191], v[58:61]
	v_mfma_f32_16x16x32_bf16 v[50:53], v[146:149], v[196:199], v[50:53]
	v_mfma_f32_16x16x32_bf16 v[42:45], v[162:165], v[196:199], v[42:45]
	v_mfma_f32_16x16x32_bf16 v[34:37], v[146:149], v[204:207], v[34:37]
	v_mfma_f32_16x16x32_bf16 v[26:29], v[162:165], v[204:207], v[26:29]
	v_mfma_f32_16x16x32_bf16 v[18:21], v[146:149], v[212:215], v[18:21]
	v_mfma_f32_16x16x32_bf16 v[10:13], v[162:165], v[212:215], v[10:13]
	s_setprio 0
	s_setprio 1
	v_mfma_f32_16x16x32_bf16 v[54:57], v[166:169], v[184:187], v[54:57]
	v_mfma_f32_16x16x32_bf16 v[46:49], v[174:177], v[184:187], v[46:49]
	v_mfma_f32_16x16x32_bf16 v[38:41], v[166:169], v[192:195], v[38:41]
	v_mfma_f32_16x16x32_bf16 v[30:33], v[174:177], v[192:195], v[30:33]
	v_mfma_f32_16x16x32_bf16 v[22:25], v[166:169], v[200:203], v[22:25]
	v_mfma_f32_16x16x32_bf16 v[14:17], v[174:177], v[200:203], v[14:17]
	v_mfma_f32_16x16x32_bf16 v[6:9], v[166:169], v[208:211], v[6:9]
	v_mfma_f32_16x16x32_bf16 v[2:5], v[174:177], v[208:211], v[2:5]
	v_mfma_f32_16x16x32_bf16 v[54:57], v[170:173], v[188:191], v[54:57]
	v_mfma_f32_16x16x32_bf16 v[46:49], v[180:183], v[188:191], v[46:49]
	v_mfma_f32_16x16x32_bf16 v[38:41], v[170:173], v[196:199], v[38:41]
	v_mfma_f32_16x16x32_bf16 v[30:33], v[180:183], v[196:199], v[30:33]
	v_mfma_f32_16x16x32_bf16 v[22:25], v[170:173], v[204:207], v[22:25]
	v_mfma_f32_16x16x32_bf16 v[14:17], v[180:183], v[204:207], v[14:17]
	v_mfma_f32_16x16x32_bf16 v[6:9], v[170:173], v[212:215], v[6:9]
	v_mfma_f32_16x16x32_bf16 v[2:5], v[180:183], v[212:215], v[2:5]
	s_barrier
	s_setprio 0
	s_add_i32 s80, s80, 2
	s_add_u32 s54, s54, 0x100
	s_addc_u32 s55, s55, 0
	s_add_u32 s78, s78, 0x100
	s_addc_u32 s79, s79, 0
	s_cmp_gt_u32 s80, 29
.LBB0_725:
	ds_read_b128 v[142:145], v139
	ds_read_b128 v[146:149], v139 offset:1024
	ds_read_b128 v[158:161], v139 offset:2048
	ds_read_b128 v[162:165], v139 offset:3072
	ds_read_b128 v[166:169], v140
	ds_read_b128 v[170:173], v140 offset:1024
	ds_read_b128 v[174:177], v140 offset:2048
	ds_read_b128 v[180:183], v140 offset:3072
	ds_read_b128 v[184:187], v141
	ds_read_b128 v[188:191], v141 offset:1024
	ds_read_b128 v[192:195], v141 offset:2048
	ds_read_b128 v[196:199], v141 offset:3072
	ds_read_b128 v[200:203], v141 offset:4096
	ds_read_b128 v[204:207], v141 offset:5120
	ds_read_b128 v[208:211], v141 offset:6144
	ds_read_b128 v[212:215], v141 offset:7168
	s_add_u32 s56, s54, 0xfff80080
	s_addc_u32 s57, s55, -1
	s_cmp_eq_u32 s80, 28
	s_cselect_b32 s59, s37, s57
	s_cselect_b32 s58, s76, s56
	s_cselect_b32 s57, s35, s79
	s_cselect_b32 s56, s77, s78
	s_add_i32 m0, s53, 0xc000
	s_nop 0
	global_load_lds_dwordx4 v130, s[54:55]
	s_add_i32 m0, s53, 0xe000
	s_nop 0
	global_load_lds_dwordx4 v132, s[54:55]
	s_waitcnt vmcnt(8)
	s_waitcnt lgkmcnt(0)
	s_setprio 1
	s_barrier
	v_mfma_f32_16x16x32_bf16 v[126:129], v[142:145], v[184:187], v[126:129]
	v_mfma_f32_16x16x32_bf16 v[122:125], v[158:161], v[184:187], v[122:125]
	v_mfma_f32_16x16x32_bf16 v[114:117], v[142:145], v[192:195], v[114:117]
	v_mfma_f32_16x16x32_bf16 v[106:109], v[158:161], v[192:195], v[106:109]
	v_mfma_f32_16x16x32_bf16 v[98:101], v[142:145], v[200:203], v[98:101]
	v_mfma_f32_16x16x32_bf16 v[90:93], v[158:161], v[200:203], v[90:93]
	v_mfma_f32_16x16x32_bf16 v[82:85], v[142:145], v[208:211], v[82:85]
	v_mfma_f32_16x16x32_bf16 v[74:77], v[158:161], v[208:211], v[74:77]
	v_mfma_f32_16x16x32_bf16 v[126:129], v[146:149], v[188:191], v[126:129]
	v_mfma_f32_16x16x32_bf16 v[122:125], v[162:165], v[188:191], v[122:125]
	v_mfma_f32_16x16x32_bf16 v[114:117], v[146:149], v[196:199], v[114:117]
	v_mfma_f32_16x16x32_bf16 v[106:109], v[162:165], v[196:199], v[106:109]
	v_mfma_f32_16x16x32_bf16 v[98:101], v[146:149], v[204:207], v[98:101]
	v_mfma_f32_16x16x32_bf16 v[90:93], v[162:165], v[204:207], v[90:93]
	v_mfma_f32_16x16x32_bf16 v[82:85], v[146:149], v[212:215], v[82:85]
	v_mfma_f32_16x16x32_bf16 v[74:77], v[162:165], v[212:215], v[74:77]
	s_setprio 0
	s_setprio 1
	v_mfma_f32_16x16x32_bf16 v[118:121], v[166:169], v[184:187], v[118:121]
	v_mfma_f32_16x16x32_bf16 v[110:113], v[174:177], v[184:187], v[110:113]
	v_mfma_f32_16x16x32_bf16 v[102:105], v[166:169], v[192:195], v[102:105]
	v_mfma_f32_16x16x32_bf16 v[94:97], v[174:177], v[192:195], v[94:97]
	v_mfma_f32_16x16x32_bf16 v[86:89], v[166:169], v[200:203], v[86:89]
	v_mfma_f32_16x16x32_bf16 v[78:81], v[174:177], v[200:203], v[78:81]
	v_mfma_f32_16x16x32_bf16 v[70:73], v[166:169], v[208:211], v[70:73]
	v_mfma_f32_16x16x32_bf16 v[66:69], v[174:177], v[208:211], v[66:69]
	v_mfma_f32_16x16x32_bf16 v[118:121], v[170:173], v[188:191], v[118:121]
	v_mfma_f32_16x16x32_bf16 v[110:113], v[180:183], v[188:191], v[110:113]
	v_mfma_f32_16x16x32_bf16 v[102:105], v[170:173], v[196:199], v[102:105]
	v_mfma_f32_16x16x32_bf16 v[94:97], v[180:183], v[196:199], v[94:97]
	v_mfma_f32_16x16x32_bf16 v[86:89], v[170:173], v[204:207], v[86:89]
	v_mfma_f32_16x16x32_bf16 v[78:81], v[180:183], v[204:207], v[78:81]
	v_mfma_f32_16x16x32_bf16 v[70:73], v[170:173], v[212:215], v[70:73]
	v_mfma_f32_16x16x32_bf16 v[66:69], v[180:183], v[212:215], v[66:69]
	s_barrier
	s_setprio 0
	ds_read_b128 v[184:187], v141 offset:16384
	ds_read_b128 v[188:191], v141 offset:17408
	ds_read_b128 v[192:195], v141 offset:18432
	ds_read_b128 v[196:199], v141 offset:19456
	ds_read_b128 v[200:203], v141 offset:20480
	ds_read_b128 v[204:207], v141 offset:21504
	ds_read_b128 v[208:211], v141 offset:22528
	ds_read_b128 v[212:215], v141 offset:23552
	s_add_i32 s81, s69, s61
	s_add_u32 s98, s56, 0x80
	s_addc_u32 s99, s57, 0
	s_mov_b32 m0, s81
	s_nop 0
	global_load_lds_dwordx4 v152, s[56:57]
	s_add_i32 m0, s81, 0x2000
	s_add_u32 s82, s56, 0x80000
	s_addc_u32 s83, s57, 0
	s_add_i32 s81, s70, s61
	global_load_lds_dwordx4 v156, s[56:57]
	s_mov_b32 m0, s81
	s_nop 0
	global_load_lds_dwordx4 v152, s[82:83]
	s_add_i32 m0, s81, 0x2000
	s_nop 0
	global_load_lds_dwordx4 v156, s[82:83]
	s_add_u32 s100, s58, 0x80
	s_addc_u32 s101, s59, 0
	s_mov_b32 m0, s53
	s_nop 0
	global_load_lds_dwordx4 v150, s[58:59]
	s_mov_b32 m0, s62
	s_nop 0
	global_load_lds_dwordx4 v154, s[58:59]
	s_waitcnt vmcnt(8)
	s_waitcnt lgkmcnt(0)
	s_setprio 1
	s_barrier
	v_mfma_f32_16x16x32_bf16 v[62:65], v[142:145], v[184:187], v[62:65]
	v_mfma_f32_16x16x32_bf16 v[58:61], v[158:161], v[184:187], v[58:61]
	v_mfma_f32_16x16x32_bf16 v[50:53], v[142:145], v[192:195], v[50:53]
	v_mfma_f32_16x16x32_bf16 v[42:45], v[158:161], v[192:195], v[42:45]
	v_mfma_f32_16x16x32_bf16 v[34:37], v[142:145], v[200:203], v[34:37]
	v_mfma_f32_16x16x32_bf16 v[26:29], v[158:161], v[200:203], v[26:29]
	v_mfma_f32_16x16x32_bf16 v[18:21], v[142:145], v[208:211], v[18:21]
	v_mfma_f32_16x16x32_bf16 v[10:13], v[158:161], v[208:211], v[10:13]
	v_mfma_f32_16x16x32_bf16 v[62:65], v[146:149], v[188:191], v[62:65]
	v_mfma_f32_16x16x32_bf16 v[58:61], v[162:165], v[188:191], v[58:61]
	v_mfma_f32_16x16x32_bf16 v[50:53], v[146:149], v[196:199], v[50:53]
	v_mfma_f32_16x16x32_bf16 v[42:45], v[162:165], v[196:199], v[42:45]
	v_mfma_f32_16x16x32_bf16 v[34:37], v[146:149], v[204:207], v[34:37]
	v_mfma_f32_16x16x32_bf16 v[26:29], v[162:165], v[204:207], v[26:29]
	v_mfma_f32_16x16x32_bf16 v[18:21], v[146:149], v[212:215], v[18:21]
	v_mfma_f32_16x16x32_bf16 v[10:13], v[162:165], v[212:215], v[10:13]
	s_setprio 0
	s_setprio 1
	v_mfma_f32_16x16x32_bf16 v[54:57], v[166:169], v[184:187], v[54:57]
	v_mfma_f32_16x16x32_bf16 v[46:49], v[174:177], v[184:187], v[46:49]
	v_mfma_f32_16x16x32_bf16 v[38:41], v[166:169], v[192:195], v[38:41]
	v_mfma_f32_16x16x32_bf16 v[30:33], v[174:177], v[192:195], v[30:33]
	v_mfma_f32_16x16x32_bf16 v[22:25], v[166:169], v[200:203], v[22:25]
	v_mfma_f32_16x16x32_bf16 v[14:17], v[174:177], v[200:203], v[14:17]
	v_mfma_f32_16x16x32_bf16 v[6:9], v[166:169], v[208:211], v[6:9]
	v_mfma_f32_16x16x32_bf16 v[2:5], v[174:177], v[208:211], v[2:5]
	v_mfma_f32_16x16x32_bf16 v[54:57], v[170:173], v[188:191], v[54:57]
	v_mfma_f32_16x16x32_bf16 v[46:49], v[180:183], v[188:191], v[46:49]
	v_mfma_f32_16x16x32_bf16 v[38:41], v[170:173], v[196:199], v[38:41]
	v_mfma_f32_16x16x32_bf16 v[30:33], v[180:183], v[196:199], v[30:33]
	v_mfma_f32_16x16x32_bf16 v[22:25], v[170:173], v[204:207], v[22:25]
	v_mfma_f32_16x16x32_bf16 v[14:17], v[180:183], v[204:207], v[14:17]
	v_mfma_f32_16x16x32_bf16 v[6:9], v[170:173], v[212:215], v[6:9]
	v_mfma_f32_16x16x32_bf16 v[2:5], v[180:183], v[212:215], v[2:5]
	s_barrier
	s_setprio 0
	ds_read_b128 v[142:145], v139 offset:32768
	ds_read_b128 v[146:149], v139 offset:33792
	ds_read_b128 v[158:161], v139 offset:34816
	ds_read_b128 v[162:165], v139 offset:35840
	ds_read_b128 v[166:169], v140 offset:32768
	ds_read_b128 v[170:173], v140 offset:33792
	ds_read_b128 v[174:177], v140 offset:34816
	ds_read_b128 v[180:183], v140 offset:35840
	ds_read_b128 v[184:187], v141 offset:32768
	ds_read_b128 v[188:191], v141 offset:33792
	ds_read_b128 v[192:195], v141 offset:34816
	ds_read_b128 v[196:199], v141 offset:35840
	ds_read_b128 v[200:203], v141 offset:36864
	ds_read_b128 v[204:207], v141 offset:37888
	ds_read_b128 v[208:211], v141 offset:38912
	ds_read_b128 v[212:215], v141 offset:39936
	s_add_i32 s81, 0, 0x18000
	s_add_i32 s82, 0, 0x1c000
	s_add_u32 s58, s58, 0x80000
	s_addc_u32 s59, s59, 0
	s_mov_b32 m0, s63
	s_nop 0
	global_load_lds_dwordx4 v150, s[58:59]
	s_mov_b32 m0, s64
	s_nop 0
	global_load_lds_dwordx4 v154, s[58:59]
	s_waitcnt vmcnt(8)
	s_waitcnt lgkmcnt(0)
	s_setprio 1
	s_barrier
	v_mfma_f32_16x16x32_bf16 v[126:129], v[142:145], v[184:187], v[126:129]
	v_mfma_f32_16x16x32_bf16 v[122:125], v[158:161], v[184:187], v[122:125]
	v_mfma_f32_16x16x32_bf16 v[114:117], v[142:145], v[192:195], v[114:117]
	v_mfma_f32_16x16x32_bf16 v[106:109], v[158:161], v[192:195], v[106:109]
	v_mfma_f32_16x16x32_bf16 v[98:101], v[142:145], v[200:203], v[98:101]
	v_mfma_f32_16x16x32_bf16 v[90:93], v[158:161], v[200:203], v[90:93]
	v_mfma_f32_16x16x32_bf16 v[82:85], v[142:145], v[208:211], v[82:85]
	v_mfma_f32_16x16x32_bf16 v[74:77], v[158:161], v[208:211], v[74:77]
	v_mfma_f32_16x16x32_bf16 v[126:129], v[146:149], v[188:191], v[126:129]
	v_mfma_f32_16x16x32_bf16 v[122:125], v[162:165], v[188:191], v[122:125]
	v_mfma_f32_16x16x32_bf16 v[114:117], v[146:149], v[196:199], v[114:117]
	v_mfma_f32_16x16x32_bf16 v[106:109], v[162:165], v[196:199], v[106:109]
	v_mfma_f32_16x16x32_bf16 v[98:101], v[146:149], v[204:207], v[98:101]
	v_mfma_f32_16x16x32_bf16 v[90:93], v[162:165], v[204:207], v[90:93]
	v_mfma_f32_16x16x32_bf16 v[82:85], v[146:149], v[212:215], v[82:85]
	v_mfma_f32_16x16x32_bf16 v[74:77], v[162:165], v[212:215], v[74:77]
	s_setprio 0
	s_setprio 1
	v_mfma_f32_16x16x32_bf16 v[118:121], v[166:169], v[184:187], v[118:121]
	v_mfma_f32_16x16x32_bf16 v[110:113], v[174:177], v[184:187], v[110:113]
	v_mfma_f32_16x16x32_bf16 v[102:105], v[166:169], v[192:195], v[102:105]
	v_mfma_f32_16x16x32_bf16 v[94:97], v[174:177], v[192:195], v[94:97]
	v_mfma_f32_16x16x32_bf16 v[86:89], v[166:169], v[200:203], v[86:89]
	v_mfma_f32_16x16x32_bf16 v[78:81], v[174:177], v[200:203], v[78:81]
	v_mfma_f32_16x16x32_bf16 v[70:73], v[166:169], v[208:211], v[70:73]
	v_mfma_f32_16x16x32_bf16 v[66:69], v[174:177], v[208:211], v[66:69]
	v_mfma_f32_16x16x32_bf16 v[118:121], v[170:173], v[188:191], v[118:121]
	v_mfma_f32_16x16x32_bf16 v[110:113], v[180:183], v[188:191], v[110:113]
	v_mfma_f32_16x16x32_bf16 v[102:105], v[170:173], v[196:199], v[102:105]
	v_mfma_f32_16x16x32_bf16 v[94:97], v[180:183], v[196:199], v[94:97]
	v_mfma_f32_16x16x32_bf16 v[86:89], v[170:173], v[204:207], v[86:89]
	v_mfma_f32_16x16x32_bf16 v[78:81], v[180:183], v[204:207], v[78:81]
	v_mfma_f32_16x16x32_bf16 v[70:73], v[170:173], v[212:215], v[70:73]
	v_mfma_f32_16x16x32_bf16 v[66:69], v[180:183], v[212:215], v[66:69]
	s_barrier
	s_setprio 0
	ds_read_b128 v[184:187], v141 offset:49152
	ds_read_b128 v[188:191], v141 offset:50176
	ds_read_b128 v[192:195], v141 offset:51200
	ds_read_b128 v[196:199], v141 offset:52224
	ds_read_b128 v[200:203], v141 offset:53248
	ds_read_b128 v[204:207], v141 offset:54272
	ds_read_b128 v[208:211], v141 offset:55296
	ds_read_b128 v[212:215], v141 offset:56320
	s_add_i32 s58, s81, s61
	s_mov_b32 m0, s58
	s_nop 0
	global_load_lds_dwordx4 v152, s[98:99]
	s_add_i32 m0, s58, 0x2000
	s_add_u32 s56, s56, 0x80080
	s_addc_u32 s57, s57, 0
	s_add_i32 s58, s82, s61
	global_load_lds_dwordx4 v156, s[98:99]
	s_mov_b32 m0, s58
	s_nop 0
	global_load_lds_dwordx4 v152, s[56:57]
	s_add_i32 m0, s58, 0x2000
	s_nop 0
	global_load_lds_dwordx4 v156, s[56:57]
	s_mov_b32 m0, s66
	s_nop 0
	global_load_lds_dwordx4 v150, s[100:101]
	s_mov_b32 m0, s67
	s_nop 0
	global_load_lds_dwordx4 v154, s[100:101]
	s_add_i32 s80, s80, 2
	s_add_u32 s54, s54, 0x100
	s_addc_u32 s55, s55, 0
	s_add_u32 s78, s78, 0x100
	s_addc_u32 s79, s79, 0
	s_cmp_gt_u32 s80, 29
	s_waitcnt vmcnt(8)
	s_waitcnt lgkmcnt(0)
	s_setprio 1
	s_barrier
	v_mfma_f32_16x16x32_bf16 v[62:65], v[142:145], v[184:187], v[62:65]
	v_mfma_f32_16x16x32_bf16 v[58:61], v[158:161], v[184:187], v[58:61]
	v_mfma_f32_16x16x32_bf16 v[50:53], v[142:145], v[192:195], v[50:53]
	v_mfma_f32_16x16x32_bf16 v[42:45], v[158:161], v[192:195], v[42:45]
	v_mfma_f32_16x16x32_bf16 v[34:37], v[142:145], v[200:203], v[34:37]
	v_mfma_f32_16x16x32_bf16 v[26:29], v[158:161], v[200:203], v[26:29]
	v_mfma_f32_16x16x32_bf16 v[18:21], v[142:145], v[208:211], v[18:21]
	v_mfma_f32_16x16x32_bf16 v[10:13], v[158:161], v[208:211], v[10:13]
	v_mfma_f32_16x16x32_bf16 v[62:65], v[146:149], v[188:191], v[62:65]
	v_mfma_f32_16x16x32_bf16 v[58:61], v[162:165], v[188:191], v[58:61]
	v_mfma_f32_16x16x32_bf16 v[50:53], v[146:149], v[196:199], v[50:53]
	v_mfma_f32_16x16x32_bf16 v[42:45], v[162:165], v[196:199], v[42:45]
	v_mfma_f32_16x16x32_bf16 v[34:37], v[146:149], v[204:207], v[34:37]
	v_mfma_f32_16x16x32_bf16 v[26:29], v[162:165], v[204:207], v[26:29]
	v_mfma_f32_16x16x32_bf16 v[18:21], v[146:149], v[212:215], v[18:21]
	v_mfma_f32_16x16x32_bf16 v[10:13], v[162:165], v[212:215], v[10:13]
	s_setprio 0
	s_setprio 1
	v_mfma_f32_16x16x32_bf16 v[54:57], v[166:169], v[184:187], v[54:57]
	v_mfma_f32_16x16x32_bf16 v[46:49], v[174:177], v[184:187], v[46:49]
	v_mfma_f32_16x16x32_bf16 v[38:41], v[166:169], v[192:195], v[38:41]
	v_mfma_f32_16x16x32_bf16 v[30:33], v[174:177], v[192:195], v[30:33]
	v_mfma_f32_16x16x32_bf16 v[22:25], v[166:169], v[200:203], v[22:25]
	v_mfma_f32_16x16x32_bf16 v[14:17], v[174:177], v[200:203], v[14:17]
	v_mfma_f32_16x16x32_bf16 v[6:9], v[166:169], v[208:211], v[6:9]
	v_mfma_f32_16x16x32_bf16 v[2:5], v[174:177], v[208:211], v[2:5]
	v_mfma_f32_16x16x32_bf16 v[54:57], v[170:173], v[188:191], v[54:57]
	v_mfma_f32_16x16x32_bf16 v[46:49], v[180:183], v[188:191], v[46:49]
	v_mfma_f32_16x16x32_bf16 v[38:41], v[170:173], v[196:199], v[38:41]
	v_mfma_f32_16x16x32_bf16 v[30:33], v[180:183], v[196:199], v[30:33]
	v_mfma_f32_16x16x32_bf16 v[22:25], v[170:173], v[204:207], v[22:25]
	v_mfma_f32_16x16x32_bf16 v[14:17], v[180:183], v[204:207], v[14:17]
	v_mfma_f32_16x16x32_bf16 v[6:9], v[170:173], v[212:215], v[6:9]
	v_mfma_f32_16x16x32_bf16 v[2:5], v[180:183], v[212:215], v[2:5]
	s_barrier
	s_setprio 0
	s_cbranch_scc0 .LBB0_725
	s_and_b64 vcc, exec, s[6:7]
	s_cbranch_vccz .LBB0_728
	s_barrier

.LBB0_1328:
	s_add_u32 s40, s36, s38
	ds_read_b128 v[134:137], v236
	ds_read_b128 v[138:141], v236 offset:1024
	ds_read_b128 v[142:145], v236 offset:2048
	ds_read_b128 v[146:149], v236 offset:3072
	s_addc_u32 s41, s37, s39
	ds_read_b128 v[150:153], v236 offset:16384
	ds_read_b128 v[154:157], v236 offset:17408
	ds_read_b128 v[158:161], v236 offset:18432
	ds_read_b128 v[162:165], v236 offset:19456
	s_add_u32 s40, s40, 0x100
	s_addc_u32 s41, s41, 0
	s_add_u32 s69, s66, s38
	s_addc_u32 s70, s67, s39
	s_cmpk_eq_i32 s38, 0xf00
	s_cselect_b32 s42, s60, s40
	s_cselect_b32 s40, s63, s69
	s_cselect_b32 s43, s17, s41
	s_cselect_b32 s41, s62, s70
	v_lshl_add_u64 v[4:5], v[190:191], 0, s[38:39]
	s_add_i32 m0, s29, 0xc000
	ds_read_b128 v[166:169], v199
	ds_read_b128 v[170:173], v199 offset:1024
	ds_read_b128 v[200:203], v199 offset:2048
	ds_read_b128 v[204:207], v199 offset:3072
	ds_read_b128 v[208:211], v199 offset:4096
	ds_read_b128 v[212:215], v199 offset:5120
	ds_read_b128 v[216:219], v199 offset:6144
	ds_read_b128 v[220:223], v199 offset:7168
	global_load_lds_dwordx4 v[4:5], off
	v_lshl_add_u64 v[4:5], v[192:193], 0, s[38:39]
	s_add_i32 m0, s29, 0xe000
	s_nop 0
	global_load_lds_dwordx4 v[4:5], off
	s_waitcnt vmcnt(8)
	s_waitcnt lgkmcnt(0)
	s_setprio 1
	s_barrier
	v_mfma_f32_16x16x32_bf16 v[130:133], v[134:137], v[166:169], v[130:133]
	v_mfma_f32_16x16x32_bf16 v[126:129], v[142:145], v[166:169], v[126:129]
	v_mfma_f32_16x16x32_bf16 v[114:117], v[134:137], v[200:203], v[114:117]
	v_mfma_f32_16x16x32_bf16 v[110:113], v[142:145], v[200:203], v[110:113]
	v_mfma_f32_16x16x32_bf16 v[98:101], v[134:137], v[208:211], v[98:101]
	v_mfma_f32_16x16x32_bf16 v[94:97], v[142:145], v[208:211], v[94:97]
	v_mfma_f32_16x16x32_bf16 v[82:85], v[134:137], v[216:219], v[82:85]
	v_mfma_f32_16x16x32_bf16 v[78:81], v[142:145], v[216:219], v[78:81]
	v_mfma_f32_16x16x32_bf16 v[130:133], v[138:141], v[170:173], v[130:133]
	v_mfma_f32_16x16x32_bf16 v[126:129], v[146:149], v[170:173], v[126:129]
	v_mfma_f32_16x16x32_bf16 v[114:117], v[138:141], v[204:207], v[114:117]
	v_mfma_f32_16x16x32_bf16 v[110:113], v[146:149], v[204:207], v[110:113]
	v_mfma_f32_16x16x32_bf16 v[98:101], v[138:141], v[212:215], v[98:101]
	v_mfma_f32_16x16x32_bf16 v[94:97], v[146:149], v[212:215], v[94:97]
	v_mfma_f32_16x16x32_bf16 v[82:85], v[138:141], v[220:223], v[82:85]
	v_mfma_f32_16x16x32_bf16 v[78:81], v[146:149], v[220:223], v[78:81]
	s_setprio 0
	s_setprio 1
	v_mfma_f32_16x16x32_bf16 v[122:125], v[150:153], v[166:169], v[122:125]
	v_mfma_f32_16x16x32_bf16 v[118:121], v[158:161], v[166:169], v[118:121]
	v_mfma_f32_16x16x32_bf16 v[106:109], v[150:153], v[200:203], v[106:109]
	v_mfma_f32_16x16x32_bf16 v[102:105], v[158:161], v[200:203], v[102:105]
	v_mfma_f32_16x16x32_bf16 v[90:93], v[150:153], v[208:211], v[90:93]
	v_mfma_f32_16x16x32_bf16 v[86:89], v[158:161], v[208:211], v[86:89]
	v_mfma_f32_16x16x32_bf16 v[74:77], v[150:153], v[216:219], v[74:77]
	v_mfma_f32_16x16x32_bf16 v[70:73], v[158:161], v[216:219], v[70:73]
	v_mfma_f32_16x16x32_bf16 v[122:125], v[154:157], v[170:173], v[122:125]
	v_mfma_f32_16x16x32_bf16 v[118:121], v[162:165], v[170:173], v[118:121]
	v_mfma_f32_16x16x32_bf16 v[106:109], v[154:157], v[204:207], v[106:109]
	v_mfma_f32_16x16x32_bf16 v[102:105], v[162:165], v[204:207], v[102:105]
	v_mfma_f32_16x16x32_bf16 v[90:93], v[154:157], v[212:215], v[90:93]
	v_mfma_f32_16x16x32_bf16 v[86:89], v[162:165], v[212:215], v[86:89]
	v_mfma_f32_16x16x32_bf16 v[74:77], v[154:157], v[220:223], v[74:77]
	v_mfma_f32_16x16x32_bf16 v[70:73], v[162:165], v[220:223], v[70:73]
	s_barrier
	s_setprio 0
	s_add_i32 s69, s58, s28
	s_add_u32 s98, s40, 0x80
	s_addc_u32 s99, s41, 0
	s_mov_b32 m0, s69
	ds_read_b128 v[166:169], v199 offset:16384
	ds_read_b128 v[170:173], v199 offset:17408
	ds_read_b128 v[200:203], v199 offset:18432
	ds_read_b128 v[204:207], v199 offset:19456
	ds_read_b128 v[208:211], v199 offset:20480
	ds_read_b128 v[212:215], v199 offset:21504
	ds_read_b128 v[216:219], v199 offset:22528
	ds_read_b128 v[220:223], v199 offset:23552
	global_load_lds_dwordx4 v176, s[40:41]
	s_add_i32 m0, s69, 0x2000
	s_add_u32 s70, s40, 0x80000
	s_addc_u32 s71, s41, 0
	s_add_i32 s69, s59, s28
	global_load_lds_dwordx4 v180, s[40:41]
	s_mov_b32 m0, s69
	s_add_u32 s100, s42, 0x80
	s_addc_u32 s101, s43, 0
	global_load_lds_dwordx4 v176, s[70:71]
	v_lshl_add_u64 v[4:5], s[70:71], 0, v[180:181]
	s_add_i32 m0, s69, 0x2000
	s_nop 0
	global_load_lds_dwordx4 v[4:5], off
	s_mov_b32 m0, s29
	s_nop 0
	global_load_lds_dwordx4 v174, s[42:43]
	s_mov_b32 m0, s44
	s_nop 0
	global_load_lds_dwordx4 v178, s[42:43]
	s_waitcnt vmcnt(8)
	s_waitcnt lgkmcnt(0)
	s_setprio 1
	s_barrier
	v_mfma_f32_16x16x32_bf16 v[66:69], v[134:137], v[166:169], v[66:69]
	v_mfma_f32_16x16x32_bf16 v[62:65], v[142:145], v[166:169], v[62:65]
	v_mfma_f32_16x16x32_bf16 v[50:53], v[134:137], v[200:203], v[50:53]
	v_mfma_f32_16x16x32_bf16 v[46:49], v[142:145], v[200:203], v[46:49]
	v_mfma_f32_16x16x32_bf16 v[34:37], v[134:137], v[208:211], v[34:37]
	v_mfma_f32_16x16x32_bf16 v[30:33], v[142:145], v[208:211], v[30:33]
	v_mfma_f32_16x16x32_bf16 v[18:21], v[134:137], v[216:219], v[18:21]
	v_mfma_f32_16x16x32_bf16 v[14:17], v[142:145], v[216:219], v[14:17]
	v_mfma_f32_16x16x32_bf16 v[66:69], v[138:141], v[170:173], v[66:69]
	v_mfma_f32_16x16x32_bf16 v[62:65], v[146:149], v[170:173], v[62:65]
	v_mfma_f32_16x16x32_bf16 v[50:53], v[138:141], v[204:207], v[50:53]
	v_mfma_f32_16x16x32_bf16 v[46:49], v[146:149], v[204:207], v[46:49]
	v_mfma_f32_16x16x32_bf16 v[34:37], v[138:141], v[212:215], v[34:37]
	v_mfma_f32_16x16x32_bf16 v[30:33], v[146:149], v[212:215], v[30:33]
	v_mfma_f32_16x16x32_bf16 v[18:21], v[138:141], v[220:223], v[18:21]
	v_mfma_f32_16x16x32_bf16 v[14:17], v[146:149], v[220:223], v[14:17]
	s_setprio 0
	s_setprio 1
	v_mfma_f32_16x16x32_bf16 v[58:61], v[150:153], v[166:169], v[58:61]
	v_mfma_f32_16x16x32_bf16 v[54:57], v[158:161], v[166:169], v[54:57]
	v_mfma_f32_16x16x32_bf16 v[42:45], v[150:153], v[200:203], v[42:45]
	v_mfma_f32_16x16x32_bf16 v[38:41], v[158:161], v[200:203], v[38:41]
	v_mfma_f32_16x16x32_bf16 v[26:29], v[150:153], v[208:211], v[26:29]
	v_mfma_f32_16x16x32_bf16 v[22:25], v[158:161], v[208:211], v[22:25]
	v_mfma_f32_16x16x32_bf16 v[10:13], v[150:153], v[216:219], v[10:13]
	v_mfma_f32_16x16x32_bf16 v[4:7], v[158:161], v[216:219], v[6:9]
	v_mfma_f32_16x16x32_bf16 v[58:61], v[154:157], v[170:173], v[58:61]
	v_mfma_f32_16x16x32_bf16 v[54:57], v[162:165], v[170:173], v[54:57]
	v_mfma_f32_16x16x32_bf16 v[42:45], v[154:157], v[204:207], v[42:45]
	v_mfma_f32_16x16x32_bf16 v[38:41], v[162:165], v[204:207], v[38:41]
	v_mfma_f32_16x16x32_bf16 v[26:29], v[154:157], v[212:215], v[26:29]
	v_mfma_f32_16x16x32_bf16 v[22:25], v[162:165], v[212:215], v[22:25]
	v_mfma_f32_16x16x32_bf16 v[10:13], v[154:157], v[220:223], v[10:13]
	v_mfma_f32_16x16x32_bf16 v[4:7], v[162:165], v[220:223], v[4:7]
	s_barrier
	s_setprio 0
	ds_read_b128 v[134:137], v236 offset:32768
	ds_read_b128 v[138:141], v236 offset:33792
	ds_read_b128 v[142:145], v236 offset:34816
	ds_read_b128 v[146:149], v236 offset:35840
	ds_read_b128 v[150:153], v236 offset:49152
	ds_read_b128 v[154:157], v236 offset:50176
	ds_read_b128 v[158:161], v236 offset:51200
	ds_read_b128 v[162:165], v236 offset:52224
	ds_read_b128 v[166:169], v199 offset:32768
	ds_read_b128 v[170:173], v199 offset:33792
	ds_read_b128 v[200:203], v199 offset:34816
	ds_read_b128 v[204:207], v199 offset:35840
	ds_read_b128 v[208:211], v199 offset:36864
	ds_read_b128 v[212:215], v199 offset:37888
	ds_read_b128 v[216:219], v199 offset:38912
	ds_read_b128 v[220:223], v199 offset:39936
	s_add_i32 s69, 0, 0x18000
	s_add_i32 s70, 0, 0x1c000
	s_add_u32 s42, s42, 0x80000
	s_addc_u32 s43, s43, 0
	s_mov_b32 m0, s45
	s_nop 0
	global_load_lds_dwordx4 v174, s[42:43]
	s_mov_b32 m0, s46
	s_nop 0
	global_load_lds_dwordx4 v178, s[42:43]
	s_waitcnt vmcnt(8)
	s_waitcnt lgkmcnt(0)
	s_setprio 1
	s_barrier
	v_mfma_f32_16x16x32_bf16 v[130:133], v[134:137], v[166:169], v[130:133]
	v_mfma_f32_16x16x32_bf16 v[126:129], v[142:145], v[166:169], v[126:129]
	v_mfma_f32_16x16x32_bf16 v[114:117], v[134:137], v[200:203], v[114:117]
	v_mfma_f32_16x16x32_bf16 v[110:113], v[142:145], v[200:203], v[110:113]
	v_mfma_f32_16x16x32_bf16 v[98:101], v[134:137], v[208:211], v[98:101]
	v_mfma_f32_16x16x32_bf16 v[94:97], v[142:145], v[208:211], v[94:97]
	v_mfma_f32_16x16x32_bf16 v[82:85], v[134:137], v[216:219], v[82:85]
	v_mfma_f32_16x16x32_bf16 v[78:81], v[142:145], v[216:219], v[78:81]
	v_mfma_f32_16x16x32_bf16 v[130:133], v[138:141], v[170:173], v[130:133]
	v_mfma_f32_16x16x32_bf16 v[126:129], v[146:149], v[170:173], v[126:129]
	v_mfma_f32_16x16x32_bf16 v[114:117], v[138:141], v[204:207], v[114:117]
	v_mfma_f32_16x16x32_bf16 v[110:113], v[146:149], v[204:207], v[110:113]
	v_mfma_f32_16x16x32_bf16 v[98:101], v[138:141], v[212:215], v[98:101]
	v_mfma_f32_16x16x32_bf16 v[94:97], v[146:149], v[212:215], v[94:97]
	v_mfma_f32_16x16x32_bf16 v[82:85], v[138:141], v[220:223], v[82:85]
	v_mfma_f32_16x16x32_bf16 v[78:81], v[146:149], v[220:223], v[78:81]
	s_setprio 0
	s_setprio 1
	v_mfma_f32_16x16x32_bf16 v[122:125], v[150:153], v[166:169], v[122:125]
	v_mfma_f32_16x16x32_bf16 v[118:121], v[158:161], v[166:169], v[118:121]
	v_mfma_f32_16x16x32_bf16 v[106:109], v[150:153], v[200:203], v[106:109]
	v_mfma_f32_16x16x32_bf16 v[102:105], v[158:161], v[200:203], v[102:105]
	v_mfma_f32_16x16x32_bf16 v[90:93], v[150:153], v[208:211], v[90:93]
	v_mfma_f32_16x16x32_bf16 v[86:89], v[158:161], v[208:211], v[86:89]
	v_mfma_f32_16x16x32_bf16 v[74:77], v[150:153], v[216:219], v[74:77]
	v_mfma_f32_16x16x32_bf16 v[70:73], v[158:161], v[216:219], v[70:73]
	v_mfma_f32_16x16x32_bf16 v[122:125], v[154:157], v[170:173], v[122:125]
	v_mfma_f32_16x16x32_bf16 v[118:121], v[162:165], v[170:173], v[118:121]
	v_mfma_f32_16x16x32_bf16 v[106:109], v[154:157], v[204:207], v[106:109]
	v_mfma_f32_16x16x32_bf16 v[102:105], v[162:165], v[204:207], v[102:105]
	v_mfma_f32_16x16x32_bf16 v[90:93], v[154:157], v[212:215], v[90:93]
	v_mfma_f32_16x16x32_bf16 v[86:89], v[162:165], v[212:215], v[86:89]
	v_mfma_f32_16x16x32_bf16 v[74:77], v[154:157], v[220:223], v[74:77]
	v_mfma_f32_16x16x32_bf16 v[70:73], v[162:165], v[220:223], v[70:73]
	s_barrier
	s_setprio 0
	ds_read_b128 v[166:169], v199 offset:49152
	ds_read_b128 v[170:173], v199 offset:50176
	ds_read_b128 v[200:203], v199 offset:51200
	ds_read_b128 v[204:207], v199 offset:52224
	ds_read_b128 v[208:211], v199 offset:53248
	ds_read_b128 v[212:215], v199 offset:54272
	ds_read_b128 v[216:219], v199 offset:55296
	ds_read_b128 v[220:223], v199 offset:56320
	s_add_i32 s42, s69, s28
	s_mov_b32 m0, s42
	s_nop 0
	global_load_lds_dwordx4 v176, s[98:99]
	s_add_i32 m0, s42, 0x2000
	s_add_u32 s40, s40, 0x80080
	s_addc_u32 s41, s41, 0
	s_add_i32 s42, s70, s28
	global_load_lds_dwordx4 v180, s[98:99]
	s_mov_b32 m0, s42
	s_nop 0
	global_load_lds_dwordx4 v176, s[40:41]
	s_add_i32 m0, s42, 0x2000
	s_nop 0
	global_load_lds_dwordx4 v180, s[40:41]
	s_mov_b32 m0, s53
	s_nop 0
	global_load_lds_dwordx4 v174, s[100:101]
	s_mov_b32 m0, s54
	s_nop 0
	global_load_lds_dwordx4 v178, s[100:101]
	s_waitcnt vmcnt(8)
	s_waitcnt lgkmcnt(0)
	s_setprio 1
	s_barrier
	v_mfma_f32_16x16x32_bf16 v[66:69], v[134:137], v[166:169], v[66:69]
	v_mfma_f32_16x16x32_bf16 v[62:65], v[142:145], v[166:169], v[62:65]
	v_mfma_f32_16x16x32_bf16 v[50:53], v[134:137], v[200:203], v[50:53]
	v_mfma_f32_16x16x32_bf16 v[46:49], v[142:145], v[200:203], v[46:49]
	v_mfma_f32_16x16x32_bf16 v[34:37], v[134:137], v[208:211], v[34:37]
	v_mfma_f32_16x16x32_bf16 v[30:33], v[142:145], v[208:211], v[30:33]
	v_mfma_f32_16x16x32_bf16 v[18:21], v[134:137], v[216:219], v[18:21]
	v_mfma_f32_16x16x32_bf16 v[14:17], v[142:145], v[216:219], v[14:17]
	v_mfma_f32_16x16x32_bf16 v[66:69], v[138:141], v[170:173], v[66:69]
	v_mfma_f32_16x16x32_bf16 v[62:65], v[146:149], v[170:173], v[62:65]
	v_mfma_f32_16x16x32_bf16 v[50:53], v[138:141], v[204:207], v[50:53]
	v_mfma_f32_16x16x32_bf16 v[46:49], v[146:149], v[204:207], v[46:49]
	v_mfma_f32_16x16x32_bf16 v[34:37], v[138:141], v[212:215], v[34:37]
	v_mfma_f32_16x16x32_bf16 v[30:33], v[146:149], v[212:215], v[30:33]
	v_mfma_f32_16x16x32_bf16 v[18:21], v[138:141], v[220:223], v[18:21]
	v_mfma_f32_16x16x32_bf16 v[14:17], v[146:149], v[220:223], v[14:17]
	s_setprio 0
	s_setprio 1
	v_mfma_f32_16x16x32_bf16 v[58:61], v[150:153], v[166:169], v[58:61]
	v_mfma_f32_16x16x32_bf16 v[54:57], v[158:161], v[166:169], v[54:57]
	v_mfma_f32_16x16x32_bf16 v[42:45], v[150:153], v[200:203], v[42:45]
	v_mfma_f32_16x16x32_bf16 v[38:41], v[158:161], v[200:203], v[38:41]
	v_mfma_f32_16x16x32_bf16 v[26:29], v[150:153], v[208:211], v[26:29]
	v_mfma_f32_16x16x32_bf16 v[22:25], v[158:161], v[208:211], v[22:25]
	v_mfma_f32_16x16x32_bf16 v[8:11], v[150:153], v[216:219], v[10:13]
	v_mfma_f32_16x16x32_bf16 v[4:7], v[158:161], v[216:219], v[4:7]
	v_mfma_f32_16x16x32_bf16 v[58:61], v[154:157], v[170:173], v[58:61]
	v_mfma_f32_16x16x32_bf16 v[54:57], v[162:165], v[170:173], v[54:57]
	v_mfma_f32_16x16x32_bf16 v[42:45], v[154:157], v[204:207], v[42:45]
	v_mfma_f32_16x16x32_bf16 v[38:41], v[162:165], v[204:207], v[38:41]
	v_mfma_f32_16x16x32_bf16 v[26:29], v[154:157], v[212:215], v[26:29]
	v_mfma_f32_16x16x32_bf16 v[22:25], v[162:165], v[212:215], v[22:25]
	v_mfma_f32_16x16x32_bf16 v[10:13], v[154:157], v[220:223], v[8:11]
	v_mfma_f32_16x16x32_bf16 v[6:9], v[162:165], v[220:223], v[4:7]
	s_barrier
	s_setprio 0
	s_add_i32 s40, s68, 2
	s_add_u32 s38, s38, 0x100
	s_addc_u32 s39, s39, 0
	s_cmp_gt_u32 s68, 29
	s_cbranch_scc1 .LBB0_1330
	s_mov_b32 s68, s40
	s_and_b32 s40, s68, 14
	s_cmp_eq_u32 s40, 8
	s_mov_b64 s[40:41], -1
	s_cbranch_scc0 .LBB0_1325
	s_branch .LBB0_1326

.LBB0_1407:
	s_ashr_i32 s39, s38, 31
	s_lshl_b64 s[40:41], s[38:39], 20
	s_add_u32 s40, s22, s40
	s_addc_u32 s41, s23, s41
	s_and_b64 s[42:43], s[10:11], exec
	s_cselect_b32 s39, s41, s47
	s_cselect_b32 s66, s40, s46
	s_ashr_i32 s37, s36, 31
	s_lshl_b64 s[42:43], s[36:37], 20
	s_add_u32 s42, s28, s42
	s_addc_u32 s43, s29, s43
	s_and_b64 s[52:53], s[10:11], exec
	s_cselect_b32 s37, s43, s49
	s_cselect_b32 s67, s42, s48
	s_add_u32 s46, s46, 0x80080
	s_addc_u32 s47, s47, 0
	s_add_u32 s68, s48, 0x100
	s_addc_u32 s69, s49, 0
	s_mov_b32 s70, -2
	s_add_u32 s48, s46, 0xfff80080
	s_addc_u32 s49, s47, -1
	s_cmp_eq_u32 s70, 28
	s_cselect_b32 s53, s39, s49
	s_cselect_b32 s52, s66, s48
	s_cselect_b32 s49, s37, s69
	s_cselect_b32 s48, s67, s68
	s_add_i32 m0, s45, 0xc000
	s_nop 0
	global_load_lds_dwordx4 v154, s[46:47]
	s_add_i32 m0, s45, 0xe000
	s_nop 0
	global_load_lds_dwordx4 v156, s[46:47]
	s_waitcnt vmcnt(8)
	s_waitcnt lgkmcnt(0)
	s_setprio 1
	s_barrier
	v_mfma_f32_16x16x32_bf16 v[126:129], v[130:133], v[188:191], 0
	v_mfma_f32_16x16x32_bf16 v[122:125], v[138:141], v[188:191], 0
	v_mfma_f32_16x16x32_bf16 v[110:113], v[130:133], v[196:199], 0
	v_mfma_f32_16x16x32_bf16 v[106:109], v[138:141], v[196:199], 0
	v_mfma_f32_16x16x32_bf16 v[94:97], v[130:133], v[204:207], 0
	v_mfma_f32_16x16x32_bf16 v[90:93], v[138:141], v[204:207], 0
	v_mfma_f32_16x16x32_bf16 v[78:81], v[130:133], v[212:215], 0
	v_mfma_f32_16x16x32_bf16 v[74:77], v[138:141], v[212:215], 0
	v_mfma_f32_16x16x32_bf16 v[126:129], v[134:137], v[192:195], v[126:129]
	v_mfma_f32_16x16x32_bf16 v[122:125], v[142:145], v[192:195], v[122:125]
	v_mfma_f32_16x16x32_bf16 v[110:113], v[134:137], v[200:203], v[110:113]
	v_mfma_f32_16x16x32_bf16 v[106:109], v[142:145], v[200:203], v[106:109]
	v_mfma_f32_16x16x32_bf16 v[94:97], v[134:137], v[208:211], v[94:97]
	v_mfma_f32_16x16x32_bf16 v[90:93], v[142:145], v[208:211], v[90:93]
	v_mfma_f32_16x16x32_bf16 v[78:81], v[134:137], v[216:219], v[78:81]
	v_mfma_f32_16x16x32_bf16 v[74:77], v[142:145], v[216:219], v[74:77]
	s_setprio 0
	s_setprio 1
	v_mfma_f32_16x16x32_bf16 v[118:121], v[162:165], v[188:191], 0
	v_mfma_f32_16x16x32_bf16 v[114:117], v[170:173], v[188:191], 0
	v_mfma_f32_16x16x32_bf16 v[102:105], v[162:165], v[196:199], 0
	v_mfma_f32_16x16x32_bf16 v[98:101], v[170:173], v[196:199], 0
	v_mfma_f32_16x16x32_bf16 v[86:89], v[162:165], v[204:207], 0
	v_mfma_f32_16x16x32_bf16 v[82:85], v[170:173], v[204:207], 0
	v_mfma_f32_16x16x32_bf16 v[70:73], v[162:165], v[212:215], 0
	v_mfma_f32_16x16x32_bf16 v[66:69], v[170:173], v[212:215], 0
	v_mfma_f32_16x16x32_bf16 v[118:121], v[166:169], v[192:195], v[118:121]
	v_mfma_f32_16x16x32_bf16 v[114:117], v[174:177], v[192:195], v[114:117]
	v_mfma_f32_16x16x32_bf16 v[102:105], v[166:169], v[200:203], v[102:105]
	v_mfma_f32_16x16x32_bf16 v[98:101], v[174:177], v[200:203], v[98:101]
	v_mfma_f32_16x16x32_bf16 v[86:89], v[166:169], v[208:211], v[86:89]
	v_mfma_f32_16x16x32_bf16 v[82:85], v[174:177], v[208:211], v[82:85]
	v_mfma_f32_16x16x32_bf16 v[70:73], v[166:169], v[216:219], v[70:73]
	v_mfma_f32_16x16x32_bf16 v[66:69], v[174:177], v[216:219], v[66:69]
	s_barrier
	s_setprio 0
	ds_read_b128 v[188:191], v185 offset:16384
	ds_read_b128 v[192:195], v185 offset:17408
	ds_read_b128 v[196:199], v185 offset:18432
	ds_read_b128 v[200:203], v185 offset:19456
	ds_read_b128 v[204:207], v185 offset:20480
	ds_read_b128 v[208:211], v185 offset:21504
	ds_read_b128 v[212:215], v185 offset:22528
	ds_read_b128 v[216:219], v185 offset:23552
	s_add_i32 s71, s63, s54
	s_add_u32 s98, s48, 0x80
	s_addc_u32 s99, s49, 0
	s_mov_b32 m0, s71
	s_nop 0
	global_load_lds_dwordx4 v148, s[48:49]
	s_add_i32 m0, s71, 0x2000
	s_add_u32 s72, s48, 0x80000
	s_addc_u32 s73, s49, 0
	s_add_i32 s71, s64, s54
	global_load_lds_dwordx4 v152, s[48:49]
	s_mov_b32 m0, s71
	s_nop 0
	global_load_lds_dwordx4 v148, s[72:73]
	s_add_i32 m0, s71, 0x2000
	s_nop 0
	global_load_lds_dwordx4 v152, s[72:73]
	s_add_u32 s100, s52, 0x80
	s_addc_u32 s101, s53, 0
	s_mov_b32 m0, s45
	s_nop 0
	global_load_lds_dwordx4 v146, s[52:53]
	s_mov_b32 m0, s55
	s_nop 0
	global_load_lds_dwordx4 v150, s[52:53]
	s_waitcnt vmcnt(8)
	s_waitcnt lgkmcnt(0)
	s_setprio 1
	s_barrier
	v_mfma_f32_16x16x32_bf16 v[62:65], v[130:133], v[188:191], 0
	v_mfma_f32_16x16x32_bf16 v[58:61], v[138:141], v[188:191], 0
	v_mfma_f32_16x16x32_bf16 v[46:49], v[130:133], v[196:199], 0
	v_mfma_f32_16x16x32_bf16 v[42:45], v[138:141], v[196:199], 0
	v_mfma_f32_16x16x32_bf16 v[30:33], v[130:133], v[204:207], 0
	v_mfma_f32_16x16x32_bf16 v[26:29], v[138:141], v[204:207], 0
	v_mfma_f32_16x16x32_bf16 v[14:17], v[130:133], v[212:215], 0
	v_mfma_f32_16x16x32_bf16 v[10:13], v[138:141], v[212:215], 0
	v_mfma_f32_16x16x32_bf16 v[62:65], v[134:137], v[192:195], v[62:65]
	v_mfma_f32_16x16x32_bf16 v[58:61], v[142:145], v[192:195], v[58:61]
	v_mfma_f32_16x16x32_bf16 v[46:49], v[134:137], v[200:203], v[46:49]
	v_mfma_f32_16x16x32_bf16 v[42:45], v[142:145], v[200:203], v[42:45]
	v_mfma_f32_16x16x32_bf16 v[30:33], v[134:137], v[208:211], v[30:33]
	v_mfma_f32_16x16x32_bf16 v[26:29], v[142:145], v[208:211], v[26:29]
	v_mfma_f32_16x16x32_bf16 v[14:17], v[134:137], v[216:219], v[14:17]
	v_mfma_f32_16x16x32_bf16 v[10:13], v[142:145], v[216:219], v[10:13]
	s_setprio 0
	s_setprio 1
	v_mfma_f32_16x16x32_bf16 v[54:57], v[162:165], v[188:191], 0
	v_mfma_f32_16x16x32_bf16 v[50:53], v[170:173], v[188:191], 0
	v_mfma_f32_16x16x32_bf16 v[38:41], v[162:165], v[196:199], 0
	v_mfma_f32_16x16x32_bf16 v[34:37], v[170:173], v[196:199], 0
	v_mfma_f32_16x16x32_bf16 v[22:25], v[162:165], v[204:207], 0
	v_mfma_f32_16x16x32_bf16 v[18:21], v[170:173], v[204:207], 0
	v_mfma_f32_16x16x32_bf16 v[6:9], v[162:165], v[212:215], 0
	v_mfma_f32_16x16x32_bf16 v[2:5], v[170:173], v[212:215], 0
	v_mfma_f32_16x16x32_bf16 v[54:57], v[166:169], v[192:195], v[54:57]
	v_mfma_f32_16x16x32_bf16 v[50:53], v[174:177], v[192:195], v[50:53]
	v_mfma_f32_16x16x32_bf16 v[38:41], v[166:169], v[200:203], v[38:41]
	v_mfma_f32_16x16x32_bf16 v[34:37], v[174:177], v[200:203], v[34:37]
	v_mfma_f32_16x16x32_bf16 v[22:25], v[166:169], v[208:211], v[22:25]
	v_mfma_f32_16x16x32_bf16 v[18:21], v[174:177], v[208:211], v[18:21]
	v_mfma_f32_16x16x32_bf16 v[6:9], v[166:169], v[216:219], v[6:9]
	v_mfma_f32_16x16x32_bf16 v[2:5], v[174:177], v[216:219], v[2:5]
	s_barrier
	s_setprio 0
	ds_read_b128 v[130:133], v183 offset:32768
	ds_read_b128 v[134:137], v183 offset:33792
	ds_read_b128 v[138:141], v183 offset:34816
	ds_read_b128 v[142:145], v183 offset:35840
	ds_read_b128 v[162:165], v184 offset:32768
	ds_read_b128 v[166:169], v184 offset:33792
	ds_read_b128 v[170:173], v184 offset:34816
	ds_read_b128 v[174:177], v184 offset:35840
	ds_read_b128 v[188:191], v185 offset:32768
	ds_read_b128 v[192:195], v185 offset:33792
	ds_read_b128 v[196:199], v185 offset:34816
	ds_read_b128 v[200:203], v185 offset:35840
	ds_read_b128 v[204:207], v185 offset:36864
	ds_read_b128 v[208:211], v185 offset:37888
	ds_read_b128 v[212:215], v185 offset:38912
	ds_read_b128 v[216:219], v185 offset:39936
	s_add_i32 s71, 0, 0x18000
	s_add_i32 s72, 0, 0x1c000
	s_add_u32 s52, s52, 0x80000
	s_addc_u32 s53, s53, 0
	s_mov_b32 m0, s56
	s_nop 0
	global_load_lds_dwordx4 v146, s[52:53]
	s_mov_b32 m0, s57
	s_nop 0
	global_load_lds_dwordx4 v150, s[52:53]
	s_waitcnt vmcnt(8)
	s_waitcnt lgkmcnt(0)
	s_setprio 1
	s_barrier
	v_mfma_f32_16x16x32_bf16 v[126:129], v[130:133], v[188:191], v[126:129]
	v_mfma_f32_16x16x32_bf16 v[122:125], v[138:141], v[188:191], v[122:125]
	v_mfma_f32_16x16x32_bf16 v[110:113], v[130:133], v[196:199], v[110:113]
	v_mfma_f32_16x16x32_bf16 v[106:109], v[138:141], v[196:199], v[106:109]
	v_mfma_f32_16x16x32_bf16 v[94:97], v[130:133], v[204:207], v[94:97]
	v_mfma_f32_16x16x32_bf16 v[90:93], v[138:141], v[204:207], v[90:93]
	v_mfma_f32_16x16x32_bf16 v[78:81], v[130:133], v[212:215], v[78:81]
	v_mfma_f32_16x16x32_bf16 v[74:77], v[138:141], v[212:215], v[74:77]
	v_mfma_f32_16x16x32_bf16 v[126:129], v[134:137], v[192:195], v[126:129]
	v_mfma_f32_16x16x32_bf16 v[122:125], v[142:145], v[192:195], v[122:125]
	v_mfma_f32_16x16x32_bf16 v[110:113], v[134:137], v[200:203], v[110:113]
	v_mfma_f32_16x16x32_bf16 v[106:109], v[142:145], v[200:203], v[106:109]
	v_mfma_f32_16x16x32_bf16 v[94:97], v[134:137], v[208:211], v[94:97]
	v_mfma_f32_16x16x32_bf16 v[90:93], v[142:145], v[208:211], v[90:93]
	v_mfma_f32_16x16x32_bf16 v[78:81], v[134:137], v[216:219], v[78:81]
	v_mfma_f32_16x16x32_bf16 v[74:77], v[142:145], v[216:219], v[74:77]
	s_setprio 0
	s_setprio 1
	v_mfma_f32_16x16x32_bf16 v[118:121], v[162:165], v[188:191], v[118:121]
	v_mfma_f32_16x16x32_bf16 v[114:117], v[170:173], v[188:191], v[114:117]
	v_mfma_f32_16x16x32_bf16 v[102:105], v[162:165], v[196:199], v[102:105]
	v_mfma_f32_16x16x32_bf16 v[98:101], v[170:173], v[196:199], v[98:101]
	v_mfma_f32_16x16x32_bf16 v[86:89], v[162:165], v[204:207], v[86:89]
	v_mfma_f32_16x16x32_bf16 v[82:85], v[170:173], v[204:207], v[82:85]
	v_mfma_f32_16x16x32_bf16 v[70:73], v[162:165], v[212:215], v[70:73]
	v_mfma_f32_16x16x32_bf16 v[66:69], v[170:173], v[212:215], v[66:69]
	v_mfma_f32_16x16x32_bf16 v[118:121], v[166:169], v[192:195], v[118:121]
	v_mfma_f32_16x16x32_bf16 v[114:117], v[174:177], v[192:195], v[114:117]
	v_mfma_f32_16x16x32_bf16 v[102:105], v[166:169], v[200:203], v[102:105]
	v_mfma_f32_16x16x32_bf16 v[98:101], v[174:177], v[200:203], v[98:101]
	v_mfma_f32_16x16x32_bf16 v[86:89], v[166:169], v[208:211], v[86:89]
	v_mfma_f32_16x16x32_bf16 v[82:85], v[174:177], v[208:211], v[82:85]
	v_mfma_f32_16x16x32_bf16 v[70:73], v[166:169], v[216:219], v[70:73]
	v_mfma_f32_16x16x32_bf16 v[66:69], v[174:177], v[216:219], v[66:69]
	s_barrier
	s_setprio 0
	ds_read_b128 v[188:191], v185 offset:49152
	ds_read_b128 v[192:195], v185 offset:50176
	ds_read_b128 v[196:199], v185 offset:51200
	ds_read_b128 v[200:203], v185 offset:52224
	ds_read_b128 v[204:207], v185 offset:53248
	ds_read_b128 v[208:211], v185 offset:54272
	ds_read_b128 v[212:215], v185 offset:55296
	ds_read_b128 v[216:219], v185 offset:56320
	s_add_i32 s52, s71, s54
	s_mov_b32 m0, s52
	s_nop 0
	global_load_lds_dwordx4 v148, s[98:99]
	s_add_i32 m0, s52, 0x2000
	s_add_u32 s48, s48, 0x80080
	s_addc_u32 s49, s49, 0
	s_add_i32 s52, s72, s54
	global_load_lds_dwordx4 v152, s[98:99]
	s_mov_b32 m0, s52
	s_nop 0
	global_load_lds_dwordx4 v148, s[48:49]
	s_add_i32 m0, s52, 0x2000
	s_nop 0
	global_load_lds_dwordx4 v152, s[48:49]
	s_mov_b32 m0, s60
	s_nop 0
	global_load_lds_dwordx4 v146, s[100:101]
	s_mov_b32 m0, s61
	s_nop 0
	global_load_lds_dwordx4 v150, s[100:101]
	s_waitcnt vmcnt(8)
	s_waitcnt lgkmcnt(0)
	s_setprio 1
	s_barrier
	v_mfma_f32_16x16x32_bf16 v[62:65], v[130:133], v[188:191], v[62:65]
	v_mfma_f32_16x16x32_bf16 v[58:61], v[138:141], v[188:191], v[58:61]
	v_mfma_f32_16x16x32_bf16 v[46:49], v[130:133], v[196:199], v[46:49]
	v_mfma_f32_16x16x32_bf16 v[42:45], v[138:141], v[196:199], v[42:45]
	v_mfma_f32_16x16x32_bf16 v[30:33], v[130:133], v[204:207], v[30:33]
	v_mfma_f32_16x16x32_bf16 v[26:29], v[138:141], v[204:207], v[26:29]
	v_mfma_f32_16x16x32_bf16 v[14:17], v[130:133], v[212:215], v[14:17]
	v_mfma_f32_16x16x32_bf16 v[10:13], v[138:141], v[212:215], v[10:13]
	v_mfma_f32_16x16x32_bf16 v[62:65], v[134:137], v[192:195], v[62:65]
	v_mfma_f32_16x16x32_bf16 v[58:61], v[142:145], v[192:195], v[58:61]
	v_mfma_f32_16x16x32_bf16 v[46:49], v[134:137], v[200:203], v[46:49]
	v_mfma_f32_16x16x32_bf16 v[42:45], v[142:145], v[200:203], v[42:45]
	v_mfma_f32_16x16x32_bf16 v[30:33], v[134:137], v[208:211], v[30:33]
	v_mfma_f32_16x16x32_bf16 v[26:29], v[142:145], v[208:211], v[26:29]
	v_mfma_f32_16x16x32_bf16 v[14:17], v[134:137], v[216:219], v[14:17]
	v_mfma_f32_16x16x32_bf16 v[10:13], v[142:145], v[216:219], v[10:13]
	s_setprio 0
	s_setprio 1
	v_mfma_f32_16x16x32_bf16 v[54:57], v[162:165], v[188:191], v[54:57]
	v_mfma_f32_16x16x32_bf16 v[50:53], v[170:173], v[188:191], v[50:53]
	v_mfma_f32_16x16x32_bf16 v[38:41], v[162:165], v[196:199], v[38:41]
	v_mfma_f32_16x16x32_bf16 v[34:37], v[170:173], v[196:199], v[34:37]
	v_mfma_f32_16x16x32_bf16 v[22:25], v[162:165], v[204:207], v[22:25]
	v_mfma_f32_16x16x32_bf16 v[18:21], v[170:173], v[204:207], v[18:21]
	v_mfma_f32_16x16x32_bf16 v[6:9], v[162:165], v[212:215], v[6:9]
	v_mfma_f32_16x16x32_bf16 v[2:5], v[170:173], v[212:215], v[2:5]
	v_mfma_f32_16x16x32_bf16 v[54:57], v[166:169], v[192:195], v[54:57]
	v_mfma_f32_16x16x32_bf16 v[50:53], v[174:177], v[192:195], v[50:53]
	v_mfma_f32_16x16x32_bf16 v[38:41], v[166:169], v[200:203], v[38:41]
	v_mfma_f32_16x16x32_bf16 v[34:37], v[174:177], v[200:203], v[34:37]
	v_mfma_f32_16x16x32_bf16 v[22:25], v[166:169], v[208:211], v[22:25]
	v_mfma_f32_16x16x32_bf16 v[18:21], v[174:177], v[208:211], v[18:21]
	v_mfma_f32_16x16x32_bf16 v[6:9], v[166:169], v[216:219], v[6:9]
	v_mfma_f32_16x16x32_bf16 v[2:5], v[174:177], v[216:219], v[2:5]
	s_barrier
	s_setprio 0
	s_add_i32 s70, s70, 2
	s_add_u32 s46, s46, 0x100
	s_addc_u32 s47, s47, 0
	s_add_u32 s68, s68, 0x100
	s_addc_u32 s69, s69, 0
	s_cmp_gt_u32 s70, 29
.LBB0_1408:
	ds_read_b128 v[130:133], v183
	ds_read_b128 v[134:137], v183 offset:1024
	ds_read_b128 v[138:141], v183 offset:2048
	ds_read_b128 v[142:145], v183 offset:3072
	ds_read_b128 v[162:165], v184
	ds_read_b128 v[166:169], v184 offset:1024
	ds_read_b128 v[170:173], v184 offset:2048
	ds_read_b128 v[174:177], v184 offset:3072
	ds_read_b128 v[188:191], v185
	ds_read_b128 v[192:195], v185 offset:1024
	ds_read_b128 v[196:199], v185 offset:2048
	ds_read_b128 v[200:203], v185 offset:3072
	ds_read_b128 v[204:207], v185 offset:4096
	ds_read_b128 v[208:211], v185 offset:5120
	ds_read_b128 v[212:215], v185 offset:6144
	ds_read_b128 v[216:219], v185 offset:7168
	s_add_u32 s48, s46, 0xfff80080
	s_addc_u32 s49, s47, -1
	s_cmp_eq_u32 s70, 28
	s_cselect_b32 s53, s39, s49
	s_cselect_b32 s52, s66, s48
	s_cselect_b32 s49, s37, s69
	s_cselect_b32 s48, s67, s68
	s_add_i32 m0, s45, 0xc000
	s_nop 0
	global_load_lds_dwordx4 v154, s[46:47]
	s_add_i32 m0, s45, 0xe000
	s_nop 0
	global_load_lds_dwordx4 v156, s[46:47]
	s_waitcnt vmcnt(8)
	s_waitcnt lgkmcnt(0)
	s_setprio 1
	s_barrier
	v_mfma_f32_16x16x32_bf16 v[126:129], v[130:133], v[188:191], v[126:129]
	v_mfma_f32_16x16x32_bf16 v[122:125], v[138:141], v[188:191], v[122:125]
	v_mfma_f32_16x16x32_bf16 v[110:113], v[130:133], v[196:199], v[110:113]
	v_mfma_f32_16x16x32_bf16 v[106:109], v[138:141], v[196:199], v[106:109]
	v_mfma_f32_16x16x32_bf16 v[94:97], v[130:133], v[204:207], v[94:97]
	v_mfma_f32_16x16x32_bf16 v[90:93], v[138:141], v[204:207], v[90:93]
	v_mfma_f32_16x16x32_bf16 v[78:81], v[130:133], v[212:215], v[78:81]
	v_mfma_f32_16x16x32_bf16 v[74:77], v[138:141], v[212:215], v[74:77]
	v_mfma_f32_16x16x32_bf16 v[126:129], v[134:137], v[192:195], v[126:129]
	v_mfma_f32_16x16x32_bf16 v[122:125], v[142:145], v[192:195], v[122:125]
	v_mfma_f32_16x16x32_bf16 v[110:113], v[134:137], v[200:203], v[110:113]
	v_mfma_f32_16x16x32_bf16 v[106:109], v[142:145], v[200:203], v[106:109]
	v_mfma_f32_16x16x32_bf16 v[94:97], v[134:137], v[208:211], v[94:97]
	v_mfma_f32_16x16x32_bf16 v[90:93], v[142:145], v[208:211], v[90:93]
	v_mfma_f32_16x16x32_bf16 v[78:81], v[134:137], v[216:219], v[78:81]
	v_mfma_f32_16x16x32_bf16 v[74:77], v[142:145], v[216:219], v[74:77]
	s_setprio 0
	s_setprio 1
	v_mfma_f32_16x16x32_bf16 v[118:121], v[162:165], v[188:191], v[118:121]
	v_mfma_f32_16x16x32_bf16 v[114:117], v[170:173], v[188:191], v[114:117]
	v_mfma_f32_16x16x32_bf16 v[102:105], v[162:165], v[196:199], v[102:105]
	v_mfma_f32_16x16x32_bf16 v[98:101], v[170:173], v[196:199], v[98:101]
	v_mfma_f32_16x16x32_bf16 v[86:89], v[162:165], v[204:207], v[86:89]
	v_mfma_f32_16x16x32_bf16 v[82:85], v[170:173], v[204:207], v[82:85]
	v_mfma_f32_16x16x32_bf16 v[70:73], v[162:165], v[212:215], v[70:73]
	v_mfma_f32_16x16x32_bf16 v[66:69], v[170:173], v[212:215], v[66:69]
	v_mfma_f32_16x16x32_bf16 v[118:121], v[166:169], v[192:195], v[118:121]
	v_mfma_f32_16x16x32_bf16 v[114:117], v[174:177], v[192:195], v[114:117]
	v_mfma_f32_16x16x32_bf16 v[102:105], v[166:169], v[200:203], v[102:105]
	v_mfma_f32_16x16x32_bf16 v[98:101], v[174:177], v[200:203], v[98:101]
	v_mfma_f32_16x16x32_bf16 v[86:89], v[166:169], v[208:211], v[86:89]
	v_mfma_f32_16x16x32_bf16 v[82:85], v[174:177], v[208:211], v[82:85]
	v_mfma_f32_16x16x32_bf16 v[70:73], v[166:169], v[216:219], v[70:73]
	v_mfma_f32_16x16x32_bf16 v[66:69], v[174:177], v[216:219], v[66:69]
	s_barrier
	s_setprio 0
	ds_read_b128 v[188:191], v185 offset:16384
	ds_read_b128 v[192:195], v185 offset:17408
	ds_read_b128 v[196:199], v185 offset:18432
	ds_read_b128 v[200:203], v185 offset:19456
	ds_read_b128 v[204:207], v185 offset:20480
	ds_read_b128 v[208:211], v185 offset:21504
	ds_read_b128 v[212:215], v185 offset:22528
	ds_read_b128 v[216:219], v185 offset:23552
	s_add_i32 s71, s63, s54
	s_add_u32 s98, s48, 0x80
	s_addc_u32 s99, s49, 0
	s_mov_b32 m0, s71
	s_nop 0
	global_load_lds_dwordx4 v148, s[48:49]
	s_add_i32 m0, s71, 0x2000
	s_add_u32 s72, s48, 0x80000
	s_addc_u32 s73, s49, 0
	s_add_i32 s71, s64, s54
	global_load_lds_dwordx4 v152, s[48:49]
	s_mov_b32 m0, s71
	s_nop 0
	global_load_lds_dwordx4 v148, s[72:73]
	s_add_i32 m0, s71, 0x2000
	s_nop 0
	global_load_lds_dwordx4 v152, s[72:73]
	s_add_u32 s100, s52, 0x80
	s_addc_u32 s101, s53, 0
	s_mov_b32 m0, s45
	s_nop 0
	global_load_lds_dwordx4 v146, s[52:53]
	s_mov_b32 m0, s55
	s_nop 0
	global_load_lds_dwordx4 v150, s[52:53]
	s_waitcnt vmcnt(8)
	s_waitcnt lgkmcnt(0)
	s_setprio 1
	s_barrier
	v_mfma_f32_16x16x32_bf16 v[62:65], v[130:133], v[188:191], v[62:65]
	v_mfma_f32_16x16x32_bf16 v[58:61], v[138:141], v[188:191], v[58:61]
	v_mfma_f32_16x16x32_bf16 v[46:49], v[130:133], v[196:199], v[46:49]
	v_mfma_f32_16x16x32_bf16 v[42:45], v[138:141], v[196:199], v[42:45]
	v_mfma_f32_16x16x32_bf16 v[30:33], v[130:133], v[204:207], v[30:33]
	v_mfma_f32_16x16x32_bf16 v[26:29], v[138:141], v[204:207], v[26:29]
	v_mfma_f32_16x16x32_bf16 v[14:17], v[130:133], v[212:215], v[14:17]
	v_mfma_f32_16x16x32_bf16 v[10:13], v[138:141], v[212:215], v[10:13]
	v_mfma_f32_16x16x32_bf16 v[62:65], v[134:137], v[192:195], v[62:65]
	v_mfma_f32_16x16x32_bf16 v[58:61], v[142:145], v[192:195], v[58:61]
	v_mfma_f32_16x16x32_bf16 v[46:49], v[134:137], v[200:203], v[46:49]
	v_mfma_f32_16x16x32_bf16 v[42:45], v[142:145], v[200:203], v[42:45]
	v_mfma_f32_16x16x32_bf16 v[30:33], v[134:137], v[208:211], v[30:33]
	v_mfma_f32_16x16x32_bf16 v[26:29], v[142:145], v[208:211], v[26:29]
	v_mfma_f32_16x16x32_bf16 v[14:17], v[134:137], v[216:219], v[14:17]
	v_mfma_f32_16x16x32_bf16 v[10:13], v[142:145], v[216:219], v[10:13]
	s_setprio 0
	s_setprio 1
	v_mfma_f32_16x16x32_bf16 v[54:57], v[162:165], v[188:191], v[54:57]
	v_mfma_f32_16x16x32_bf16 v[50:53], v[170:173], v[188:191], v[50:53]
	v_mfma_f32_16x16x32_bf16 v[38:41], v[162:165], v[196:199], v[38:41]
	v_mfma_f32_16x16x32_bf16 v[34:37], v[170:173], v[196:199], v[34:37]
	v_mfma_f32_16x16x32_bf16 v[22:25], v[162:165], v[204:207], v[22:25]
	v_mfma_f32_16x16x32_bf16 v[18:21], v[170:173], v[204:207], v[18:21]
	v_mfma_f32_16x16x32_bf16 v[6:9], v[162:165], v[212:215], v[6:9]
	v_mfma_f32_16x16x32_bf16 v[2:5], v[170:173], v[212:215], v[2:5]
	v_mfma_f32_16x16x32_bf16 v[54:57], v[166:169], v[192:195], v[54:57]
	v_mfma_f32_16x16x32_bf16 v[50:53], v[174:177], v[192:195], v[50:53]
	v_mfma_f32_16x16x32_bf16 v[38:41], v[166:169], v[200:203], v[38:41]
	v_mfma_f32_16x16x32_bf16 v[34:37], v[174:177], v[200:203], v[34:37]
	v_mfma_f32_16x16x32_bf16 v[22:25], v[166:169], v[208:211], v[22:25]
	v_mfma_f32_16x16x32_bf16 v[18:21], v[174:177], v[208:211], v[18:21]
	v_mfma_f32_16x16x32_bf16 v[6:9], v[166:169], v[216:219], v[6:9]
	v_mfma_f32_16x16x32_bf16 v[2:5], v[174:177], v[216:219], v[2:5]
	s_barrier
	s_setprio 0
	ds_read_b128 v[130:133], v183 offset:32768
	ds_read_b128 v[134:137], v183 offset:33792
	ds_read_b128 v[138:141], v183 offset:34816
	ds_read_b128 v[142:145], v183 offset:35840
	ds_read_b128 v[162:165], v184 offset:32768
	ds_read_b128 v[166:169], v184 offset:33792
	ds_read_b128 v[170:173], v184 offset:34816
	ds_read_b128 v[174:177], v184 offset:35840
	ds_read_b128 v[188:191], v185 offset:32768
	ds_read_b128 v[192:195], v185 offset:33792
	ds_read_b128 v[196:199], v185 offset:34816
	ds_read_b128 v[200:203], v185 offset:35840
	ds_read_b128 v[204:207], v185 offset:36864
	ds_read_b128 v[208:211], v185 offset:37888
	ds_read_b128 v[212:215], v185 offset:38912
	ds_read_b128 v[216:219], v185 offset:39936
	s_add_i32 s71, 0, 0x18000
	s_add_i32 s72, 0, 0x1c000
	s_add_u32 s52, s52, 0x80000
	s_addc_u32 s53, s53, 0
	s_mov_b32 m0, s56
	s_nop 0
	global_load_lds_dwordx4 v146, s[52:53]
	s_mov_b32 m0, s57
	s_nop 0
	global_load_lds_dwordx4 v150, s[52:53]
	s_waitcnt vmcnt(8)
	s_waitcnt lgkmcnt(0)
	s_setprio 1
	s_barrier
	v_mfma_f32_16x16x32_bf16 v[126:129], v[130:133], v[188:191], v[126:129]
	v_mfma_f32_16x16x32_bf16 v[122:125], v[138:141], v[188:191], v[122:125]
	v_mfma_f32_16x16x32_bf16 v[110:113], v[130:133], v[196:199], v[110:113]
	v_mfma_f32_16x16x32_bf16 v[106:109], v[138:141], v[196:199], v[106:109]
	v_mfma_f32_16x16x32_bf16 v[94:97], v[130:133], v[204:207], v[94:97]
	v_mfma_f32_16x16x32_bf16 v[90:93], v[138:141], v[204:207], v[90:93]
	v_mfma_f32_16x16x32_bf16 v[78:81], v[130:133], v[212:215], v[78:81]
	v_mfma_f32_16x16x32_bf16 v[74:77], v[138:141], v[212:215], v[74:77]
	v_mfma_f32_16x16x32_bf16 v[126:129], v[134:137], v[192:195], v[126:129]
	v_mfma_f32_16x16x32_bf16 v[122:125], v[142:145], v[192:195], v[122:125]
	v_mfma_f32_16x16x32_bf16 v[110:113], v[134:137], v[200:203], v[110:113]
	v_mfma_f32_16x16x32_bf16 v[106:109], v[142:145], v[200:203], v[106:109]
	v_mfma_f32_16x16x32_bf16 v[94:97], v[134:137], v[208:211], v[94:97]
	v_mfma_f32_16x16x32_bf16 v[90:93], v[142:145], v[208:211], v[90:93]
	v_mfma_f32_16x16x32_bf16 v[78:81], v[134:137], v[216:219], v[78:81]
	v_mfma_f32_16x16x32_bf16 v[74:77], v[142:145], v[216:219], v[74:77]
	s_setprio 0
	s_setprio 1
	v_mfma_f32_16x16x32_bf16 v[118:121], v[162:165], v[188:191], v[118:121]
	v_mfma_f32_16x16x32_bf16 v[114:117], v[170:173], v[188:191], v[114:117]
	v_mfma_f32_16x16x32_bf16 v[102:105], v[162:165], v[196:199], v[102:105]
	v_mfma_f32_16x16x32_bf16 v[98:101], v[170:173], v[196:199], v[98:101]
	v_mfma_f32_16x16x32_bf16 v[86:89], v[162:165], v[204:207], v[86:89]
	v_mfma_f32_16x16x32_bf16 v[82:85], v[170:173], v[204:207], v[82:85]
	v_mfma_f32_16x16x32_bf16 v[70:73], v[162:165], v[212:215], v[70:73]
	v_mfma_f32_16x16x32_bf16 v[66:69], v[170:173], v[212:215], v[66:69]
	v_mfma_f32_16x16x32_bf16 v[118:121], v[166:169], v[192:195], v[118:121]
	v_mfma_f32_16x16x32_bf16 v[114:117], v[174:177], v[192:195], v[114:117]
	v_mfma_f32_16x16x32_bf16 v[102:105], v[166:169], v[200:203], v[102:105]
	v_mfma_f32_16x16x32_bf16 v[98:101], v[174:177], v[200:203], v[98:101]
	v_mfma_f32_16x16x32_bf16 v[86:89], v[166:169], v[208:211], v[86:89]
	v_mfma_f32_16x16x32_bf16 v[82:85], v[174:177], v[208:211], v[82:85]
	v_mfma_f32_16x16x32_bf16 v[70:73], v[166:169], v[216:219], v[70:73]
	v_mfma_f32_16x16x32_bf16 v[66:69], v[174:177], v[216:219], v[66:69]
	s_barrier
	s_setprio 0
	ds_read_b128 v[188:191], v185 offset:49152
	ds_read_b128 v[192:195], v185 offset:50176
	ds_read_b128 v[196:199], v185 offset:51200
	ds_read_b128 v[200:203], v185 offset:52224
	ds_read_b128 v[204:207], v185 offset:53248
	ds_read_b128 v[208:211], v185 offset:54272
	ds_read_b128 v[212:215], v185 offset:55296
	ds_read_b128 v[216:219], v185 offset:56320
	s_add_i32 s52, s71, s54
	s_mov_b32 m0, s52
	s_nop 0
	global_load_lds_dwordx4 v148, s[98:99]
	s_add_i32 m0, s52, 0x2000
	s_add_u32 s48, s48, 0x80080
	s_addc_u32 s49, s49, 0
	s_add_i32 s52, s72, s54
	global_load_lds_dwordx4 v152, s[98:99]
	s_mov_b32 m0, s52
	s_nop 0
	global_load_lds_dwordx4 v148, s[48:49]
	s_add_i32 m0, s52, 0x2000
	s_nop 0
	global_load_lds_dwordx4 v152, s[48:49]
	s_mov_b32 m0, s60
	s_nop 0
	global_load_lds_dwordx4 v146, s[100:101]
	s_mov_b32 m0, s61
	s_nop 0
	global_load_lds_dwordx4 v150, s[100:101]
	s_add_i32 s70, s70, 2
	s_add_u32 s46, s46, 0x100
	s_addc_u32 s47, s47, 0
	s_add_u32 s68, s68, 0x100
	s_addc_u32 s69, s69, 0
	s_cmp_gt_u32 s70, 29
	s_waitcnt vmcnt(8)
	s_waitcnt lgkmcnt(0)
	s_setprio 1
	s_barrier
	v_mfma_f32_16x16x32_bf16 v[62:65], v[130:133], v[188:191], v[62:65]
	v_mfma_f32_16x16x32_bf16 v[58:61], v[138:141], v[188:191], v[58:61]
	v_mfma_f32_16x16x32_bf16 v[46:49], v[130:133], v[196:199], v[46:49]
	v_mfma_f32_16x16x32_bf16 v[42:45], v[138:141], v[196:199], v[42:45]
	v_mfma_f32_16x16x32_bf16 v[30:33], v[130:133], v[204:207], v[30:33]
	v_mfma_f32_16x16x32_bf16 v[26:29], v[138:141], v[204:207], v[26:29]
	v_mfma_f32_16x16x32_bf16 v[14:17], v[130:133], v[212:215], v[14:17]
	v_mfma_f32_16x16x32_bf16 v[10:13], v[138:141], v[212:215], v[10:13]
	v_mfma_f32_16x16x32_bf16 v[62:65], v[134:137], v[192:195], v[62:65]
	v_mfma_f32_16x16x32_bf16 v[58:61], v[142:145], v[192:195], v[58:61]
	v_mfma_f32_16x16x32_bf16 v[46:49], v[134:137], v[200:203], v[46:49]
	v_mfma_f32_16x16x32_bf16 v[42:45], v[142:145], v[200:203], v[42:45]
	v_mfma_f32_16x16x32_bf16 v[30:33], v[134:137], v[208:211], v[30:33]
	v_mfma_f32_16x16x32_bf16 v[26:29], v[142:145], v[208:211], v[26:29]
	v_mfma_f32_16x16x32_bf16 v[14:17], v[134:137], v[216:219], v[14:17]
	v_mfma_f32_16x16x32_bf16 v[10:13], v[142:145], v[216:219], v[10:13]
	s_setprio 0
	s_setprio 1
	v_mfma_f32_16x16x32_bf16 v[54:57], v[162:165], v[188:191], v[54:57]
	v_mfma_f32_16x16x32_bf16 v[50:53], v[170:173], v[188:191], v[50:53]
	v_mfma_f32_16x16x32_bf16 v[38:41], v[162:165], v[196:199], v[38:41]
	v_mfma_f32_16x16x32_bf16 v[34:37], v[170:173], v[196:199], v[34:37]
	v_mfma_f32_16x16x32_bf16 v[22:25], v[162:165], v[204:207], v[22:25]
	v_mfma_f32_16x16x32_bf16 v[18:21], v[170:173], v[204:207], v[18:21]
	v_mfma_f32_16x16x32_bf16 v[6:9], v[162:165], v[212:215], v[6:9]
	v_mfma_f32_16x16x32_bf16 v[2:5], v[170:173], v[212:215], v[2:5]
	v_mfma_f32_16x16x32_bf16 v[54:57], v[166:169], v[192:195], v[54:57]
	v_mfma_f32_16x16x32_bf16 v[50:53], v[174:177], v[192:195], v[50:53]
	v_mfma_f32_16x16x32_bf16 v[38:41], v[166:169], v[200:203], v[38:41]
	v_mfma_f32_16x16x32_bf16 v[34:37], v[174:177], v[200:203], v[34:37]
	v_mfma_f32_16x16x32_bf16 v[22:25], v[166:169], v[208:211], v[22:25]
	v_mfma_f32_16x16x32_bf16 v[18:21], v[174:177], v[208:211], v[18:21]
	v_mfma_f32_16x16x32_bf16 v[6:9], v[166:169], v[216:219], v[6:9]
	v_mfma_f32_16x16x32_bf16 v[2:5], v[174:177], v[216:219], v[2:5]
	s_barrier
	s_setprio 0
	s_cbranch_scc0 .LBB0_1408
	s_and_b64 vcc, exec, s[34:35]
	s_cbranch_vccz .LBB0_1411
	s_barrier

.LBB0_1478:
	s_ashr_i32 s11, s10, 31
	s_lshl_b64 s[6:7], s[10:11], 20
	s_add_u32 s38, s19, s6
	s_addc_u32 s39, s22, s7
	s_and_b64 s[6:7], s[2:3], exec
	s_cselect_b32 s9, s39, s1
	s_cselect_b32 s11, s38, s0
	s_ashr_i32 s37, s36, 31
	s_lshl_b64 s[6:7], s[36:37], 20
	s_add_u32 s40, s23, s6
	s_addc_u32 s41, s28, s7
	s_and_b64 s[6:7], s[2:3], exec
	s_cselect_b32 s37, s41, s5
	s_cselect_b32 s60, s40, s4
	s_add_u32 s0, s0, 0x80080
	s_addc_u32 s1, s1, 0
	s_add_u32 s61, s4, 0x100
	s_addc_u32 s62, s5, 0
	s_mov_b32 s63, -2
	s_add_u32 s4, s0, 0xfff80080
	s_addc_u32 s5, s1, -1
	s_cmp_eq_u32 s63, 28
	s_cselect_b32 s7, s9, s5
	s_cselect_b32 s6, s11, s4
	s_cselect_b32 s5, s37, s62
	s_cselect_b32 s4, s60, s61
	s_add_i32 m0, s44, 0xc000
	s_nop 0
	global_load_lds_dwordx4 v146, s[0:1]
	s_add_i32 m0, s44, 0xe000
	s_nop 0
	global_load_lds_dwordx4 v148, s[0:1]
	s_waitcnt vmcnt(8)
	s_waitcnt lgkmcnt(0)
	s_setprio 1
	s_barrier
	v_mfma_f32_16x16x32_bf16 v[128:131], v[132:135], v[198:201], 0
	v_mfma_f32_16x16x32_bf16 v[124:127], v[166:169], v[198:201], 0
	v_mfma_f32_16x16x32_bf16 v[112:115], v[132:135], v[206:209], 0
	v_mfma_f32_16x16x32_bf16 v[108:111], v[166:169], v[206:209], 0
	v_mfma_f32_16x16x32_bf16 v[96:99], v[132:135], v[214:217], 0
	v_mfma_f32_16x16x32_bf16 v[92:95], v[166:169], v[214:217], 0
	v_mfma_f32_16x16x32_bf16 v[80:83], v[132:135], v[222:225], 0
	v_mfma_f32_16x16x32_bf16 v[76:79], v[166:169], v[222:225], 0
	v_mfma_f32_16x16x32_bf16 v[128:131], v[158:161], v[202:205], v[128:131]
	v_mfma_f32_16x16x32_bf16 v[124:127], v[170:173], v[202:205], v[124:127]
	v_mfma_f32_16x16x32_bf16 v[112:115], v[158:161], v[210:213], v[112:115]
	v_mfma_f32_16x16x32_bf16 v[108:111], v[170:173], v[210:213], v[108:111]
	v_mfma_f32_16x16x32_bf16 v[96:99], v[158:161], v[218:221], v[96:99]
	v_mfma_f32_16x16x32_bf16 v[92:95], v[170:173], v[218:221], v[92:95]
	v_mfma_f32_16x16x32_bf16 v[80:83], v[158:161], v[226:229], v[80:83]
	v_mfma_f32_16x16x32_bf16 v[76:79], v[170:173], v[226:229], v[76:79]
	s_setprio 0
	s_setprio 1
	v_mfma_f32_16x16x32_bf16 v[120:123], v[182:185], v[198:201], 0
	v_mfma_f32_16x16x32_bf16 v[116:119], v[190:193], v[198:201], 0
	v_mfma_f32_16x16x32_bf16 v[104:107], v[182:185], v[206:209], 0
	v_mfma_f32_16x16x32_bf16 v[100:103], v[190:193], v[206:209], 0
	v_mfma_f32_16x16x32_bf16 v[88:91], v[182:185], v[214:217], 0
	v_mfma_f32_16x16x32_bf16 v[84:87], v[190:193], v[214:217], 0
	v_mfma_f32_16x16x32_bf16 v[72:75], v[182:185], v[222:225], 0
	v_mfma_f32_16x16x32_bf16 v[68:71], v[190:193], v[222:225], 0
	v_mfma_f32_16x16x32_bf16 v[120:123], v[186:189], v[202:205], v[120:123]
	v_mfma_f32_16x16x32_bf16 v[116:119], v[194:197], v[202:205], v[116:119]
	v_mfma_f32_16x16x32_bf16 v[104:107], v[186:189], v[210:213], v[104:107]
	v_mfma_f32_16x16x32_bf16 v[100:103], v[194:197], v[210:213], v[100:103]
	v_mfma_f32_16x16x32_bf16 v[88:91], v[186:189], v[218:221], v[88:91]
	v_mfma_f32_16x16x32_bf16 v[84:87], v[194:197], v[218:221], v[84:87]
	v_mfma_f32_16x16x32_bf16 v[72:75], v[186:189], v[226:229], v[72:75]
	v_mfma_f32_16x16x32_bf16 v[68:71], v[194:197], v[226:229], v[68:71]
	s_barrier
	s_setprio 0
	ds_read_b128 v[198:201], v176 offset:16384
	ds_read_b128 v[202:205], v176 offset:17408
	ds_read_b128 v[206:209], v176 offset:18432
	ds_read_b128 v[210:213], v176 offset:19456
	ds_read_b128 v[214:217], v176 offset:20480
	ds_read_b128 v[218:221], v176 offset:21504
	ds_read_b128 v[222:225], v176 offset:22528
	ds_read_b128 v[226:229], v176 offset:23552
	s_add_i32 s64, s54, s29
	s_add_u32 s98, s4, 0x80
	s_addc_u32 s99, s5, 0
	s_mov_b32 m0, s64
	s_nop 0
	global_load_lds_dwordx4 v142, s[4:5]
	s_add_i32 m0, s64, 0x2000
	s_add_u32 s64, s4, 0x80000
	s_addc_u32 s65, s5, 0
	s_add_i32 s66, s55, s29
	global_load_lds_dwordx4 v138, s[4:5]
	s_mov_b32 m0, s66
	s_nop 0
	global_load_lds_dwordx4 v142, s[64:65]
	s_add_i32 m0, s66, 0x2000
	s_nop 0
	global_load_lds_dwordx4 v138, s[64:65]
	s_add_u32 s100, s6, 0x80
	s_addc_u32 s101, s7, 0
	s_mov_b32 m0, s44
	s_nop 0
	global_load_lds_dwordx4 v144, s[6:7]
	s_mov_b32 m0, s45
	s_nop 0
	global_load_lds_dwordx4 v140, s[6:7]
	s_waitcnt vmcnt(8)
	s_waitcnt lgkmcnt(0)
	s_setprio 1
	s_barrier
	v_mfma_f32_16x16x32_bf16 v[62:65], v[132:135], v[198:201], 0
	v_mfma_f32_16x16x32_bf16 v[58:61], v[166:169], v[198:201], 0
	v_mfma_f32_16x16x32_bf16 v[46:49], v[132:135], v[206:209], 0
	v_mfma_f32_16x16x32_bf16 v[42:45], v[166:169], v[206:209], 0
	v_mfma_f32_16x16x32_bf16 v[30:33], v[132:135], v[214:217], 0
	v_mfma_f32_16x16x32_bf16 v[26:29], v[166:169], v[214:217], 0
	v_mfma_f32_16x16x32_bf16 v[14:17], v[132:135], v[222:225], 0
	v_mfma_f32_16x16x32_bf16 v[10:13], v[166:169], v[222:225], 0
	v_mfma_f32_16x16x32_bf16 v[62:65], v[158:161], v[202:205], v[62:65]
	v_mfma_f32_16x16x32_bf16 v[58:61], v[170:173], v[202:205], v[58:61]
	v_mfma_f32_16x16x32_bf16 v[46:49], v[158:161], v[210:213], v[46:49]
	v_mfma_f32_16x16x32_bf16 v[42:45], v[170:173], v[210:213], v[42:45]
	v_mfma_f32_16x16x32_bf16 v[30:33], v[158:161], v[218:221], v[30:33]
	v_mfma_f32_16x16x32_bf16 v[26:29], v[170:173], v[218:221], v[26:29]
	v_mfma_f32_16x16x32_bf16 v[14:17], v[158:161], v[226:229], v[14:17]
	v_mfma_f32_16x16x32_bf16 v[10:13], v[170:173], v[226:229], v[10:13]
	s_setprio 0
	s_setprio 1
	v_mfma_f32_16x16x32_bf16 v[54:57], v[182:185], v[198:201], 0
	v_mfma_f32_16x16x32_bf16 v[50:53], v[190:193], v[198:201], 0
	v_mfma_f32_16x16x32_bf16 v[38:41], v[182:185], v[206:209], 0
	v_mfma_f32_16x16x32_bf16 v[34:37], v[190:193], v[206:209], 0
	v_mfma_f32_16x16x32_bf16 v[22:25], v[182:185], v[214:217], 0
	v_mfma_f32_16x16x32_bf16 v[18:21], v[190:193], v[214:217], 0
	v_mfma_f32_16x16x32_bf16 v[6:9], v[182:185], v[222:225], 0
	v_mfma_f32_16x16x32_bf16 v[2:5], v[190:193], v[222:225], 0
	v_mfma_f32_16x16x32_bf16 v[54:57], v[186:189], v[202:205], v[54:57]
	v_mfma_f32_16x16x32_bf16 v[50:53], v[194:197], v[202:205], v[50:53]
	v_mfma_f32_16x16x32_bf16 v[38:41], v[186:189], v[210:213], v[38:41]
	v_mfma_f32_16x16x32_bf16 v[34:37], v[194:197], v[210:213], v[34:37]
	v_mfma_f32_16x16x32_bf16 v[22:25], v[186:189], v[218:221], v[22:25]
	v_mfma_f32_16x16x32_bf16 v[18:21], v[194:197], v[218:221], v[18:21]
	v_mfma_f32_16x16x32_bf16 v[6:9], v[186:189], v[226:229], v[6:9]
	v_mfma_f32_16x16x32_bf16 v[2:5], v[194:197], v[226:229], v[2:5]
	s_barrier
	s_setprio 0
	ds_read_b128 v[132:135], v174 offset:32768
	ds_read_b128 v[158:161], v174 offset:33792
	ds_read_b128 v[166:169], v174 offset:34816
	ds_read_b128 v[170:173], v174 offset:35840
	ds_read_b128 v[182:185], v175 offset:32768
	ds_read_b128 v[186:189], v175 offset:33792
	ds_read_b128 v[190:193], v175 offset:34816
	ds_read_b128 v[194:197], v175 offset:35840
	ds_read_b128 v[198:201], v176 offset:32768
	ds_read_b128 v[202:205], v176 offset:33792
	ds_read_b128 v[206:209], v176 offset:34816
	ds_read_b128 v[210:213], v176 offset:35840
	ds_read_b128 v[214:217], v176 offset:36864
	ds_read_b128 v[218:221], v176 offset:37888
	ds_read_b128 v[222:225], v176 offset:38912
	ds_read_b128 v[226:229], v176 offset:39936
	s_add_i32 s64, 0, 0x18000
	s_add_i32 s65, 0, 0x1c000
	s_add_u32 s6, s6, 0x80000
	s_addc_u32 s7, s7, 0
	s_mov_b32 m0, s46
	s_nop 0
	global_load_lds_dwordx4 v144, s[6:7]
	s_mov_b32 m0, s47
	s_nop 0
	global_load_lds_dwordx4 v140, s[6:7]
	s_waitcnt vmcnt(8)
	s_waitcnt lgkmcnt(0)
	s_setprio 1
	s_barrier
	v_mfma_f32_16x16x32_bf16 v[128:131], v[132:135], v[198:201], v[128:131]
	v_mfma_f32_16x16x32_bf16 v[124:127], v[166:169], v[198:201], v[124:127]
	v_mfma_f32_16x16x32_bf16 v[112:115], v[132:135], v[206:209], v[112:115]
	v_mfma_f32_16x16x32_bf16 v[108:111], v[166:169], v[206:209], v[108:111]
	v_mfma_f32_16x16x32_bf16 v[96:99], v[132:135], v[214:217], v[96:99]
	v_mfma_f32_16x16x32_bf16 v[92:95], v[166:169], v[214:217], v[92:95]
	v_mfma_f32_16x16x32_bf16 v[80:83], v[132:135], v[222:225], v[80:83]
	v_mfma_f32_16x16x32_bf16 v[76:79], v[166:169], v[222:225], v[76:79]
	v_mfma_f32_16x16x32_bf16 v[128:131], v[158:161], v[202:205], v[128:131]
	v_mfma_f32_16x16x32_bf16 v[124:127], v[170:173], v[202:205], v[124:127]
	v_mfma_f32_16x16x32_bf16 v[112:115], v[158:161], v[210:213], v[112:115]
	v_mfma_f32_16x16x32_bf16 v[108:111], v[170:173], v[210:213], v[108:111]
	v_mfma_f32_16x16x32_bf16 v[96:99], v[158:161], v[218:221], v[96:99]
	v_mfma_f32_16x16x32_bf16 v[92:95], v[170:173], v[218:221], v[92:95]
	v_mfma_f32_16x16x32_bf16 v[80:83], v[158:161], v[226:229], v[80:83]
	v_mfma_f32_16x16x32_bf16 v[76:79], v[170:173], v[226:229], v[76:79]
	s_setprio 0
	s_setprio 1
	v_mfma_f32_16x16x32_bf16 v[120:123], v[182:185], v[198:201], v[120:123]
	v_mfma_f32_16x16x32_bf16 v[116:119], v[190:193], v[198:201], v[116:119]
	v_mfma_f32_16x16x32_bf16 v[104:107], v[182:185], v[206:209], v[104:107]
	v_mfma_f32_16x16x32_bf16 v[100:103], v[190:193], v[206:209], v[100:103]
	v_mfma_f32_16x16x32_bf16 v[88:91], v[182:185], v[214:217], v[88:91]
	v_mfma_f32_16x16x32_bf16 v[84:87], v[190:193], v[214:217], v[84:87]
	v_mfma_f32_16x16x32_bf16 v[72:75], v[182:185], v[222:225], v[72:75]
	v_mfma_f32_16x16x32_bf16 v[68:71], v[190:193], v[222:225], v[68:71]
	v_mfma_f32_16x16x32_bf16 v[120:123], v[186:189], v[202:205], v[120:123]
	v_mfma_f32_16x16x32_bf16 v[116:119], v[194:197], v[202:205], v[116:119]
	v_mfma_f32_16x16x32_bf16 v[104:107], v[186:189], v[210:213], v[104:107]
	v_mfma_f32_16x16x32_bf16 v[100:103], v[194:197], v[210:213], v[100:103]
	v_mfma_f32_16x16x32_bf16 v[88:91], v[186:189], v[218:221], v[88:91]
	v_mfma_f32_16x16x32_bf16 v[84:87], v[194:197], v[218:221], v[84:87]
	v_mfma_f32_16x16x32_bf16 v[72:75], v[186:189], v[226:229], v[72:75]
	v_mfma_f32_16x16x32_bf16 v[68:71], v[194:197], v[226:229], v[68:71]
	s_barrier
	s_setprio 0
	ds_read_b128 v[198:201], v176 offset:49152
	ds_read_b128 v[202:205], v176 offset:50176
	ds_read_b128 v[206:209], v176 offset:51200
	ds_read_b128 v[210:213], v176 offset:52224
	ds_read_b128 v[214:217], v176 offset:53248
	ds_read_b128 v[218:221], v176 offset:54272
	ds_read_b128 v[222:225], v176 offset:55296
	ds_read_b128 v[226:229], v176 offset:56320
	s_add_i32 s6, s64, s29
	s_mov_b32 m0, s6
	s_nop 0
	global_load_lds_dwordx4 v142, s[98:99]
	s_add_i32 m0, s6, 0x2000
	s_add_u32 s4, s4, 0x80080
	s_addc_u32 s5, s5, 0
	s_add_i32 s6, s65, s29
	global_load_lds_dwordx4 v138, s[98:99]
	s_mov_b32 m0, s6
	s_nop 0
	global_load_lds_dwordx4 v142, s[4:5]
	s_add_i32 m0, s6, 0x2000
	s_nop 0
	global_load_lds_dwordx4 v138, s[4:5]
	s_mov_b32 m0, s48
	s_nop 0
	global_load_lds_dwordx4 v144, s[100:101]
	s_mov_b32 m0, s49
	s_nop 0
	global_load_lds_dwordx4 v140, s[100:101]
	s_waitcnt vmcnt(8)
	s_waitcnt lgkmcnt(0)
	s_setprio 1
	s_barrier
	v_mfma_f32_16x16x32_bf16 v[62:65], v[132:135], v[198:201], v[62:65]
	v_mfma_f32_16x16x32_bf16 v[58:61], v[166:169], v[198:201], v[58:61]
	v_mfma_f32_16x16x32_bf16 v[46:49], v[132:135], v[206:209], v[46:49]
	v_mfma_f32_16x16x32_bf16 v[42:45], v[166:169], v[206:209], v[42:45]
	v_mfma_f32_16x16x32_bf16 v[30:33], v[132:135], v[214:217], v[30:33]
	v_mfma_f32_16x16x32_bf16 v[26:29], v[166:169], v[214:217], v[26:29]
	v_mfma_f32_16x16x32_bf16 v[14:17], v[132:135], v[222:225], v[14:17]
	v_mfma_f32_16x16x32_bf16 v[10:13], v[166:169], v[222:225], v[10:13]
	v_mfma_f32_16x16x32_bf16 v[62:65], v[158:161], v[202:205], v[62:65]
	v_mfma_f32_16x16x32_bf16 v[58:61], v[170:173], v[202:205], v[58:61]
	v_mfma_f32_16x16x32_bf16 v[46:49], v[158:161], v[210:213], v[46:49]
	v_mfma_f32_16x16x32_bf16 v[42:45], v[170:173], v[210:213], v[42:45]
	v_mfma_f32_16x16x32_bf16 v[30:33], v[158:161], v[218:221], v[30:33]
	v_mfma_f32_16x16x32_bf16 v[26:29], v[170:173], v[218:221], v[26:29]
	v_mfma_f32_16x16x32_bf16 v[14:17], v[158:161], v[226:229], v[14:17]
	v_mfma_f32_16x16x32_bf16 v[10:13], v[170:173], v[226:229], v[10:13]
	s_setprio 0
	s_setprio 1
	v_mfma_f32_16x16x32_bf16 v[54:57], v[182:185], v[198:201], v[54:57]
	v_mfma_f32_16x16x32_bf16 v[50:53], v[190:193], v[198:201], v[50:53]
	v_mfma_f32_16x16x32_bf16 v[38:41], v[182:185], v[206:209], v[38:41]
	v_mfma_f32_16x16x32_bf16 v[34:37], v[190:193], v[206:209], v[34:37]
	v_mfma_f32_16x16x32_bf16 v[22:25], v[182:185], v[214:217], v[22:25]
	v_mfma_f32_16x16x32_bf16 v[18:21], v[190:193], v[214:217], v[18:21]
	v_mfma_f32_16x16x32_bf16 v[6:9], v[182:185], v[222:225], v[6:9]
	v_mfma_f32_16x16x32_bf16 v[2:5], v[190:193], v[222:225], v[2:5]
	v_mfma_f32_16x16x32_bf16 v[54:57], v[186:189], v[202:205], v[54:57]
	v_mfma_f32_16x16x32_bf16 v[50:53], v[194:197], v[202:205], v[50:53]
	v_mfma_f32_16x16x32_bf16 v[38:41], v[186:189], v[210:213], v[38:41]
	v_mfma_f32_16x16x32_bf16 v[34:37], v[194:197], v[210:213], v[34:37]
	v_mfma_f32_16x16x32_bf16 v[22:25], v[186:189], v[218:221], v[22:25]
	v_mfma_f32_16x16x32_bf16 v[18:21], v[194:197], v[218:221], v[18:21]
	v_mfma_f32_16x16x32_bf16 v[6:9], v[186:189], v[226:229], v[6:9]
	v_mfma_f32_16x16x32_bf16 v[2:5], v[194:197], v[226:229], v[2:5]
	s_barrier
	s_setprio 0
	s_add_i32 s63, s63, 2
	s_add_u32 s0, s0, 0x100
	s_addc_u32 s1, s1, 0
	s_add_u32 s61, s61, 0x100
	s_addc_u32 s62, s62, 0
	s_cmp_gt_u32 s63, 29
.LBB0_1479:
	ds_read_b128 v[132:135], v174
	ds_read_b128 v[158:161], v174 offset:1024
	ds_read_b128 v[166:169], v174 offset:2048
	ds_read_b128 v[170:173], v174 offset:3072
	ds_read_b128 v[182:185], v175
	ds_read_b128 v[186:189], v175 offset:1024
	ds_read_b128 v[190:193], v175 offset:2048
	ds_read_b128 v[194:197], v175 offset:3072
	ds_read_b128 v[198:201], v176
	ds_read_b128 v[202:205], v176 offset:1024
	ds_read_b128 v[206:209], v176 offset:2048
	ds_read_b128 v[210:213], v176 offset:3072
	ds_read_b128 v[214:217], v176 offset:4096
	ds_read_b128 v[218:221], v176 offset:5120
	ds_read_b128 v[222:225], v176 offset:6144
	ds_read_b128 v[226:229], v176 offset:7168
	s_add_u32 s4, s0, 0xfff80080
	s_addc_u32 s5, s1, -1
	s_cmp_eq_u32 s63, 28
	s_cselect_b32 s7, s9, s5
	s_cselect_b32 s6, s11, s4
	s_cselect_b32 s5, s37, s62
	s_cselect_b32 s4, s60, s61
	s_add_i32 m0, s44, 0xc000
	s_nop 0
	global_load_lds_dwordx4 v146, s[0:1]
	s_add_i32 m0, s44, 0xe000
	s_nop 0
	global_load_lds_dwordx4 v148, s[0:1]
	s_waitcnt vmcnt(8)
	s_waitcnt lgkmcnt(0)
	s_setprio 1
	s_barrier
	v_mfma_f32_16x16x32_bf16 v[128:131], v[132:135], v[198:201], v[128:131]
	v_mfma_f32_16x16x32_bf16 v[124:127], v[166:169], v[198:201], v[124:127]
	v_mfma_f32_16x16x32_bf16 v[112:115], v[132:135], v[206:209], v[112:115]
	v_mfma_f32_16x16x32_bf16 v[108:111], v[166:169], v[206:209], v[108:111]
	v_mfma_f32_16x16x32_bf16 v[96:99], v[132:135], v[214:217], v[96:99]
	v_mfma_f32_16x16x32_bf16 v[92:95], v[166:169], v[214:217], v[92:95]
	v_mfma_f32_16x16x32_bf16 v[80:83], v[132:135], v[222:225], v[80:83]
	v_mfma_f32_16x16x32_bf16 v[76:79], v[166:169], v[222:225], v[76:79]
	v_mfma_f32_16x16x32_bf16 v[128:131], v[158:161], v[202:205], v[128:131]
	v_mfma_f32_16x16x32_bf16 v[124:127], v[170:173], v[202:205], v[124:127]
	v_mfma_f32_16x16x32_bf16 v[112:115], v[158:161], v[210:213], v[112:115]
	v_mfma_f32_16x16x32_bf16 v[108:111], v[170:173], v[210:213], v[108:111]
	v_mfma_f32_16x16x32_bf16 v[96:99], v[158:161], v[218:221], v[96:99]
	v_mfma_f32_16x16x32_bf16 v[92:95], v[170:173], v[218:221], v[92:95]
	v_mfma_f32_16x16x32_bf16 v[80:83], v[158:161], v[226:229], v[80:83]
	v_mfma_f32_16x16x32_bf16 v[76:79], v[170:173], v[226:229], v[76:79]
	s_setprio 0
	s_setprio 1
	v_mfma_f32_16x16x32_bf16 v[120:123], v[182:185], v[198:201], v[120:123]
	v_mfma_f32_16x16x32_bf16 v[116:119], v[190:193], v[198:201], v[116:119]
	v_mfma_f32_16x16x32_bf16 v[104:107], v[182:185], v[206:209], v[104:107]
	v_mfma_f32_16x16x32_bf16 v[100:103], v[190:193], v[206:209], v[100:103]
	v_mfma_f32_16x16x32_bf16 v[88:91], v[182:185], v[214:217], v[88:91]
	v_mfma_f32_16x16x32_bf16 v[84:87], v[190:193], v[214:217], v[84:87]
	v_mfma_f32_16x16x32_bf16 v[72:75], v[182:185], v[222:225], v[72:75]
	v_mfma_f32_16x16x32_bf16 v[68:71], v[190:193], v[222:225], v[68:71]
	v_mfma_f32_16x16x32_bf16 v[120:123], v[186:189], v[202:205], v[120:123]
	v_mfma_f32_16x16x32_bf16 v[116:119], v[194:197], v[202:205], v[116:119]
	v_mfma_f32_16x16x32_bf16 v[104:107], v[186:189], v[210:213], v[104:107]
	v_mfma_f32_16x16x32_bf16 v[100:103], v[194:197], v[210:213], v[100:103]
	v_mfma_f32_16x16x32_bf16 v[88:91], v[186:189], v[218:221], v[88:91]
	v_mfma_f32_16x16x32_bf16 v[84:87], v[194:197], v[218:221], v[84:87]
	v_mfma_f32_16x16x32_bf16 v[72:75], v[186:189], v[226:229], v[72:75]
	v_mfma_f32_16x16x32_bf16 v[68:71], v[194:197], v[226:229], v[68:71]
	s_barrier
	s_setprio 0
	ds_read_b128 v[198:201], v176 offset:16384
	ds_read_b128 v[202:205], v176 offset:17408
	ds_read_b128 v[206:209], v176 offset:18432
	ds_read_b128 v[210:213], v176 offset:19456
	ds_read_b128 v[214:217], v176 offset:20480
	ds_read_b128 v[218:221], v176 offset:21504
	ds_read_b128 v[222:225], v176 offset:22528
	ds_read_b128 v[226:229], v176 offset:23552
	s_add_i32 s64, s54, s29
	s_add_u32 s98, s4, 0x80
	s_addc_u32 s99, s5, 0
	s_mov_b32 m0, s64
	s_nop 0
	global_load_lds_dwordx4 v142, s[4:5]
	s_add_i32 m0, s64, 0x2000
	s_add_u32 s64, s4, 0x80000
	s_addc_u32 s65, s5, 0
	s_add_i32 s66, s55, s29
	global_load_lds_dwordx4 v138, s[4:5]
	s_mov_b32 m0, s66
	s_nop 0
	global_load_lds_dwordx4 v142, s[64:65]
	s_add_i32 m0, s66, 0x2000
	s_nop 0
	global_load_lds_dwordx4 v138, s[64:65]
	s_add_u32 s100, s6, 0x80
	s_addc_u32 s101, s7, 0
	s_mov_b32 m0, s44
	s_nop 0
	global_load_lds_dwordx4 v144, s[6:7]
	s_mov_b32 m0, s45
	s_nop 0
	global_load_lds_dwordx4 v140, s[6:7]
	s_waitcnt vmcnt(8)
	s_waitcnt lgkmcnt(0)
	s_setprio 1
	s_barrier
	v_mfma_f32_16x16x32_bf16 v[62:65], v[132:135], v[198:201], v[62:65]
	v_mfma_f32_16x16x32_bf16 v[58:61], v[166:169], v[198:201], v[58:61]
	v_mfma_f32_16x16x32_bf16 v[46:49], v[132:135], v[206:209], v[46:49]
	v_mfma_f32_16x16x32_bf16 v[42:45], v[166:169], v[206:209], v[42:45]
	v_mfma_f32_16x16x32_bf16 v[30:33], v[132:135], v[214:217], v[30:33]
	v_mfma_f32_16x16x32_bf16 v[26:29], v[166:169], v[214:217], v[26:29]
	v_mfma_f32_16x16x32_bf16 v[14:17], v[132:135], v[222:225], v[14:17]
	v_mfma_f32_16x16x32_bf16 v[10:13], v[166:169], v[222:225], v[10:13]
	v_mfma_f32_16x16x32_bf16 v[62:65], v[158:161], v[202:205], v[62:65]
	v_mfma_f32_16x16x32_bf16 v[58:61], v[170:173], v[202:205], v[58:61]
	v_mfma_f32_16x16x32_bf16 v[46:49], v[158:161], v[210:213], v[46:49]
	v_mfma_f32_16x16x32_bf16 v[42:45], v[170:173], v[210:213], v[42:45]
	v_mfma_f32_16x16x32_bf16 v[30:33], v[158:161], v[218:221], v[30:33]
	v_mfma_f32_16x16x32_bf16 v[26:29], v[170:173], v[218:221], v[26:29]
	v_mfma_f32_16x16x32_bf16 v[14:17], v[158:161], v[226:229], v[14:17]
	v_mfma_f32_16x16x32_bf16 v[10:13], v[170:173], v[226:229], v[10:13]
	s_setprio 0
	s_setprio 1
	v_mfma_f32_16x16x32_bf16 v[54:57], v[182:185], v[198:201], v[54:57]
	v_mfma_f32_16x16x32_bf16 v[50:53], v[190:193], v[198:201], v[50:53]
	v_mfma_f32_16x16x32_bf16 v[38:41], v[182:185], v[206:209], v[38:41]
	v_mfma_f32_16x16x32_bf16 v[34:37], v[190:193], v[206:209], v[34:37]
	v_mfma_f32_16x16x32_bf16 v[22:25], v[182:185], v[214:217], v[22:25]
	v_mfma_f32_16x16x32_bf16 v[18:21], v[190:193], v[214:217], v[18:21]
	v_mfma_f32_16x16x32_bf16 v[6:9], v[182:185], v[222:225], v[6:9]
	v_mfma_f32_16x16x32_bf16 v[2:5], v[190:193], v[222:225], v[2:5]
	v_mfma_f32_16x16x32_bf16 v[54:57], v[186:189], v[202:205], v[54:57]
	v_mfma_f32_16x16x32_bf16 v[50:53], v[194:197], v[202:205], v[50:53]
	v_mfma_f32_16x16x32_bf16 v[38:41], v[186:189], v[210:213], v[38:41]
	v_mfma_f32_16x16x32_bf16 v[34:37], v[194:197], v[210:213], v[34:37]
	v_mfma_f32_16x16x32_bf16 v[22:25], v[186:189], v[218:221], v[22:25]
	v_mfma_f32_16x16x32_bf16 v[18:21], v[194:197], v[218:221], v[18:21]
	v_mfma_f32_16x16x32_bf16 v[6:9], v[186:189], v[226:229], v[6:9]
	v_mfma_f32_16x16x32_bf16 v[2:5], v[194:197], v[226:229], v[2:5]
	s_barrier
	s_setprio 0
	ds_read_b128 v[132:135], v174 offset:32768
	ds_read_b128 v[158:161], v174 offset:33792
	ds_read_b128 v[166:169], v174 offset:34816
	ds_read_b128 v[170:173], v174 offset:35840
	ds_read_b128 v[182:185], v175 offset:32768
	ds_read_b128 v[186:189], v175 offset:33792
	ds_read_b128 v[190:193], v175 offset:34816
	ds_read_b128 v[194:197], v175 offset:35840
	ds_read_b128 v[198:201], v176 offset:32768
	ds_read_b128 v[202:205], v176 offset:33792
	ds_read_b128 v[206:209], v176 offset:34816
	ds_read_b128 v[210:213], v176 offset:35840
	ds_read_b128 v[214:217], v176 offset:36864
	ds_read_b128 v[218:221], v176 offset:37888
	ds_read_b128 v[222:225], v176 offset:38912
	ds_read_b128 v[226:229], v176 offset:39936
	s_add_i32 s64, 0, 0x18000
	s_add_i32 s65, 0, 0x1c000
	s_add_u32 s6, s6, 0x80000
	s_addc_u32 s7, s7, 0
	s_mov_b32 m0, s46
	s_nop 0
	global_load_lds_dwordx4 v144, s[6:7]
	s_mov_b32 m0, s47
	s_nop 0
	global_load_lds_dwordx4 v140, s[6:7]
	s_waitcnt vmcnt(8)
	s_waitcnt lgkmcnt(0)
	s_setprio 1
	s_barrier
	v_mfma_f32_16x16x32_bf16 v[128:131], v[132:135], v[198:201], v[128:131]
	v_mfma_f32_16x16x32_bf16 v[124:127], v[166:169], v[198:201], v[124:127]
	v_mfma_f32_16x16x32_bf16 v[112:115], v[132:135], v[206:209], v[112:115]
	v_mfma_f32_16x16x32_bf16 v[108:111], v[166:169], v[206:209], v[108:111]
	v_mfma_f32_16x16x32_bf16 v[96:99], v[132:135], v[214:217], v[96:99]
	v_mfma_f32_16x16x32_bf16 v[92:95], v[166:169], v[214:217], v[92:95]
	v_mfma_f32_16x16x32_bf16 v[80:83], v[132:135], v[222:225], v[80:83]
	v_mfma_f32_16x16x32_bf16 v[76:79], v[166:169], v[222:225], v[76:79]
	v_mfma_f32_16x16x32_bf16 v[128:131], v[158:161], v[202:205], v[128:131]
	v_mfma_f32_16x16x32_bf16 v[124:127], v[170:173], v[202:205], v[124:127]
	v_mfma_f32_16x16x32_bf16 v[112:115], v[158:161], v[210:213], v[112:115]
	v_mfma_f32_16x16x32_bf16 v[108:111], v[170:173], v[210:213], v[108:111]
	v_mfma_f32_16x16x32_bf16 v[96:99], v[158:161], v[218:221], v[96:99]
	v_mfma_f32_16x16x32_bf16 v[92:95], v[170:173], v[218:221], v[92:95]
	v_mfma_f32_16x16x32_bf16 v[80:83], v[158:161], v[226:229], v[80:83]
	v_mfma_f32_16x16x32_bf16 v[76:79], v[170:173], v[226:229], v[76:79]
	s_setprio 0
	s_setprio 1
	v_mfma_f32_16x16x32_bf16 v[120:123], v[182:185], v[198:201], v[120:123]
	v_mfma_f32_16x16x32_bf16 v[116:119], v[190:193], v[198:201], v[116:119]
	v_mfma_f32_16x16x32_bf16 v[104:107], v[182:185], v[206:209], v[104:107]
	v_mfma_f32_16x16x32_bf16 v[100:103], v[190:193], v[206:209], v[100:103]
	v_mfma_f32_16x16x32_bf16 v[88:91], v[182:185], v[214:217], v[88:91]
	v_mfma_f32_16x16x32_bf16 v[84:87], v[190:193], v[214:217], v[84:87]
	v_mfma_f32_16x16x32_bf16 v[72:75], v[182:185], v[222:225], v[72:75]
	v_mfma_f32_16x16x32_bf16 v[68:71], v[190:193], v[222:225], v[68:71]
	v_mfma_f32_16x16x32_bf16 v[120:123], v[186:189], v[202:205], v[120:123]
	v_mfma_f32_16x16x32_bf16 v[116:119], v[194:197], v[202:205], v[116:119]
	v_mfma_f32_16x16x32_bf16 v[104:107], v[186:189], v[210:213], v[104:107]
	v_mfma_f32_16x16x32_bf16 v[100:103], v[194:197], v[210:213], v[100:103]
	v_mfma_f32_16x16x32_bf16 v[88:91], v[186:189], v[218:221], v[88:91]
	v_mfma_f32_16x16x32_bf16 v[84:87], v[194:197], v[218:221], v[84:87]
	v_mfma_f32_16x16x32_bf16 v[72:75], v[186:189], v[226:229], v[72:75]
	v_mfma_f32_16x16x32_bf16 v[68:71], v[194:197], v[226:229], v[68:71]
	s_barrier
	s_setprio 0
	ds_read_b128 v[198:201], v176 offset:49152
	ds_read_b128 v[202:205], v176 offset:50176
	ds_read_b128 v[206:209], v176 offset:51200
	ds_read_b128 v[210:213], v176 offset:52224
	ds_read_b128 v[214:217], v176 offset:53248
	ds_read_b128 v[218:221], v176 offset:54272
	ds_read_b128 v[222:225], v176 offset:55296
	ds_read_b128 v[226:229], v176 offset:56320
	s_add_i32 s6, s64, s29
	s_mov_b32 m0, s6
	s_nop 0
	global_load_lds_dwordx4 v142, s[98:99]
	s_add_i32 m0, s6, 0x2000
	s_add_u32 s4, s4, 0x80080
	s_addc_u32 s5, s5, 0
	s_add_i32 s6, s65, s29
	global_load_lds_dwordx4 v138, s[98:99]
	s_mov_b32 m0, s6
	s_nop 0
	global_load_lds_dwordx4 v142, s[4:5]
	s_add_i32 m0, s6, 0x2000
	s_nop 0
	global_load_lds_dwordx4 v138, s[4:5]
	s_mov_b32 m0, s48
	s_nop 0
	global_load_lds_dwordx4 v144, s[100:101]
	s_mov_b32 m0, s49
	s_nop 0
	global_load_lds_dwordx4 v140, s[100:101]
	s_add_i32 s63, s63, 2
	s_add_u32 s0, s0, 0x100
	s_addc_u32 s1, s1, 0
	s_add_u32 s61, s61, 0x100
	s_addc_u32 s62, s62, 0
	s_cmp_gt_u32 s63, 29
	s_waitcnt vmcnt(8)
	s_waitcnt lgkmcnt(0)
	s_setprio 1
	s_barrier
	v_mfma_f32_16x16x32_bf16 v[62:65], v[132:135], v[198:201], v[62:65]
	v_mfma_f32_16x16x32_bf16 v[58:61], v[166:169], v[198:201], v[58:61]
	v_mfma_f32_16x16x32_bf16 v[46:49], v[132:135], v[206:209], v[46:49]
	v_mfma_f32_16x16x32_bf16 v[42:45], v[166:169], v[206:209], v[42:45]
	v_mfma_f32_16x16x32_bf16 v[30:33], v[132:135], v[214:217], v[30:33]
	v_mfma_f32_16x16x32_bf16 v[26:29], v[166:169], v[214:217], v[26:29]
	v_mfma_f32_16x16x32_bf16 v[14:17], v[132:135], v[222:225], v[14:17]
	v_mfma_f32_16x16x32_bf16 v[10:13], v[166:169], v[222:225], v[10:13]
	v_mfma_f32_16x16x32_bf16 v[62:65], v[158:161], v[202:205], v[62:65]
	v_mfma_f32_16x16x32_bf16 v[58:61], v[170:173], v[202:205], v[58:61]
	v_mfma_f32_16x16x32_bf16 v[46:49], v[158:161], v[210:213], v[46:49]
	v_mfma_f32_16x16x32_bf16 v[42:45], v[170:173], v[210:213], v[42:45]
	v_mfma_f32_16x16x32_bf16 v[30:33], v[158:161], v[218:221], v[30:33]
	v_mfma_f32_16x16x32_bf16 v[26:29], v[170:173], v[218:221], v[26:29]
	v_mfma_f32_16x16x32_bf16 v[14:17], v[158:161], v[226:229], v[14:17]
	v_mfma_f32_16x16x32_bf16 v[10:13], v[170:173], v[226:229], v[10:13]
	s_setprio 0
	s_setprio 1
	v_mfma_f32_16x16x32_bf16 v[54:57], v[182:185], v[198:201], v[54:57]
	v_mfma_f32_16x16x32_bf16 v[50:53], v[190:193], v[198:201], v[50:53]
	v_mfma_f32_16x16x32_bf16 v[38:41], v[182:185], v[206:209], v[38:41]
	v_mfma_f32_16x16x32_bf16 v[34:37], v[190:193], v[206:209], v[34:37]
	v_mfma_f32_16x16x32_bf16 v[22:25], v[182:185], v[214:217], v[22:25]
	v_mfma_f32_16x16x32_bf16 v[18:21], v[190:193], v[214:217], v[18:21]
	v_mfma_f32_16x16x32_bf16 v[6:9], v[182:185], v[222:225], v[6:9]
	v_mfma_f32_16x16x32_bf16 v[2:5], v[190:193], v[222:225], v[2:5]
	v_mfma_f32_16x16x32_bf16 v[54:57], v[186:189], v[202:205], v[54:57]
	v_mfma_f32_16x16x32_bf16 v[50:53], v[194:197], v[202:205], v[50:53]
	v_mfma_f32_16x16x32_bf16 v[38:41], v[186:189], v[210:213], v[38:41]
	v_mfma_f32_16x16x32_bf16 v[34:37], v[194:197], v[210:213], v[34:37]
	v_mfma_f32_16x16x32_bf16 v[22:25], v[186:189], v[218:221], v[22:25]
	v_mfma_f32_16x16x32_bf16 v[18:21], v[194:197], v[218:221], v[18:21]
	v_mfma_f32_16x16x32_bf16 v[6:9], v[186:189], v[226:229], v[6:9]
	v_mfma_f32_16x16x32_bf16 v[2:5], v[194:197], v[226:229], v[2:5]
	s_barrier
	s_setprio 0
	s_cbranch_scc0 .LBB0_1479
	s_and_b64 vcc, exec, s[34:35]
	s_cbranch_vccz .LBB0_1482
	s_barrier

.LBB0_1565:
	s_add_u32 s16, s16, 0x160080
	s_addc_u32 s17, s17, 0
	s_add_u32 s46, s20, 0x100
	s_addc_u32 s47, s21, 0
	s_mov_b32 s48, -2
	s_add_u32 s20, s16, 0xffea0080
	s_addc_u32 s21, s17, -1
	s_cmpk_eq_i32 s48, 0x54
	s_cselect_b32 s27, s5, s21
	s_cselect_b32 s26, s4, s20
	s_cselect_b32 s21, s15, s47
	s_cselect_b32 s20, s14, s46
	s_add_i32 m0, s30, 0xc000
	s_nop 0
	global_load_lds_dwordx4 v136, s[16:17]
	s_add_i32 m0, s30, 0xe000
	s_nop 0
	global_load_lds_dwordx4 v138, s[16:17]
	s_waitcnt vmcnt(8)
	s_waitcnt lgkmcnt(0)
	s_setprio 1
	s_barrier
	v_mfma_f32_16x16x32_bf16 v[124:127], v[144:147], v[182:185], 0
	v_mfma_f32_16x16x32_bf16 v[120:123], v[158:161], v[182:185], 0
	v_mfma_f32_16x16x32_bf16 v[108:111], v[144:147], v[190:193], 0
	v_mfma_f32_16x16x32_bf16 v[104:107], v[158:161], v[190:193], 0
	v_mfma_f32_16x16x32_bf16 v[88:91], v[144:147], v[198:201], 0
	v_mfma_f32_16x16x32_bf16 v[92:95], v[158:161], v[198:201], 0
	v_mfma_f32_16x16x32_bf16 v[72:75], v[144:147], v[206:209], 0
	v_mfma_f32_16x16x32_bf16 v[76:79], v[158:161], v[206:209], 0
	v_mfma_f32_16x16x32_bf16 v[124:127], v[154:157], v[186:189], v[124:127]
	v_mfma_f32_16x16x32_bf16 v[120:123], v[162:165], v[186:189], v[120:123]
	v_mfma_f32_16x16x32_bf16 v[108:111], v[154:157], v[194:197], v[108:111]
	v_mfma_f32_16x16x32_bf16 v[104:107], v[162:165], v[194:197], v[104:107]
	v_mfma_f32_16x16x32_bf16 v[88:91], v[154:157], v[202:205], v[88:91]
	v_mfma_f32_16x16x32_bf16 v[92:95], v[162:165], v[202:205], v[92:95]
	v_mfma_f32_16x16x32_bf16 v[72:75], v[154:157], v[210:213], v[72:75]
	v_mfma_f32_16x16x32_bf16 v[76:79], v[162:165], v[210:213], v[76:79]
	s_setprio 0
	s_setprio 1
	v_mfma_f32_16x16x32_bf16 v[116:119], v[166:169], v[182:185], 0
	v_mfma_f32_16x16x32_bf16 v[112:115], v[174:177], v[182:185], 0
	v_mfma_f32_16x16x32_bf16 v[96:99], v[166:169], v[190:193], 0
	v_mfma_f32_16x16x32_bf16 v[100:103], v[174:177], v[190:193], 0
	v_mfma_f32_16x16x32_bf16 v[80:83], v[166:169], v[198:201], 0
	v_mfma_f32_16x16x32_bf16 v[84:87], v[174:177], v[198:201], 0
	v_mfma_f32_16x16x32_bf16 v[64:67], v[166:169], v[206:209], 0
	v_mfma_f32_16x16x32_bf16 v[68:71], v[174:177], v[206:209], 0
	v_mfma_f32_16x16x32_bf16 v[116:119], v[170:173], v[186:189], v[116:119]
	v_mfma_f32_16x16x32_bf16 v[112:115], v[178:181], v[186:189], v[112:115]
	v_mfma_f32_16x16x32_bf16 v[96:99], v[170:173], v[194:197], v[96:99]
	v_mfma_f32_16x16x32_bf16 v[100:103], v[178:181], v[194:197], v[100:103]
	v_mfma_f32_16x16x32_bf16 v[80:83], v[170:173], v[202:205], v[80:83]
	v_mfma_f32_16x16x32_bf16 v[84:87], v[178:181], v[202:205], v[84:87]
	v_mfma_f32_16x16x32_bf16 v[64:67], v[170:173], v[210:213], v[64:67]
	v_mfma_f32_16x16x32_bf16 v[68:71], v[178:181], v[210:213], v[68:71]
	s_barrier
	s_setprio 0
	ds_read_b128 v[182:185], v153 offset:16384
	ds_read_b128 v[186:189], v153 offset:17408
	ds_read_b128 v[190:193], v153 offset:18432
	ds_read_b128 v[194:197], v153 offset:19456
	ds_read_b128 v[198:201], v153 offset:20480
	ds_read_b128 v[202:205], v153 offset:21504
	ds_read_b128 v[206:209], v153 offset:22528
	ds_read_b128 v[210:213], v153 offset:23552
	s_add_i32 s49, s40, s29
	s_add_u32 s98, s20, 0x80
	s_addc_u32 s99, s21, 0
	s_mov_b32 m0, s49
	s_nop 0
	global_load_lds_dwordx4 v130, s[20:21]
	s_add_i32 m0, s49, 0x2000
	s_add_u32 s52, s20, 0x160000
	s_addc_u32 s53, s21, 0
	s_add_i32 s49, s41, s29
	global_load_lds_dwordx4 v134, s[20:21]
	s_mov_b32 m0, s49
	s_nop 0
	global_load_lds_dwordx4 v130, s[52:53]
	s_add_i32 m0, s49, 0x2000
	s_nop 0
	global_load_lds_dwordx4 v134, s[52:53]
	s_add_u32 s100, s26, 0x80
	s_addc_u32 s101, s27, 0
	s_mov_b32 m0, s30
	s_nop 0
	global_load_lds_dwordx4 v128, s[26:27]
	s_mov_b32 m0, s31
	s_nop 0
	global_load_lds_dwordx4 v132, s[26:27]
	s_waitcnt vmcnt(8)
	s_waitcnt lgkmcnt(0)
	s_setprio 1
	s_barrier
	v_mfma_f32_16x16x32_bf16 v[56:59], v[144:147], v[182:185], 0
	v_mfma_f32_16x16x32_bf16 v[60:63], v[158:161], v[182:185], 0
	v_mfma_f32_16x16x32_bf16 v[40:43], v[144:147], v[190:193], 0
	v_mfma_f32_16x16x32_bf16 v[44:47], v[158:161], v[190:193], 0
	v_mfma_f32_16x16x32_bf16 v[24:27], v[144:147], v[198:201], 0
	v_mfma_f32_16x16x32_bf16 v[28:31], v[158:161], v[198:201], 0
	v_mfma_f32_16x16x32_bf16 v[8:11], v[144:147], v[206:209], 0
	v_mfma_f32_16x16x32_bf16 v[12:15], v[158:161], v[206:209], 0
	v_mfma_f32_16x16x32_bf16 v[56:59], v[154:157], v[186:189], v[56:59]
	v_mfma_f32_16x16x32_bf16 v[60:63], v[162:165], v[186:189], v[60:63]
	v_mfma_f32_16x16x32_bf16 v[40:43], v[154:157], v[194:197], v[40:43]
	v_mfma_f32_16x16x32_bf16 v[44:47], v[162:165], v[194:197], v[44:47]
	v_mfma_f32_16x16x32_bf16 v[24:27], v[154:157], v[202:205], v[24:27]
	v_mfma_f32_16x16x32_bf16 v[28:31], v[162:165], v[202:205], v[28:31]
	v_mfma_f32_16x16x32_bf16 v[8:11], v[154:157], v[210:213], v[8:11]
	v_mfma_f32_16x16x32_bf16 v[12:15], v[162:165], v[210:213], v[12:15]
	s_setprio 0
	s_setprio 1
	v_mfma_f32_16x16x32_bf16 v[48:51], v[166:169], v[182:185], 0
	v_mfma_f32_16x16x32_bf16 v[52:55], v[174:177], v[182:185], 0
	v_mfma_f32_16x16x32_bf16 v[32:35], v[166:169], v[190:193], 0
	v_mfma_f32_16x16x32_bf16 v[36:39], v[174:177], v[190:193], 0
	v_mfma_f32_16x16x32_bf16 v[16:19], v[166:169], v[198:201], 0
	v_mfma_f32_16x16x32_bf16 v[20:23], v[174:177], v[198:201], 0
	v_mfma_f32_16x16x32_bf16 v[0:3], v[166:169], v[206:209], 0
	v_mfma_f32_16x16x32_bf16 v[4:7], v[174:177], v[206:209], 0
	v_mfma_f32_16x16x32_bf16 v[48:51], v[170:173], v[186:189], v[48:51]
	v_mfma_f32_16x16x32_bf16 v[52:55], v[178:181], v[186:189], v[52:55]
	v_mfma_f32_16x16x32_bf16 v[32:35], v[170:173], v[194:197], v[32:35]
	v_mfma_f32_16x16x32_bf16 v[36:39], v[178:181], v[194:197], v[36:39]
	v_mfma_f32_16x16x32_bf16 v[16:19], v[170:173], v[202:205], v[16:19]
	v_mfma_f32_16x16x32_bf16 v[20:23], v[178:181], v[202:205], v[20:23]
	v_mfma_f32_16x16x32_bf16 v[0:3], v[170:173], v[210:213], v[0:3]
	v_mfma_f32_16x16x32_bf16 v[4:7], v[178:181], v[210:213], v[4:7]
	s_barrier
	s_setprio 0
	ds_read_b128 v[144:147], v151 offset:32768
	ds_read_b128 v[154:157], v151 offset:33792
	ds_read_b128 v[158:161], v151 offset:34816
	ds_read_b128 v[162:165], v151 offset:35840
	ds_read_b128 v[166:169], v152 offset:32768
	ds_read_b128 v[170:173], v152 offset:33792
	ds_read_b128 v[174:177], v152 offset:34816
	ds_read_b128 v[178:181], v152 offset:35840
	ds_read_b128 v[182:185], v153 offset:32768
	ds_read_b128 v[186:189], v153 offset:33792
	ds_read_b128 v[190:193], v153 offset:34816
	ds_read_b128 v[194:197], v153 offset:35840
	ds_read_b128 v[198:201], v153 offset:36864
	ds_read_b128 v[202:205], v153 offset:37888
	ds_read_b128 v[206:209], v153 offset:38912
	ds_read_b128 v[210:213], v153 offset:39936
	s_add_i32 s49, 0, 0x18000
	s_add_i32 s52, 0, 0x1c000
	s_add_u32 s26, s26, 0x160000
	s_addc_u32 s27, s27, 0
	s_mov_b32 m0, s34
	s_nop 0
	global_load_lds_dwordx4 v128, s[26:27]
	s_mov_b32 m0, s35
	s_nop 0
	global_load_lds_dwordx4 v132, s[26:27]
	s_waitcnt vmcnt(8)
	s_waitcnt lgkmcnt(0)
	s_setprio 1
	s_barrier
	v_mfma_f32_16x16x32_bf16 v[124:127], v[144:147], v[182:185], v[124:127]
	v_mfma_f32_16x16x32_bf16 v[120:123], v[158:161], v[182:185], v[120:123]
	v_mfma_f32_16x16x32_bf16 v[108:111], v[144:147], v[190:193], v[108:111]
	v_mfma_f32_16x16x32_bf16 v[104:107], v[158:161], v[190:193], v[104:107]
	v_mfma_f32_16x16x32_bf16 v[88:91], v[144:147], v[198:201], v[88:91]
	v_mfma_f32_16x16x32_bf16 v[92:95], v[158:161], v[198:201], v[92:95]
	v_mfma_f32_16x16x32_bf16 v[72:75], v[144:147], v[206:209], v[72:75]
	v_mfma_f32_16x16x32_bf16 v[76:79], v[158:161], v[206:209], v[76:79]
	v_mfma_f32_16x16x32_bf16 v[124:127], v[154:157], v[186:189], v[124:127]
	v_mfma_f32_16x16x32_bf16 v[120:123], v[162:165], v[186:189], v[120:123]
	v_mfma_f32_16x16x32_bf16 v[108:111], v[154:157], v[194:197], v[108:111]
	v_mfma_f32_16x16x32_bf16 v[104:107], v[162:165], v[194:197], v[104:107]
	v_mfma_f32_16x16x32_bf16 v[88:91], v[154:157], v[202:205], v[88:91]
	v_mfma_f32_16x16x32_bf16 v[92:95], v[162:165], v[202:205], v[92:95]
	v_mfma_f32_16x16x32_bf16 v[72:75], v[154:157], v[210:213], v[72:75]
	v_mfma_f32_16x16x32_bf16 v[76:79], v[162:165], v[210:213], v[76:79]
	s_setprio 0
	s_setprio 1
	v_mfma_f32_16x16x32_bf16 v[116:119], v[166:169], v[182:185], v[116:119]
	v_mfma_f32_16x16x32_bf16 v[112:115], v[174:177], v[182:185], v[112:115]
	v_mfma_f32_16x16x32_bf16 v[96:99], v[166:169], v[190:193], v[96:99]
	v_mfma_f32_16x16x32_bf16 v[100:103], v[174:177], v[190:193], v[100:103]
	v_mfma_f32_16x16x32_bf16 v[80:83], v[166:169], v[198:201], v[80:83]
	v_mfma_f32_16x16x32_bf16 v[84:87], v[174:177], v[198:201], v[84:87]
	v_mfma_f32_16x16x32_bf16 v[64:67], v[166:169], v[206:209], v[64:67]
	v_mfma_f32_16x16x32_bf16 v[68:71], v[174:177], v[206:209], v[68:71]
	v_mfma_f32_16x16x32_bf16 v[116:119], v[170:173], v[186:189], v[116:119]
	v_mfma_f32_16x16x32_bf16 v[112:115], v[178:181], v[186:189], v[112:115]
	v_mfma_f32_16x16x32_bf16 v[96:99], v[170:173], v[194:197], v[96:99]
	v_mfma_f32_16x16x32_bf16 v[100:103], v[178:181], v[194:197], v[100:103]
	v_mfma_f32_16x16x32_bf16 v[80:83], v[170:173], v[202:205], v[80:83]
	v_mfma_f32_16x16x32_bf16 v[84:87], v[178:181], v[202:205], v[84:87]
	v_mfma_f32_16x16x32_bf16 v[64:67], v[170:173], v[210:213], v[64:67]
	v_mfma_f32_16x16x32_bf16 v[68:71], v[178:181], v[210:213], v[68:71]
	s_barrier
	s_setprio 0
	ds_read_b128 v[182:185], v153 offset:49152
	ds_read_b128 v[186:189], v153 offset:50176
	ds_read_b128 v[190:193], v153 offset:51200
	ds_read_b128 v[194:197], v153 offset:52224
	ds_read_b128 v[198:201], v153 offset:53248
	ds_read_b128 v[202:205], v153 offset:54272
	ds_read_b128 v[206:209], v153 offset:55296
	ds_read_b128 v[210:213], v153 offset:56320
	s_add_i32 s26, s49, s29
	s_mov_b32 m0, s26
	s_nop 0
	global_load_lds_dwordx4 v130, s[98:99]
	s_add_i32 m0, s26, 0x2000
	s_add_u32 s20, s20, 0x160080
	s_addc_u32 s21, s21, 0
	s_add_i32 s26, s52, s29
	global_load_lds_dwordx4 v134, s[98:99]
	s_mov_b32 m0, s26
	s_nop 0
	global_load_lds_dwordx4 v130, s[20:21]
	s_add_i32 m0, s26, 0x2000
	s_nop 0
	global_load_lds_dwordx4 v134, s[20:21]
	s_mov_b32 m0, s37
	s_nop 0
	global_load_lds_dwordx4 v128, s[100:101]
	s_mov_b32 m0, s38
	s_nop 0
	global_load_lds_dwordx4 v132, s[100:101]
	s_waitcnt vmcnt(8)
	s_waitcnt lgkmcnt(0)
	s_setprio 1
	s_barrier
	v_mfma_f32_16x16x32_bf16 v[56:59], v[144:147], v[182:185], v[56:59]
	v_mfma_f32_16x16x32_bf16 v[60:63], v[158:161], v[182:185], v[60:63]
	v_mfma_f32_16x16x32_bf16 v[40:43], v[144:147], v[190:193], v[40:43]
	v_mfma_f32_16x16x32_bf16 v[44:47], v[158:161], v[190:193], v[44:47]
	v_mfma_f32_16x16x32_bf16 v[24:27], v[144:147], v[198:201], v[24:27]
	v_mfma_f32_16x16x32_bf16 v[28:31], v[158:161], v[198:201], v[28:31]
	v_mfma_f32_16x16x32_bf16 v[8:11], v[144:147], v[206:209], v[8:11]
	v_mfma_f32_16x16x32_bf16 v[12:15], v[158:161], v[206:209], v[12:15]
	v_mfma_f32_16x16x32_bf16 v[56:59], v[154:157], v[186:189], v[56:59]
	v_mfma_f32_16x16x32_bf16 v[60:63], v[162:165], v[186:189], v[60:63]
	v_mfma_f32_16x16x32_bf16 v[40:43], v[154:157], v[194:197], v[40:43]
	v_mfma_f32_16x16x32_bf16 v[44:47], v[162:165], v[194:197], v[44:47]
	v_mfma_f32_16x16x32_bf16 v[24:27], v[154:157], v[202:205], v[24:27]
	v_mfma_f32_16x16x32_bf16 v[28:31], v[162:165], v[202:205], v[28:31]
	v_mfma_f32_16x16x32_bf16 v[8:11], v[154:157], v[210:213], v[8:11]
	v_mfma_f32_16x16x32_bf16 v[12:15], v[162:165], v[210:213], v[12:15]
	s_setprio 0
	s_setprio 1
	v_mfma_f32_16x16x32_bf16 v[48:51], v[166:169], v[182:185], v[48:51]
	v_mfma_f32_16x16x32_bf16 v[52:55], v[174:177], v[182:185], v[52:55]
	v_mfma_f32_16x16x32_bf16 v[32:35], v[166:169], v[190:193], v[32:35]
	v_mfma_f32_16x16x32_bf16 v[36:39], v[174:177], v[190:193], v[36:39]
	v_mfma_f32_16x16x32_bf16 v[16:19], v[166:169], v[198:201], v[16:19]
	v_mfma_f32_16x16x32_bf16 v[20:23], v[174:177], v[198:201], v[20:23]
	v_mfma_f32_16x16x32_bf16 v[0:3], v[166:169], v[206:209], v[0:3]
	v_mfma_f32_16x16x32_bf16 v[4:7], v[174:177], v[206:209], v[4:7]
	v_mfma_f32_16x16x32_bf16 v[48:51], v[170:173], v[186:189], v[48:51]
	v_mfma_f32_16x16x32_bf16 v[52:55], v[178:181], v[186:189], v[52:55]
	v_mfma_f32_16x16x32_bf16 v[32:35], v[170:173], v[194:197], v[32:35]
	v_mfma_f32_16x16x32_bf16 v[36:39], v[178:181], v[194:197], v[36:39]
	v_mfma_f32_16x16x32_bf16 v[16:19], v[170:173], v[202:205], v[16:19]
	v_mfma_f32_16x16x32_bf16 v[20:23], v[178:181], v[202:205], v[20:23]
	v_mfma_f32_16x16x32_bf16 v[0:3], v[170:173], v[210:213], v[0:3]
	v_mfma_f32_16x16x32_bf16 v[4:7], v[178:181], v[210:213], v[4:7]
	s_barrier
	s_setprio 0
	s_add_i32 s48, s48, 2
	s_add_u32 s16, s16, 0x100
	s_addc_u32 s17, s17, 0
	s_add_u32 s46, s46, 0x100
	s_addc_u32 s47, s47, 0
	s_cmpk_gt_u32 s48, 0x55
.LBB0_1566:
	ds_read_b128 v[144:147], v151
	ds_read_b128 v[154:157], v151 offset:1024
	ds_read_b128 v[158:161], v151 offset:2048
	ds_read_b128 v[162:165], v151 offset:3072
	ds_read_b128 v[166:169], v152
	ds_read_b128 v[170:173], v152 offset:1024
	ds_read_b128 v[174:177], v152 offset:2048
	ds_read_b128 v[178:181], v152 offset:3072
	ds_read_b128 v[182:185], v153
	ds_read_b128 v[186:189], v153 offset:1024
	ds_read_b128 v[190:193], v153 offset:2048
	ds_read_b128 v[194:197], v153 offset:3072
	ds_read_b128 v[198:201], v153 offset:4096
	ds_read_b128 v[202:205], v153 offset:5120
	ds_read_b128 v[206:209], v153 offset:6144
	ds_read_b128 v[210:213], v153 offset:7168
	s_add_u32 s20, s16, 0xffea0080
	s_addc_u32 s21, s17, -1
	s_cmpk_eq_i32 s48, 0x54
	s_cselect_b32 s27, s5, s21
	s_cselect_b32 s26, s4, s20
	s_cselect_b32 s21, s15, s47
	s_cselect_b32 s20, s14, s46
	s_add_i32 m0, s30, 0xc000
	s_nop 0
	global_load_lds_dwordx4 v136, s[16:17]
	s_add_i32 m0, s30, 0xe000
	s_nop 0
	global_load_lds_dwordx4 v138, s[16:17]
	s_waitcnt vmcnt(8)
	s_waitcnt lgkmcnt(0)
	s_setprio 1
	s_barrier
	v_mfma_f32_16x16x32_bf16 v[124:127], v[144:147], v[182:185], v[124:127]
	v_mfma_f32_16x16x32_bf16 v[120:123], v[158:161], v[182:185], v[120:123]
	v_mfma_f32_16x16x32_bf16 v[108:111], v[144:147], v[190:193], v[108:111]
	v_mfma_f32_16x16x32_bf16 v[104:107], v[158:161], v[190:193], v[104:107]
	v_mfma_f32_16x16x32_bf16 v[88:91], v[144:147], v[198:201], v[88:91]
	v_mfma_f32_16x16x32_bf16 v[92:95], v[158:161], v[198:201], v[92:95]
	v_mfma_f32_16x16x32_bf16 v[72:75], v[144:147], v[206:209], v[72:75]
	v_mfma_f32_16x16x32_bf16 v[76:79], v[158:161], v[206:209], v[76:79]
	v_mfma_f32_16x16x32_bf16 v[124:127], v[154:157], v[186:189], v[124:127]
	v_mfma_f32_16x16x32_bf16 v[120:123], v[162:165], v[186:189], v[120:123]
	v_mfma_f32_16x16x32_bf16 v[108:111], v[154:157], v[194:197], v[108:111]
	v_mfma_f32_16x16x32_bf16 v[104:107], v[162:165], v[194:197], v[104:107]
	v_mfma_f32_16x16x32_bf16 v[88:91], v[154:157], v[202:205], v[88:91]
	v_mfma_f32_16x16x32_bf16 v[92:95], v[162:165], v[202:205], v[92:95]
	v_mfma_f32_16x16x32_bf16 v[72:75], v[154:157], v[210:213], v[72:75]
	v_mfma_f32_16x16x32_bf16 v[76:79], v[162:165], v[210:213], v[76:79]
	s_setprio 0
	s_setprio 1
	v_mfma_f32_16x16x32_bf16 v[116:119], v[166:169], v[182:185], v[116:119]
	v_mfma_f32_16x16x32_bf16 v[112:115], v[174:177], v[182:185], v[112:115]
	v_mfma_f32_16x16x32_bf16 v[96:99], v[166:169], v[190:193], v[96:99]
	v_mfma_f32_16x16x32_bf16 v[100:103], v[174:177], v[190:193], v[100:103]
	v_mfma_f32_16x16x32_bf16 v[80:83], v[166:169], v[198:201], v[80:83]
	v_mfma_f32_16x16x32_bf16 v[84:87], v[174:177], v[198:201], v[84:87]
	v_mfma_f32_16x16x32_bf16 v[64:67], v[166:169], v[206:209], v[64:67]
	v_mfma_f32_16x16x32_bf16 v[68:71], v[174:177], v[206:209], v[68:71]
	v_mfma_f32_16x16x32_bf16 v[116:119], v[170:173], v[186:189], v[116:119]
	v_mfma_f32_16x16x32_bf16 v[112:115], v[178:181], v[186:189], v[112:115]
	v_mfma_f32_16x16x32_bf16 v[96:99], v[170:173], v[194:197], v[96:99]
	v_mfma_f32_16x16x32_bf16 v[100:103], v[178:181], v[194:197], v[100:103]
	v_mfma_f32_16x16x32_bf16 v[80:83], v[170:173], v[202:205], v[80:83]
	v_mfma_f32_16x16x32_bf16 v[84:87], v[178:181], v[202:205], v[84:87]
	v_mfma_f32_16x16x32_bf16 v[64:67], v[170:173], v[210:213], v[64:67]
	v_mfma_f32_16x16x32_bf16 v[68:71], v[178:181], v[210:213], v[68:71]
	s_barrier
	s_setprio 0
	ds_read_b128 v[182:185], v153 offset:16384
	ds_read_b128 v[186:189], v153 offset:17408
	ds_read_b128 v[190:193], v153 offset:18432
	ds_read_b128 v[194:197], v153 offset:19456
	ds_read_b128 v[198:201], v153 offset:20480
	ds_read_b128 v[202:205], v153 offset:21504
	ds_read_b128 v[206:209], v153 offset:22528
	ds_read_b128 v[210:213], v153 offset:23552
	s_add_i32 s49, s40, s29
	s_add_u32 s98, s20, 0x80
	s_addc_u32 s99, s21, 0
	s_mov_b32 m0, s49
	s_nop 0
	global_load_lds_dwordx4 v130, s[20:21]
	s_add_i32 m0, s49, 0x2000
	s_add_u32 s52, s20, 0x160000
	s_addc_u32 s53, s21, 0
	s_add_i32 s49, s41, s29
	global_load_lds_dwordx4 v134, s[20:21]
	s_mov_b32 m0, s49
	s_nop 0
	global_load_lds_dwordx4 v130, s[52:53]
	s_add_i32 m0, s49, 0x2000
	s_nop 0
	global_load_lds_dwordx4 v134, s[52:53]
	s_add_u32 s100, s26, 0x80
	s_addc_u32 s101, s27, 0
	s_mov_b32 m0, s30
	s_nop 0
	global_load_lds_dwordx4 v128, s[26:27]
	s_mov_b32 m0, s31
	s_nop 0
	global_load_lds_dwordx4 v132, s[26:27]
	s_waitcnt vmcnt(8)
	s_waitcnt lgkmcnt(0)
	s_setprio 1
	s_barrier
	v_mfma_f32_16x16x32_bf16 v[56:59], v[144:147], v[182:185], v[56:59]
	v_mfma_f32_16x16x32_bf16 v[60:63], v[158:161], v[182:185], v[60:63]
	v_mfma_f32_16x16x32_bf16 v[40:43], v[144:147], v[190:193], v[40:43]
	v_mfma_f32_16x16x32_bf16 v[44:47], v[158:161], v[190:193], v[44:47]
	v_mfma_f32_16x16x32_bf16 v[24:27], v[144:147], v[198:201], v[24:27]
	v_mfma_f32_16x16x32_bf16 v[28:31], v[158:161], v[198:201], v[28:31]
	v_mfma_f32_16x16x32_bf16 v[8:11], v[144:147], v[206:209], v[8:11]
	v_mfma_f32_16x16x32_bf16 v[12:15], v[158:161], v[206:209], v[12:15]
	v_mfma_f32_16x16x32_bf16 v[56:59], v[154:157], v[186:189], v[56:59]
	v_mfma_f32_16x16x32_bf16 v[60:63], v[162:165], v[186:189], v[60:63]
	v_mfma_f32_16x16x32_bf16 v[40:43], v[154:157], v[194:197], v[40:43]
	v_mfma_f32_16x16x32_bf16 v[44:47], v[162:165], v[194:197], v[44:47]
	v_mfma_f32_16x16x32_bf16 v[24:27], v[154:157], v[202:205], v[24:27]
	v_mfma_f32_16x16x32_bf16 v[28:31], v[162:165], v[202:205], v[28:31]
	v_mfma_f32_16x16x32_bf16 v[8:11], v[154:157], v[210:213], v[8:11]
	v_mfma_f32_16x16x32_bf16 v[12:15], v[162:165], v[210:213], v[12:15]
	s_setprio 0
	s_setprio 1
	v_mfma_f32_16x16x32_bf16 v[48:51], v[166:169], v[182:185], v[48:51]
	v_mfma_f32_16x16x32_bf16 v[52:55], v[174:177], v[182:185], v[52:55]
	v_mfma_f32_16x16x32_bf16 v[32:35], v[166:169], v[190:193], v[32:35]
	v_mfma_f32_16x16x32_bf16 v[36:39], v[174:177], v[190:193], v[36:39]
	v_mfma_f32_16x16x32_bf16 v[16:19], v[166:169], v[198:201], v[16:19]
	v_mfma_f32_16x16x32_bf16 v[20:23], v[174:177], v[198:201], v[20:23]
	v_mfma_f32_16x16x32_bf16 v[0:3], v[166:169], v[206:209], v[0:3]
	v_mfma_f32_16x16x32_bf16 v[4:7], v[174:177], v[206:209], v[4:7]
	v_mfma_f32_16x16x32_bf16 v[48:51], v[170:173], v[186:189], v[48:51]
	v_mfma_f32_16x16x32_bf16 v[52:55], v[178:181], v[186:189], v[52:55]
	v_mfma_f32_16x16x32_bf16 v[32:35], v[170:173], v[194:197], v[32:35]
	v_mfma_f32_16x16x32_bf16 v[36:39], v[178:181], v[194:197], v[36:39]
	v_mfma_f32_16x16x32_bf16 v[16:19], v[170:173], v[202:205], v[16:19]
	v_mfma_f32_16x16x32_bf16 v[20:23], v[178:181], v[202:205], v[20:23]
	v_mfma_f32_16x16x32_bf16 v[0:3], v[170:173], v[210:213], v[0:3]
	v_mfma_f32_16x16x32_bf16 v[4:7], v[178:181], v[210:213], v[4:7]
	s_barrier
	s_setprio 0
	ds_read_b128 v[144:147], v151 offset:32768
	ds_read_b128 v[154:157], v151 offset:33792
	ds_read_b128 v[158:161], v151 offset:34816
	ds_read_b128 v[162:165], v151 offset:35840
	ds_read_b128 v[166:169], v152 offset:32768
	ds_read_b128 v[170:173], v152 offset:33792
	ds_read_b128 v[174:177], v152 offset:34816
	ds_read_b128 v[178:181], v152 offset:35840
	ds_read_b128 v[182:185], v153 offset:32768
	ds_read_b128 v[186:189], v153 offset:33792
	ds_read_b128 v[190:193], v153 offset:34816
	ds_read_b128 v[194:197], v153 offset:35840
	ds_read_b128 v[198:201], v153 offset:36864
	ds_read_b128 v[202:205], v153 offset:37888
	ds_read_b128 v[206:209], v153 offset:38912
	ds_read_b128 v[210:213], v153 offset:39936
	s_add_i32 s49, 0, 0x18000
	s_add_i32 s52, 0, 0x1c000
	s_add_u32 s26, s26, 0x160000
	s_addc_u32 s27, s27, 0
	s_mov_b32 m0, s34
	s_nop 0
	global_load_lds_dwordx4 v128, s[26:27]
	s_mov_b32 m0, s35
	s_nop 0
	global_load_lds_dwordx4 v132, s[26:27]
	s_waitcnt vmcnt(8)
	s_waitcnt lgkmcnt(0)
	s_setprio 1
	s_barrier
	v_mfma_f32_16x16x32_bf16 v[124:127], v[144:147], v[182:185], v[124:127]
	v_mfma_f32_16x16x32_bf16 v[120:123], v[158:161], v[182:185], v[120:123]
	v_mfma_f32_16x16x32_bf16 v[108:111], v[144:147], v[190:193], v[108:111]
	v_mfma_f32_16x16x32_bf16 v[104:107], v[158:161], v[190:193], v[104:107]
	v_mfma_f32_16x16x32_bf16 v[88:91], v[144:147], v[198:201], v[88:91]
	v_mfma_f32_16x16x32_bf16 v[92:95], v[158:161], v[198:201], v[92:95]
	v_mfma_f32_16x16x32_bf16 v[72:75], v[144:147], v[206:209], v[72:75]
	v_mfma_f32_16x16x32_bf16 v[76:79], v[158:161], v[206:209], v[76:79]
	v_mfma_f32_16x16x32_bf16 v[124:127], v[154:157], v[186:189], v[124:127]
	v_mfma_f32_16x16x32_bf16 v[120:123], v[162:165], v[186:189], v[120:123]
	v_mfma_f32_16x16x32_bf16 v[108:111], v[154:157], v[194:197], v[108:111]
	v_mfma_f32_16x16x32_bf16 v[104:107], v[162:165], v[194:197], v[104:107]
	v_mfma_f32_16x16x32_bf16 v[88:91], v[154:157], v[202:205], v[88:91]
	v_mfma_f32_16x16x32_bf16 v[92:95], v[162:165], v[202:205], v[92:95]
	v_mfma_f32_16x16x32_bf16 v[72:75], v[154:157], v[210:213], v[72:75]
	v_mfma_f32_16x16x32_bf16 v[76:79], v[162:165], v[210:213], v[76:79]
	s_setprio 0
	s_setprio 1
	v_mfma_f32_16x16x32_bf16 v[116:119], v[166:169], v[182:185], v[116:119]
	v_mfma_f32_16x16x32_bf16 v[112:115], v[174:177], v[182:185], v[112:115]
	v_mfma_f32_16x16x32_bf16 v[96:99], v[166:169], v[190:193], v[96:99]
	v_mfma_f32_16x16x32_bf16 v[100:103], v[174:177], v[190:193], v[100:103]
	v_mfma_f32_16x16x32_bf16 v[80:83], v[166:169], v[198:201], v[80:83]
	v_mfma_f32_16x16x32_bf16 v[84:87], v[174:177], v[198:201], v[84:87]
	v_mfma_f32_16x16x32_bf16 v[64:67], v[166:169], v[206:209], v[64:67]
	v_mfma_f32_16x16x32_bf16 v[68:71], v[174:177], v[206:209], v[68:71]
	v_mfma_f32_16x16x32_bf16 v[116:119], v[170:173], v[186:189], v[116:119]
	v_mfma_f32_16x16x32_bf16 v[112:115], v[178:181], v[186:189], v[112:115]
	v_mfma_f32_16x16x32_bf16 v[96:99], v[170:173], v[194:197], v[96:99]
	v_mfma_f32_16x16x32_bf16 v[100:103], v[178:181], v[194:197], v[100:103]
	v_mfma_f32_16x16x32_bf16 v[80:83], v[170:173], v[202:205], v[80:83]
	v_mfma_f32_16x16x32_bf16 v[84:87], v[178:181], v[202:205], v[84:87]
	v_mfma_f32_16x16x32_bf16 v[64:67], v[170:173], v[210:213], v[64:67]
	v_mfma_f32_16x16x32_bf16 v[68:71], v[178:181], v[210:213], v[68:71]
	s_barrier
	s_setprio 0
	ds_read_b128 v[182:185], v153 offset:49152
	ds_read_b128 v[186:189], v153 offset:50176
	ds_read_b128 v[190:193], v153 offset:51200
	ds_read_b128 v[194:197], v153 offset:52224
	ds_read_b128 v[198:201], v153 offset:53248
	ds_read_b128 v[202:205], v153 offset:54272
	ds_read_b128 v[206:209], v153 offset:55296
	ds_read_b128 v[210:213], v153 offset:56320
	s_add_i32 s26, s49, s29
	s_mov_b32 m0, s26
	s_nop 0
	global_load_lds_dwordx4 v130, s[98:99]
	s_add_i32 m0, s26, 0x2000
	s_add_u32 s20, s20, 0x160080
	s_addc_u32 s21, s21, 0
	s_add_i32 s26, s52, s29
	global_load_lds_dwordx4 v134, s[98:99]
	s_mov_b32 m0, s26
	s_nop 0
	global_load_lds_dwordx4 v130, s[20:21]
	s_add_i32 m0, s26, 0x2000
	s_nop 0
	global_load_lds_dwordx4 v134, s[20:21]
	s_mov_b32 m0, s37
	s_nop 0
	global_load_lds_dwordx4 v128, s[100:101]
	s_mov_b32 m0, s38
	s_nop 0
	global_load_lds_dwordx4 v132, s[100:101]
	s_add_i32 s48, s48, 2
	s_add_u32 s16, s16, 0x100
	s_addc_u32 s17, s17, 0
	s_add_u32 s46, s46, 0x100
	s_addc_u32 s47, s47, 0
	s_cmpk_gt_u32 s48, 0x55
	s_waitcnt vmcnt(8)
	s_waitcnt lgkmcnt(0)
	s_setprio 1
	s_barrier
	v_mfma_f32_16x16x32_bf16 v[56:59], v[144:147], v[182:185], v[56:59]
	v_mfma_f32_16x16x32_bf16 v[60:63], v[158:161], v[182:185], v[60:63]
	v_mfma_f32_16x16x32_bf16 v[40:43], v[144:147], v[190:193], v[40:43]
	v_mfma_f32_16x16x32_bf16 v[44:47], v[158:161], v[190:193], v[44:47]
	v_mfma_f32_16x16x32_bf16 v[24:27], v[144:147], v[198:201], v[24:27]
	v_mfma_f32_16x16x32_bf16 v[28:31], v[158:161], v[198:201], v[28:31]
	v_mfma_f32_16x16x32_bf16 v[8:11], v[144:147], v[206:209], v[8:11]
	v_mfma_f32_16x16x32_bf16 v[12:15], v[158:161], v[206:209], v[12:15]
	v_mfma_f32_16x16x32_bf16 v[56:59], v[154:157], v[186:189], v[56:59]
	v_mfma_f32_16x16x32_bf16 v[60:63], v[162:165], v[186:189], v[60:63]
	v_mfma_f32_16x16x32_bf16 v[40:43], v[154:157], v[194:197], v[40:43]
	v_mfma_f32_16x16x32_bf16 v[44:47], v[162:165], v[194:197], v[44:47]
	v_mfma_f32_16x16x32_bf16 v[24:27], v[154:157], v[202:205], v[24:27]
	v_mfma_f32_16x16x32_bf16 v[28:31], v[162:165], v[202:205], v[28:31]
	v_mfma_f32_16x16x32_bf16 v[8:11], v[154:157], v[210:213], v[8:11]
	v_mfma_f32_16x16x32_bf16 v[12:15], v[162:165], v[210:213], v[12:15]
	s_setprio 0
	s_setprio 1
	v_mfma_f32_16x16x32_bf16 v[48:51], v[166:169], v[182:185], v[48:51]
	v_mfma_f32_16x16x32_bf16 v[52:55], v[174:177], v[182:185], v[52:55]
	v_mfma_f32_16x16x32_bf16 v[32:35], v[166:169], v[190:193], v[32:35]
	v_mfma_f32_16x16x32_bf16 v[36:39], v[174:177], v[190:193], v[36:39]
	v_mfma_f32_16x16x32_bf16 v[16:19], v[166:169], v[198:201], v[16:19]
	v_mfma_f32_16x16x32_bf16 v[20:23], v[174:177], v[198:201], v[20:23]
	v_mfma_f32_16x16x32_bf16 v[0:3], v[166:169], v[206:209], v[0:3]
	v_mfma_f32_16x16x32_bf16 v[4:7], v[174:177], v[206:209], v[4:7]
	v_mfma_f32_16x16x32_bf16 v[48:51], v[170:173], v[186:189], v[48:51]
	v_mfma_f32_16x16x32_bf16 v[52:55], v[178:181], v[186:189], v[52:55]
	v_mfma_f32_16x16x32_bf16 v[32:35], v[170:173], v[194:197], v[32:35]
	v_mfma_f32_16x16x32_bf16 v[36:39], v[178:181], v[194:197], v[36:39]
	v_mfma_f32_16x16x32_bf16 v[16:19], v[170:173], v[202:205], v[16:19]
	v_mfma_f32_16x16x32_bf16 v[20:23], v[178:181], v[202:205], v[20:23]
	v_mfma_f32_16x16x32_bf16 v[0:3], v[170:173], v[210:213], v[0:3]
	v_mfma_f32_16x16x32_bf16 v[4:7], v[178:181], v[210:213], v[4:7]
	s_barrier
	s_setprio 0
	s_cbranch_scc0 .LBB0_1566
	s_and_b64 vcc, exec, s[10:11]
	s_cbranch_vccz .LBB0_1569
	s_barrier
